# rope table staged in LDS for in-proj epilogue (no per-element vmcnt stalls); EpiResidT epilogues: hoisted src/gamma/beta loads, single drain per half
# speedup vs baseline: 1.0335x; 1.0144x over previous
.LBB0_199:
	s_andn2_saveexec_b64 s[42:43], s[2:3]
	s_cbranch_execz .LBB0_265
	v_lshrrev_b32_e32 v122, 6, v216
	v_add_u32_e32 v123, 1, v122
	v_lshrrev_b32_e32 v123, 2, v123
	v_mul_u32_u24_e32 v122, 0x1800, v122
	v_lshl_add_u32 v122, v123, 7, v122
	v_add_u32_e32 v122, 0xd800, v122
	v_and_b32_e32 v123, 63, v216
	v_lshlrev_b32_e32 v123, 4, v123
	v_mul_u32_u24_e32 v124, 0x60, v64
	v_add_u32_e32 v125, v124, v123
	v_add_u32_e32 v126, 0x1000, v125
	v_sub_u32_e32 v127, v122, v124
	v_add_u32_e32 v122, v122, v123
	global_load_dwordx4 v[146:149], v125, s[14:15]
	global_load_dwordx4 v[150:153], v125, s[14:15] offset:1024
	global_load_dwordx4 v[154:157], v125, s[14:15] offset:2048
	global_load_dwordx4 v[158:161], v125, s[14:15] offset:3072
	global_load_dwordx4 v[162:165], v126, s[14:15]
	global_load_dwordx4 v[166:169], v126, s[14:15] offset:1024
	s_waitcnt vmcnt(5)
	ds_write_b128 v122, v[146:149]
	s_waitcnt vmcnt(4)
	ds_write_b128 v122, v[150:153] offset:1024
	s_waitcnt vmcnt(3)
	ds_write_b128 v122, v[154:157] offset:2048
	s_waitcnt vmcnt(2)
	ds_write_b128 v122, v[158:161] offset:3072
	s_waitcnt vmcnt(1)
	ds_write_b128 v122, v[162:165] offset:4096
	s_waitcnt vmcnt(0)
	ds_write_b128 v122, v[166:169] offset:5120
	s_waitcnt lgkmcnt(0)
	v_and_b32_e32 v66, 64, v224
	s_waitcnt vmcnt(6)
	v_lshl_or_b32 v97, v71, 2, v64
	v_xor_b32_e32 v64, 8, v224
	v_add_u32_e32 v66, 64, v66
	v_cmp_lt_i32_e32 vcc, v64, v66
	v_cmp_gt_u32_e64 s[6:7], 16, v129
	v_or_b32_e32 v98, 8, v142
	v_cndmask_b32_e32 v64, v224, v64, vcc
	v_lshlrev_b32_e32 v99, 2, v64
	ds_bpermute_b32 v64, v99, v48
	v_or_b32_e32 v96, 16, v142
	v_cmp_gt_u32_e32 vcc, 8, v129
	v_mov_b32_e32 v66, v48
	s_and_saveexec_b64 s[2:3], s[6:7]
	s_cbranch_execz .LBB0_202
	v_mul_lo_u32 v68, v97, 24
	v_or_b32_e32 v66, v68, v98
	v_ashrrev_i32_e32 v67, 31, v66
	v_lshl_add_u32 v66, v66, 2, v127
	ds_read_b32 v69, v66
	v_or_b32_e32 v66, v68, v96
	v_ashrrev_i32_e32 v67, 31, v66
	v_lshl_add_u32 v66, v66, 2, v127
	ds_read_b32 v66, v66
	s_waitcnt lgkmcnt(0)
	v_mul_f32_e32 v64, v66, v64
	v_cndmask_b32_e64 v66, v64, -v64, vcc
	v_fmac_f32_e32 v66, v48, v69
.LBB0_202:
	s_or_b64 exec, exec, s[2:3]
	v_cmp_gt_u32_e64 s[8:9], 18, v65
	s_waitcnt lgkmcnt(0)
	v_mov_b32_e32 v64, 0x2400000
	v_mov_b32_e32 v67, 0x1800000
	v_cndmask_b32_e64 v178, v64, v67, s[8:9]
	v_not_b32_e32 v64, 17
	v_cndmask_b32_e64 v64, v64, -12, s[8:9]
	v_lshl_add_u64 v[68:69], s[10:11], 0, v[178:179]
	v_add_lshl_u32 v178, v64, v65, 7
	v_lshl_add_u64 v[64:65], v[68:69], 0, v[178:179]
	ds_bpermute_b32 v69, v99, v49
	v_lshlrev_b32_e32 v178, 1, v129
	v_lshl_add_u64 v[64:65], v[64:65], 0, v[178:179]
	v_cvt_pk_bf16_f32 v68, v66, s0
	v_mad_i64_i32 v[66:67], s[2:3], v97, s69, v[64:65]
	global_store_short v[66:67], v68, off
	v_or_b32_e32 v68, 1, v97
	v_mov_b32_e32 v70, v49
	s_and_saveexec_b64 s[2:3], s[6:7]
	s_cbranch_execz .LBB0_204
	v_mul_lo_u32 v72, v68, 24
	v_add_u32_e32 v70, v72, v98
	v_ashrrev_i32_e32 v71, 31, v70
	v_lshl_add_u32 v70, v70, 2, v127
	ds_read_b32 v73, v70
	v_add_u32_e32 v70, v72, v96
	v_ashrrev_i32_e32 v71, 31, v70
	v_lshl_add_u32 v70, v70, 2, v127
	ds_read_b32 v70, v70
	s_waitcnt lgkmcnt(0)
	v_mul_f32_e32 v69, v70, v69
	v_cndmask_b32_e64 v70, v69, -v69, vcc
	v_fmac_f32_e32 v70, v49, v73
.LBB0_204:
	s_or_b64 exec, exec, s[2:3]
	ds_bpermute_b32 v71, v99, v50
	v_cvt_pk_bf16_f32 v70, v70, s0
	s_waitcnt lgkmcnt(1)
	v_mad_i64_i32 v[68:69], s[2:3], v68, s69, v[64:65]
	global_store_short v[68:69], v70, off
	v_or_b32_e32 v70, 2, v97
	v_mov_b32_e32 v72, v50
	s_and_saveexec_b64 s[2:3], s[6:7]
	s_cbranch_execz .LBB0_206
	v_mul_lo_u32 v74, v70, 24
	v_or_b32_e32 v72, v74, v98
	v_ashrrev_i32_e32 v73, 31, v72
	v_lshl_add_u32 v72, v72, 2, v127
	ds_read_b32 v75, v72
	v_add_u32_e32 v72, v74, v96
	v_ashrrev_i32_e32 v73, 31, v72
	v_lshl_add_u32 v72, v72, 2, v127
	ds_read_b32 v72, v72
	s_waitcnt lgkmcnt(0)
	v_mul_f32_e32 v71, v72, v71
	v_cndmask_b32_e64 v72, v71, -v71, vcc
	v_fmac_f32_e32 v72, v50, v75
.LBB0_206:
	s_or_b64 exec, exec, s[2:3]
	ds_bpermute_b32 v73, v99, v51
	v_cvt_pk_bf16_f32 v72, v72, s0
	s_waitcnt lgkmcnt(1)
	v_mad_i64_i32 v[70:71], s[2:3], v70, s69, v[64:65]
	global_store_short v[70:71], v72, off
	v_or_b32_e32 v72, 3, v97
	v_mov_b32_e32 v74, v51
	s_and_saveexec_b64 s[2:3], s[6:7]
	s_cbranch_execz .LBB0_208
	v_mul_lo_u32 v76, v72, 24
	v_add_u32_e32 v74, v76, v98
	v_ashrrev_i32_e32 v75, 31, v74
	v_lshl_add_u32 v74, v74, 2, v127
	ds_read_b32 v77, v74
	v_or_b32_e32 v74, v76, v96
	v_ashrrev_i32_e32 v75, 31, v74
	v_lshl_add_u32 v74, v74, 2, v127
	ds_read_b32 v74, v74
	s_waitcnt lgkmcnt(0)
	v_mul_f32_e32 v73, v74, v73
	v_cndmask_b32_e64 v74, v73, -v73, vcc
	v_fmac_f32_e32 v74, v51, v77
.LBB0_208:
	s_or_b64 exec, exec, s[2:3]
	ds_bpermute_b32 v75, v99, v52
	v_cvt_pk_bf16_f32 v74, v74, s0
	s_waitcnt lgkmcnt(1)
	v_mad_i64_i32 v[72:73], s[2:3], v72, s69, v[64:65]
	global_store_short v[72:73], v74, off
	v_or_b32_e32 v74, 8, v97
	v_mov_b32_e32 v76, v52
	s_and_saveexec_b64 s[2:3], s[6:7]
	s_cbranch_execz .LBB0_210
	v_mul_lo_u32 v78, v74, 24
	v_or_b32_e32 v76, v78, v98
	v_ashrrev_i32_e32 v77, 31, v76
	v_lshl_add_u32 v76, v76, 2, v127
	ds_read_b32 v79, v76
	v_or_b32_e32 v76, v78, v96
	v_ashrrev_i32_e32 v77, 31, v76
	v_lshl_add_u32 v76, v76, 2, v127
	ds_read_b32 v76, v76
	s_waitcnt lgkmcnt(0)
	v_mul_f32_e32 v75, v76, v75
	v_cndmask_b32_e64 v76, v75, -v75, vcc
	v_fmac_f32_e32 v76, v52, v79
.LBB0_210:
	s_or_b64 exec, exec, s[2:3]
	ds_bpermute_b32 v77, v99, v53
	v_cvt_pk_bf16_f32 v76, v76, s0
	s_waitcnt lgkmcnt(1)
	v_mad_i64_i32 v[74:75], s[2:3], v74, s69, v[64:65]
	global_store_short v[74:75], v76, off
	v_or_b32_e32 v76, 9, v97
	v_mov_b32_e32 v78, v53
	s_and_saveexec_b64 s[2:3], s[6:7]
	s_cbranch_execz .LBB0_212
	v_mul_lo_u32 v80, v76, 24
	v_add_u32_e32 v78, v80, v98
	v_ashrrev_i32_e32 v79, 31, v78
	v_lshl_add_u32 v78, v78, 2, v127
	ds_read_b32 v81, v78
	v_add_u32_e32 v78, v80, v96
	v_ashrrev_i32_e32 v79, 31, v78
	v_lshl_add_u32 v78, v78, 2, v127
	ds_read_b32 v78, v78
	s_waitcnt lgkmcnt(0)
	v_mul_f32_e32 v77, v78, v77
	v_cndmask_b32_e64 v78, v77, -v77, vcc
	v_fmac_f32_e32 v78, v53, v81
.LBB0_212:
	s_or_b64 exec, exec, s[2:3]
	ds_bpermute_b32 v79, v99, v54
	v_cvt_pk_bf16_f32 v78, v78, s0
	s_waitcnt lgkmcnt(1)
	v_mad_i64_i32 v[76:77], s[2:3], v76, s69, v[64:65]
	global_store_short v[76:77], v78, off
	v_or_b32_e32 v78, 10, v97
	v_mov_b32_e32 v80, v54
	s_and_saveexec_b64 s[2:3], s[6:7]
	s_cbranch_execz .LBB0_214
	v_mul_lo_u32 v82, v78, 24
	v_or_b32_e32 v80, v82, v98
	v_ashrrev_i32_e32 v81, 31, v80
	v_lshl_add_u32 v80, v80, 2, v127
	ds_read_b32 v83, v80
	v_add_u32_e32 v80, v82, v96
	v_ashrrev_i32_e32 v81, 31, v80
	v_lshl_add_u32 v80, v80, 2, v127
	ds_read_b32 v80, v80
	s_waitcnt lgkmcnt(0)
	v_mul_f32_e32 v79, v80, v79
	v_cndmask_b32_e64 v80, v79, -v79, vcc
	v_fmac_f32_e32 v80, v54, v83
.LBB0_214:
	s_or_b64 exec, exec, s[2:3]
	ds_bpermute_b32 v81, v99, v55
	v_cvt_pk_bf16_f32 v80, v80, s0
	s_waitcnt lgkmcnt(1)
	v_mad_i64_i32 v[78:79], s[2:3], v78, s69, v[64:65]
	global_store_short v[78:79], v80, off
	v_or_b32_e32 v80, 11, v97
	v_mov_b32_e32 v82, v55
	s_and_saveexec_b64 s[2:3], s[6:7]
	s_cbranch_execz .LBB0_216
	v_mul_lo_u32 v84, v80, 24
	v_add_u32_e32 v82, v84, v98
	v_ashrrev_i32_e32 v83, 31, v82
	v_lshl_add_u32 v82, v82, 2, v127
	ds_read_b32 v85, v82
	v_or_b32_e32 v82, v84, v96
	v_ashrrev_i32_e32 v83, 31, v82
	v_lshl_add_u32 v82, v82, 2, v127
	ds_read_b32 v82, v82
	s_waitcnt lgkmcnt(0)
	v_mul_f32_e32 v81, v82, v81
	v_cndmask_b32_e64 v82, v81, -v81, vcc
	v_fmac_f32_e32 v82, v55, v85
.LBB0_216:
	s_or_b64 exec, exec, s[2:3]
	ds_bpermute_b32 v83, v99, v56
	v_cvt_pk_bf16_f32 v82, v82, s0
	s_waitcnt lgkmcnt(1)
	v_mad_i64_i32 v[80:81], s[2:3], v80, s69, v[64:65]
	global_store_short v[80:81], v82, off
	v_or_b32_e32 v82, 16, v97
	v_mov_b32_e32 v84, v56
	s_and_saveexec_b64 s[2:3], s[6:7]
	s_cbranch_execz .LBB0_218
	v_mul_lo_u32 v86, v82, 24
	v_or_b32_e32 v84, v86, v98
	v_ashrrev_i32_e32 v85, 31, v84
	v_lshl_add_u32 v84, v84, 2, v127
	ds_read_b32 v87, v84
	v_or_b32_e32 v84, v86, v96
	v_ashrrev_i32_e32 v85, 31, v84
	v_lshl_add_u32 v84, v84, 2, v127
	ds_read_b32 v84, v84
	s_waitcnt lgkmcnt(0)
	v_mul_f32_e32 v83, v84, v83
	v_cndmask_b32_e64 v84, v83, -v83, vcc
	v_fmac_f32_e32 v84, v56, v87
.LBB0_218:
	s_or_b64 exec, exec, s[2:3]
	ds_bpermute_b32 v85, v99, v57
	v_cvt_pk_bf16_f32 v84, v84, s0
	s_waitcnt lgkmcnt(1)
	v_mad_i64_i32 v[82:83], s[2:3], v82, s69, v[64:65]
	global_store_short v[82:83], v84, off
	v_or_b32_e32 v84, 17, v97
	v_mov_b32_e32 v86, v57
	s_and_saveexec_b64 s[2:3], s[6:7]
	s_cbranch_execz .LBB0_220
	v_mul_lo_u32 v88, v84, 24
	v_add_u32_e32 v86, v88, v98
	v_ashrrev_i32_e32 v87, 31, v86
	v_lshl_add_u32 v86, v86, 2, v127
	ds_read_b32 v89, v86
	v_add_u32_e32 v86, v88, v96
	v_ashrrev_i32_e32 v87, 31, v86
	v_lshl_add_u32 v86, v86, 2, v127
	ds_read_b32 v86, v86
	s_waitcnt lgkmcnt(0)
	v_mul_f32_e32 v85, v86, v85
	v_cndmask_b32_e64 v86, v85, -v85, vcc
	v_fmac_f32_e32 v86, v57, v89
.LBB0_220:
	s_or_b64 exec, exec, s[2:3]
	ds_bpermute_b32 v87, v99, v58
	v_cvt_pk_bf16_f32 v86, v86, s0
	s_waitcnt lgkmcnt(1)
	v_mad_i64_i32 v[84:85], s[2:3], v84, s69, v[64:65]
	global_store_short v[84:85], v86, off
	v_or_b32_e32 v86, 18, v97
	v_mov_b32_e32 v88, v58
	s_and_saveexec_b64 s[2:3], s[6:7]
	s_cbranch_execz .LBB0_222
	v_mul_lo_u32 v90, v86, 24
	v_or_b32_e32 v88, v90, v98
	v_ashrrev_i32_e32 v89, 31, v88
	v_lshl_add_u32 v88, v88, 2, v127
	ds_read_b32 v91, v88
	v_add_u32_e32 v88, v90, v96
	v_ashrrev_i32_e32 v89, 31, v88
	v_lshl_add_u32 v88, v88, 2, v127
	ds_read_b32 v88, v88
	s_waitcnt lgkmcnt(0)
	v_mul_f32_e32 v87, v88, v87
	v_cndmask_b32_e64 v88, v87, -v87, vcc
	v_fmac_f32_e32 v88, v58, v91
.LBB0_222:
	s_or_b64 exec, exec, s[2:3]
	ds_bpermute_b32 v89, v99, v59
	v_cvt_pk_bf16_f32 v88, v88, s0
	s_waitcnt lgkmcnt(1)
	v_mad_i64_i32 v[86:87], s[2:3], v86, s69, v[64:65]
	global_store_short v[86:87], v88, off
	v_or_b32_e32 v88, 19, v97
	v_mov_b32_e32 v90, v59
	s_and_saveexec_b64 s[2:3], s[6:7]
	s_cbranch_execz .LBB0_224
	v_mul_lo_u32 v92, v88, 24
	v_add_u32_e32 v90, v92, v98
	v_ashrrev_i32_e32 v91, 31, v90
	v_lshl_add_u32 v90, v90, 2, v127
	ds_read_b32 v93, v90
	v_or_b32_e32 v90, v92, v96
	v_ashrrev_i32_e32 v91, 31, v90
	v_lshl_add_u32 v90, v90, 2, v127
	ds_read_b32 v90, v90
	s_waitcnt lgkmcnt(0)
	v_mul_f32_e32 v89, v90, v89
	v_cndmask_b32_e64 v90, v89, -v89, vcc
	v_fmac_f32_e32 v90, v59, v93
.LBB0_224:
	s_or_b64 exec, exec, s[2:3]
	ds_bpermute_b32 v91, v99, v60
	v_cvt_pk_bf16_f32 v90, v90, s0
	s_waitcnt lgkmcnt(1)
	v_mad_i64_i32 v[88:89], s[2:3], v88, s69, v[64:65]
	global_store_short v[88:89], v90, off
	v_or_b32_e32 v90, 24, v97
	v_mov_b32_e32 v92, v60
	s_and_saveexec_b64 s[2:3], s[6:7]
	s_cbranch_execz .LBB0_226
	v_mul_lo_u32 v94, v90, 24
	v_or_b32_e32 v92, v94, v98
	v_ashrrev_i32_e32 v93, 31, v92
	v_lshl_add_u32 v92, v92, 2, v127
	ds_read_b32 v95, v92
	v_or_b32_e32 v92, v94, v96
	v_ashrrev_i32_e32 v93, 31, v92
	v_lshl_add_u32 v92, v92, 2, v127
	ds_read_b32 v92, v92
	s_waitcnt lgkmcnt(0)
	v_mul_f32_e32 v91, v92, v91
	v_cndmask_b32_e64 v92, v91, -v91, vcc
	v_fmac_f32_e32 v92, v60, v95
.LBB0_226:
	s_or_b64 exec, exec, s[2:3]
	ds_bpermute_b32 v93, v99, v61
	v_cvt_pk_bf16_f32 v92, v92, s0
	s_waitcnt lgkmcnt(1)
	v_mad_i64_i32 v[90:91], s[2:3], v90, s69, v[64:65]
	global_store_short v[90:91], v92, off
	v_or_b32_e32 v92, 25, v97
	v_mov_b32_e32 v94, v61
	s_and_saveexec_b64 s[2:3], s[6:7]
	s_cbranch_execz .LBB0_228
	v_mul_lo_u32 v100, v92, 24
	v_add_u32_e32 v94, v100, v98
	v_ashrrev_i32_e32 v95, 31, v94
	v_lshl_add_u32 v94, v94, 2, v127
	ds_read_b32 v101, v94
	v_add_u32_e32 v94, v100, v96
	v_ashrrev_i32_e32 v95, 31, v94
	v_lshl_add_u32 v94, v94, 2, v127
	ds_read_b32 v94, v94
	s_waitcnt lgkmcnt(0)
	v_mul_f32_e32 v93, v94, v93
	v_cndmask_b32_e64 v94, v93, -v93, vcc
	v_fmac_f32_e32 v94, v61, v101
.LBB0_228:
	s_or_b64 exec, exec, s[2:3]
	ds_bpermute_b32 v95, v99, v62
	v_cvt_pk_bf16_f32 v94, v94, s0
	s_waitcnt lgkmcnt(1)
	v_mad_i64_i32 v[92:93], s[2:3], v92, s69, v[64:65]
	global_store_short v[92:93], v94, off
	v_or_b32_e32 v94, 26, v97
	v_mov_b32_e32 v100, v62
	s_and_saveexec_b64 s[2:3], s[6:7]
	s_cbranch_execz .LBB0_230
	v_mul_lo_u32 v102, v94, 24
	v_or_b32_e32 v100, v102, v98
	v_ashrrev_i32_e32 v101, 31, v100
	v_lshl_add_u32 v100, v100, 2, v127
	ds_read_b32 v103, v100
	v_add_u32_e32 v100, v102, v96
	v_ashrrev_i32_e32 v101, 31, v100
	v_lshl_add_u32 v100, v100, 2, v127
	ds_read_b32 v100, v100
	s_waitcnt lgkmcnt(0)
	v_mul_f32_e32 v95, v100, v95
	v_cndmask_b32_e64 v100, v95, -v95, vcc
	v_fmac_f32_e32 v100, v62, v103
.LBB0_230:
	s_or_b64 exec, exec, s[2:3]
	ds_bpermute_b32 v101, v99, v63
	v_cvt_pk_bf16_f32 v100, v100, s0
	s_waitcnt lgkmcnt(1)
	v_mad_i64_i32 v[94:95], s[2:3], v94, s69, v[64:65]
	global_store_short v[94:95], v100, off
	v_or_b32_e32 v100, 27, v97
	v_mov_b32_e32 v102, v63
	s_and_saveexec_b64 s[2:3], s[6:7]
	s_cbranch_execz .LBB0_232
	s_waitcnt vmcnt(20)
	v_mul_lo_u32 v104, v100, 24
	v_add_u32_e32 v102, v104, v98
	v_ashrrev_i32_e32 v103, 31, v102
	v_lshl_add_u32 v102, v102, 2, v127
	ds_read_b32 v105, v102
	v_or_b32_e32 v102, v104, v96
	v_ashrrev_i32_e32 v103, 31, v102
	v_lshl_add_u32 v102, v102, 2, v127
	ds_read_b32 v102, v102
	s_waitcnt lgkmcnt(0)
	v_mul_f32_e32 v101, v102, v101
	v_cndmask_b32_e64 v102, v101, -v101, vcc
	v_fmac_f32_e32 v102, v63, v105
.LBB0_232:
	s_or_b64 exec, exec, s[2:3]
	v_cvt_pk_bf16_f32 v102, v102, s0
	s_waitcnt lgkmcnt(0)
	v_mad_i64_i32 v[100:101], s[2:3], v100, s69, v[64:65]
	global_store_short v[100:101], v102, off
	v_cvt_pk_bf16_f32 v102, v32, s0
	global_store_short v[66:67], v102, off offset:64
	v_cvt_pk_bf16_f32 v66, v33, s0
	global_store_short v[68:69], v66, off offset:64
	v_cvt_pk_bf16_f32 v66, v34, s0
	global_store_short v[70:71], v66, off offset:64
	v_cvt_pk_bf16_f32 v66, v35, s0
	global_store_short v[72:73], v66, off offset:64
	v_cvt_pk_bf16_f32 v66, v36, s0
	global_store_short v[74:75], v66, off offset:64
	v_cvt_pk_bf16_f32 v66, v37, s0
	global_store_short v[76:77], v66, off offset:64
	v_cvt_pk_bf16_f32 v66, v38, s0
	global_store_short v[78:79], v66, off offset:64
	v_cvt_pk_bf16_f32 v66, v39, s0
	global_store_short v[80:81], v66, off offset:64
	v_cvt_pk_bf16_f32 v66, v40, s0
	global_store_short v[82:83], v66, off offset:64
	v_cvt_pk_bf16_f32 v66, v41, s0
	global_store_short v[84:85], v66, off offset:64
	v_cvt_pk_bf16_f32 v66, v42, s0
	global_store_short v[86:87], v66, off offset:64
	v_cvt_pk_bf16_f32 v66, v43, s0
	global_store_short v[88:89], v66, off offset:64
	v_cvt_pk_bf16_f32 v66, v44, s0
	ds_bpermute_b32 v67, v99, v16
	global_store_short v[90:91], v66, off offset:64
	v_cvt_pk_bf16_f32 v66, v45, s0
	global_store_short v[92:93], v66, off offset:64
	v_cvt_pk_bf16_f32 v66, v46, s0
	global_store_short v[94:95], v66, off offset:64
	v_cvt_pk_bf16_f32 v66, v47, s0
	global_store_short v[100:101], v66, off offset:64
	v_or_b32_e32 v66, 32, v97
	v_mov_b32_e32 v68, v16
	s_and_saveexec_b64 s[2:3], s[6:7]
	s_cbranch_execz .LBB0_234
	v_mul_lo_u32 v70, v66, 24
	v_or_b32_e32 v68, v70, v98
	v_ashrrev_i32_e32 v69, 31, v68
	v_lshl_add_u32 v68, v68, 2, v127
	ds_read_b32 v71, v68
	v_or_b32_e32 v68, v70, v96
	v_ashrrev_i32_e32 v69, 31, v68
	v_lshl_add_u32 v68, v68, 2, v127
	ds_read_b32 v68, v68
	s_waitcnt lgkmcnt(0)
	v_mul_f32_e32 v67, v68, v67
	v_cndmask_b32_e64 v68, v67, -v67, vcc
	v_fmac_f32_e32 v68, v16, v71
.LBB0_234:
	s_or_b64 exec, exec, s[2:3]
	ds_bpermute_b32 v69, v99, v17
	v_cvt_pk_bf16_f32 v68, v68, s0
	s_waitcnt lgkmcnt(1)
	v_mad_i64_i32 v[66:67], s[2:3], v66, s69, v[64:65]
	global_store_short v[66:67], v68, off
	v_or_b32_e32 v68, 33, v97
	v_mov_b32_e32 v70, v17
	s_and_saveexec_b64 s[2:3], s[6:7]
	s_cbranch_execz .LBB0_236
	v_mul_lo_u32 v72, v68, 24
	v_add_u32_e32 v70, v72, v98
	v_ashrrev_i32_e32 v71, 31, v70
	v_lshl_add_u32 v70, v70, 2, v127
	ds_read_b32 v73, v70
	v_add_u32_e32 v70, v72, v96
	v_ashrrev_i32_e32 v71, 31, v70
	v_lshl_add_u32 v70, v70, 2, v127
	ds_read_b32 v70, v70
	s_waitcnt lgkmcnt(0)
	v_mul_f32_e32 v69, v70, v69
	v_cndmask_b32_e64 v70, v69, -v69, vcc
	v_fmac_f32_e32 v70, v17, v73
.LBB0_236:
	s_or_b64 exec, exec, s[2:3]
	ds_bpermute_b32 v71, v99, v18
	v_cvt_pk_bf16_f32 v70, v70, s0
	s_waitcnt lgkmcnt(1)
	v_mad_i64_i32 v[68:69], s[2:3], v68, s69, v[64:65]
	global_store_short v[68:69], v70, off
	v_or_b32_e32 v70, 34, v97
	v_mov_b32_e32 v72, v18
	s_and_saveexec_b64 s[2:3], s[6:7]
	s_cbranch_execz .LBB0_238
	v_mul_lo_u32 v74, v70, 24
	v_or_b32_e32 v72, v74, v98
	v_ashrrev_i32_e32 v73, 31, v72
	v_lshl_add_u32 v72, v72, 2, v127
	ds_read_b32 v75, v72
	v_add_u32_e32 v72, v74, v96
	v_ashrrev_i32_e32 v73, 31, v72
	v_lshl_add_u32 v72, v72, 2, v127
	ds_read_b32 v72, v72
	s_waitcnt lgkmcnt(0)
	v_mul_f32_e32 v71, v72, v71
	v_cndmask_b32_e64 v72, v71, -v71, vcc
	v_fmac_f32_e32 v72, v18, v75
.LBB0_238:
	s_or_b64 exec, exec, s[2:3]
	ds_bpermute_b32 v73, v99, v19
	v_cvt_pk_bf16_f32 v72, v72, s0
	s_waitcnt lgkmcnt(1)
	v_mad_i64_i32 v[70:71], s[2:3], v70, s69, v[64:65]
	global_store_short v[70:71], v72, off
	v_or_b32_e32 v72, 35, v97
	v_mov_b32_e32 v74, v19
	s_and_saveexec_b64 s[2:3], s[6:7]
	s_cbranch_execz .LBB0_240
	v_mul_lo_u32 v76, v72, 24
	v_add_u32_e32 v74, v76, v98
	v_ashrrev_i32_e32 v75, 31, v74
	v_lshl_add_u32 v74, v74, 2, v127
	ds_read_b32 v77, v74
	v_or_b32_e32 v74, v76, v96
	v_ashrrev_i32_e32 v75, 31, v74
	v_lshl_add_u32 v74, v74, 2, v127
	ds_read_b32 v74, v74
	s_waitcnt lgkmcnt(0)
	v_mul_f32_e32 v73, v74, v73
	v_cndmask_b32_e64 v74, v73, -v73, vcc
	v_fmac_f32_e32 v74, v19, v77
.LBB0_240:
	s_or_b64 exec, exec, s[2:3]
	ds_bpermute_b32 v75, v99, v20
	v_cvt_pk_bf16_f32 v74, v74, s0
	s_waitcnt lgkmcnt(1)
	v_mad_i64_i32 v[72:73], s[2:3], v72, s69, v[64:65]
	global_store_short v[72:73], v74, off
	v_or_b32_e32 v74, 40, v97
	v_mov_b32_e32 v76, v20
	s_and_saveexec_b64 s[2:3], s[6:7]
	s_cbranch_execz .LBB0_242
	v_mul_lo_u32 v78, v74, 24
	v_or_b32_e32 v76, v78, v98
	v_ashrrev_i32_e32 v77, 31, v76
	v_lshl_add_u32 v76, v76, 2, v127
	ds_read_b32 v79, v76
	v_or_b32_e32 v76, v78, v96
	v_ashrrev_i32_e32 v77, 31, v76
	v_lshl_add_u32 v76, v76, 2, v127
	ds_read_b32 v76, v76
	s_waitcnt lgkmcnt(0)
	v_mul_f32_e32 v75, v76, v75
	v_cndmask_b32_e64 v76, v75, -v75, vcc
	v_fmac_f32_e32 v76, v20, v79
.LBB0_242:
	s_or_b64 exec, exec, s[2:3]
	ds_bpermute_b32 v77, v99, v21
	v_cvt_pk_bf16_f32 v76, v76, s0
	s_waitcnt lgkmcnt(1)
	v_mad_i64_i32 v[74:75], s[2:3], v74, s69, v[64:65]
	global_store_short v[74:75], v76, off
	v_or_b32_e32 v76, 41, v97
	v_mov_b32_e32 v78, v21
	s_and_saveexec_b64 s[2:3], s[6:7]
	s_cbranch_execz .LBB0_244
	v_mul_lo_u32 v80, v76, 24
	v_add_u32_e32 v78, v80, v98
	v_ashrrev_i32_e32 v79, 31, v78
	v_lshl_add_u32 v78, v78, 2, v127
	ds_read_b32 v81, v78
	v_add_u32_e32 v78, v80, v96
	v_ashrrev_i32_e32 v79, 31, v78
	v_lshl_add_u32 v78, v78, 2, v127
	ds_read_b32 v78, v78
	s_waitcnt lgkmcnt(0)
	v_mul_f32_e32 v77, v78, v77
	v_cndmask_b32_e64 v78, v77, -v77, vcc
	v_fmac_f32_e32 v78, v21, v81
.LBB0_244:
	s_or_b64 exec, exec, s[2:3]
	ds_bpermute_b32 v79, v99, v22
	v_cvt_pk_bf16_f32 v78, v78, s0
	s_waitcnt lgkmcnt(1)
	v_mad_i64_i32 v[76:77], s[2:3], v76, s69, v[64:65]
	global_store_short v[76:77], v78, off
	v_or_b32_e32 v78, 42, v97
	v_mov_b32_e32 v80, v22
	s_and_saveexec_b64 s[2:3], s[6:7]
	s_cbranch_execz .LBB0_246
	v_mul_lo_u32 v82, v78, 24
	v_or_b32_e32 v80, v82, v98
	v_ashrrev_i32_e32 v81, 31, v80
	v_lshl_add_u32 v80, v80, 2, v127
	ds_read_b32 v83, v80
	v_add_u32_e32 v80, v82, v96
	v_ashrrev_i32_e32 v81, 31, v80
	v_lshl_add_u32 v80, v80, 2, v127
	ds_read_b32 v80, v80
	s_waitcnt lgkmcnt(0)
	v_mul_f32_e32 v79, v80, v79
	v_cndmask_b32_e64 v80, v79, -v79, vcc
	v_fmac_f32_e32 v80, v22, v83
.LBB0_246:
	s_or_b64 exec, exec, s[2:3]
	ds_bpermute_b32 v81, v99, v23
	v_cvt_pk_bf16_f32 v80, v80, s0
	s_waitcnt lgkmcnt(1)
	v_mad_i64_i32 v[78:79], s[2:3], v78, s69, v[64:65]
	global_store_short v[78:79], v80, off
	v_or_b32_e32 v80, 43, v97
	v_mov_b32_e32 v82, v23
	s_and_saveexec_b64 s[2:3], s[6:7]
	s_cbranch_execz .LBB0_248
	v_mul_lo_u32 v84, v80, 24
	v_add_u32_e32 v82, v84, v98
	v_ashrrev_i32_e32 v83, 31, v82
	v_lshl_add_u32 v82, v82, 2, v127
	ds_read_b32 v85, v82
	v_or_b32_e32 v82, v84, v96
	v_ashrrev_i32_e32 v83, 31, v82
	v_lshl_add_u32 v82, v82, 2, v127
	ds_read_b32 v82, v82
	s_waitcnt lgkmcnt(0)
	v_mul_f32_e32 v81, v82, v81
	v_cndmask_b32_e64 v82, v81, -v81, vcc
	v_fmac_f32_e32 v82, v23, v85
.LBB0_248:
	s_or_b64 exec, exec, s[2:3]
	ds_bpermute_b32 v83, v99, v24
	v_cvt_pk_bf16_f32 v82, v82, s0
	s_waitcnt lgkmcnt(1)
	v_mad_i64_i32 v[80:81], s[2:3], v80, s69, v[64:65]
	global_store_short v[80:81], v82, off
	v_or_b32_e32 v82, 48, v97
	v_mov_b32_e32 v84, v24
	s_and_saveexec_b64 s[2:3], s[6:7]
	s_cbranch_execz .LBB0_250
	v_mul_lo_u32 v86, v82, 24
	v_or_b32_e32 v84, v86, v98
	v_ashrrev_i32_e32 v85, 31, v84
	v_lshl_add_u32 v84, v84, 2, v127
	ds_read_b32 v87, v84
	v_or_b32_e32 v84, v86, v96
	v_ashrrev_i32_e32 v85, 31, v84
	v_lshl_add_u32 v84, v84, 2, v127
	ds_read_b32 v84, v84
	s_waitcnt lgkmcnt(0)
	v_mul_f32_e32 v83, v84, v83
	v_cndmask_b32_e64 v84, v83, -v83, vcc
	v_fmac_f32_e32 v84, v24, v87
.LBB0_250:
	s_or_b64 exec, exec, s[2:3]
	ds_bpermute_b32 v85, v99, v25
	v_cvt_pk_bf16_f32 v84, v84, s0
	s_waitcnt lgkmcnt(1)
	v_mad_i64_i32 v[82:83], s[2:3], v82, s69, v[64:65]
	global_store_short v[82:83], v84, off
	v_or_b32_e32 v84, 49, v97
	v_mov_b32_e32 v86, v25
	s_and_saveexec_b64 s[2:3], s[6:7]
	s_cbranch_execz .LBB0_252
	v_mul_lo_u32 v88, v84, 24
	v_add_u32_e32 v86, v88, v98
	v_ashrrev_i32_e32 v87, 31, v86
	v_lshl_add_u32 v86, v86, 2, v127
	ds_read_b32 v89, v86
	v_add_u32_e32 v86, v88, v96
	v_ashrrev_i32_e32 v87, 31, v86
	v_lshl_add_u32 v86, v86, 2, v127
	ds_read_b32 v86, v86
	s_waitcnt lgkmcnt(0)
	v_mul_f32_e32 v85, v86, v85
	v_cndmask_b32_e64 v86, v85, -v85, vcc
	v_fmac_f32_e32 v86, v25, v89
.LBB0_252:
	s_or_b64 exec, exec, s[2:3]
	ds_bpermute_b32 v87, v99, v26
	v_cvt_pk_bf16_f32 v86, v86, s0
	s_waitcnt lgkmcnt(1)
	v_mad_i64_i32 v[84:85], s[2:3], v84, s69, v[64:65]
	global_store_short v[84:85], v86, off
	v_or_b32_e32 v86, 50, v97
	v_mov_b32_e32 v88, v26
	s_and_saveexec_b64 s[2:3], s[6:7]
	s_cbranch_execz .LBB0_254
	v_mul_lo_u32 v90, v86, 24
	v_or_b32_e32 v88, v90, v98
	v_ashrrev_i32_e32 v89, 31, v88
	v_lshl_add_u32 v88, v88, 2, v127
	ds_read_b32 v91, v88
	v_add_u32_e32 v88, v90, v96
	v_ashrrev_i32_e32 v89, 31, v88
	v_lshl_add_u32 v88, v88, 2, v127
	ds_read_b32 v88, v88
	s_waitcnt lgkmcnt(0)
	v_mul_f32_e32 v87, v88, v87
	v_cndmask_b32_e64 v88, v87, -v87, vcc
	v_fmac_f32_e32 v88, v26, v91
.LBB0_254:
	s_or_b64 exec, exec, s[2:3]
	ds_bpermute_b32 v89, v99, v27
	v_cvt_pk_bf16_f32 v88, v88, s0
	s_waitcnt lgkmcnt(1)
	v_mad_i64_i32 v[86:87], s[2:3], v86, s69, v[64:65]
	global_store_short v[86:87], v88, off
	v_or_b32_e32 v88, 51, v97
	v_mov_b32_e32 v90, v27
	s_and_saveexec_b64 s[2:3], s[6:7]
	s_cbranch_execz .LBB0_256
	v_mul_lo_u32 v92, v88, 24
	v_add_u32_e32 v90, v92, v98
	v_ashrrev_i32_e32 v91, 31, v90
	v_lshl_add_u32 v90, v90, 2, v127
	ds_read_b32 v93, v90
	v_or_b32_e32 v90, v92, v96
	v_ashrrev_i32_e32 v91, 31, v90
	v_lshl_add_u32 v90, v90, 2, v127
	ds_read_b32 v90, v90
	s_waitcnt lgkmcnt(0)
	v_mul_f32_e32 v89, v90, v89
	v_cndmask_b32_e64 v90, v89, -v89, vcc
	v_fmac_f32_e32 v90, v27, v93
.LBB0_256:
	s_or_b64 exec, exec, s[2:3]
	ds_bpermute_b32 v91, v99, v28
	v_cvt_pk_bf16_f32 v90, v90, s0
	s_waitcnt lgkmcnt(1)
	v_mad_i64_i32 v[88:89], s[2:3], v88, s69, v[64:65]
	global_store_short v[88:89], v90, off
	v_or_b32_e32 v90, 56, v97
	v_mov_b32_e32 v92, v28
	s_and_saveexec_b64 s[2:3], s[6:7]
	s_cbranch_execz .LBB0_258
	v_mul_lo_u32 v94, v90, 24
	v_or_b32_e32 v92, v94, v98
	v_ashrrev_i32_e32 v93, 31, v92
	v_lshl_add_u32 v92, v92, 2, v127
	ds_read_b32 v95, v92
	v_or_b32_e32 v92, v94, v96
	v_ashrrev_i32_e32 v93, 31, v92
	v_lshl_add_u32 v92, v92, 2, v127
	ds_read_b32 v92, v92
	s_waitcnt lgkmcnt(0)
	v_mul_f32_e32 v91, v92, v91
	v_cndmask_b32_e64 v92, v91, -v91, vcc
	v_fmac_f32_e32 v92, v28, v95
.LBB0_258:
	s_or_b64 exec, exec, s[2:3]
	ds_bpermute_b32 v93, v99, v29
	v_cvt_pk_bf16_f32 v92, v92, s0
	s_waitcnt lgkmcnt(1)
	v_mad_i64_i32 v[90:91], s[2:3], v90, s69, v[64:65]
	global_store_short v[90:91], v92, off
	v_or_b32_e32 v92, 57, v97
	v_mov_b32_e32 v94, v29
	s_and_saveexec_b64 s[2:3], s[6:7]
	s_cbranch_execz .LBB0_260
	v_mul_lo_u32 v100, v92, 24
	v_add_u32_e32 v94, v100, v98
	v_ashrrev_i32_e32 v95, 31, v94
	v_lshl_add_u32 v94, v94, 2, v127
	ds_read_b32 v101, v94
	v_add_u32_e32 v94, v100, v96
	v_ashrrev_i32_e32 v95, 31, v94
	v_lshl_add_u32 v94, v94, 2, v127
	ds_read_b32 v94, v94
	s_waitcnt lgkmcnt(0)
	v_mul_f32_e32 v93, v94, v93
	v_cndmask_b32_e64 v94, v93, -v93, vcc
	v_fmac_f32_e32 v94, v29, v101
.LBB0_260:
	s_or_b64 exec, exec, s[2:3]
	ds_bpermute_b32 v95, v99, v30
	v_cvt_pk_bf16_f32 v94, v94, s0
	s_waitcnt lgkmcnt(1)
	v_mad_i64_i32 v[92:93], s[2:3], v92, s69, v[64:65]
	global_store_short v[92:93], v94, off
	v_or_b32_e32 v94, 58, v97
	v_mov_b32_e32 v100, v30
	s_and_saveexec_b64 s[2:3], s[6:7]
	s_cbranch_execz .LBB0_262
	v_mul_lo_u32 v102, v94, 24
	v_or_b32_e32 v100, v102, v98
	v_ashrrev_i32_e32 v101, 31, v100
	v_lshl_add_u32 v100, v100, 2, v127
	ds_read_b32 v103, v100
	v_add_u32_e32 v100, v102, v96
	v_ashrrev_i32_e32 v101, 31, v100
	v_lshl_add_u32 v100, v100, 2, v127
	ds_read_b32 v100, v100
	s_waitcnt lgkmcnt(0)
	v_mul_f32_e32 v95, v100, v95
	v_cndmask_b32_e64 v100, v95, -v95, vcc
	v_fmac_f32_e32 v100, v30, v103
.LBB0_262:
	s_or_b64 exec, exec, s[2:3]
	ds_bpermute_b32 v99, v99, v31
	v_cvt_pk_bf16_f32 v100, v100, s0
	s_waitcnt lgkmcnt(1)
	v_mad_i64_i32 v[94:95], s[2:3], v94, s69, v[64:65]
	global_store_short v[94:95], v100, off
	v_or_b32_e32 v97, 59, v97
	v_mov_b32_e32 v100, v31
	s_and_saveexec_b64 s[2:3], s[6:7]
	s_cbranch_execz .LBB0_264
	v_mul_lo_u32 v102, v97, 24
	v_add_u32_e32 v100, v102, v98
	v_ashrrev_i32_e32 v101, 31, v100
	v_lshl_add_u32 v100, v100, 2, v127
	ds_read_b32 v98, v100
	v_or_b32_e32 v100, v102, v96
	v_ashrrev_i32_e32 v101, 31, v100
	v_lshl_add_u32 v100, v100, 2, v127
	ds_read_b32 v96, v100
	s_waitcnt lgkmcnt(0)
	v_mul_f32_e32 v96, v96, v99
	v_cndmask_b32_e64 v100, v96, -v96, vcc
	v_fmac_f32_e32 v100, v31, v98

.LBB0_269:
	s_andn2_saveexec_b64 s[0:1], s[0:1]
	s_cbranch_execz .LBB0_399
	v_lshrrev_b32_e32 v122, 6, v216
	v_add_u32_e32 v123, 1, v122
	v_lshrrev_b32_e32 v123, 2, v123
	v_mul_u32_u24_e32 v122, 0x1800, v122
	v_lshl_add_u32 v122, v123, 7, v122
	v_add_u32_e32 v122, 0xd800, v122
	v_and_b32_e32 v123, 63, v216
	v_lshlrev_b32_e32 v123, 4, v123
	v_mul_u32_u24_e32 v124, 0x60, v64
	v_add_u32_e32 v125, v124, v123
	v_add_u32_e32 v126, 0x1000, v125
	v_sub_u32_e32 v127, v122, v124
	v_add_u32_e32 v122, v122, v123
	global_load_dwordx4 v[146:149], v125, s[14:15]
	global_load_dwordx4 v[150:153], v125, s[14:15] offset:1024
	global_load_dwordx4 v[154:157], v125, s[14:15] offset:2048
	global_load_dwordx4 v[158:161], v125, s[14:15] offset:3072
	global_load_dwordx4 v[162:165], v126, s[14:15]
	global_load_dwordx4 v[166:169], v126, s[14:15] offset:1024
	s_waitcnt vmcnt(5)
	ds_write_b128 v122, v[146:149]
	s_waitcnt vmcnt(4)
	ds_write_b128 v122, v[150:153] offset:1024
	s_waitcnt vmcnt(3)
	ds_write_b128 v122, v[154:157] offset:2048
	s_waitcnt vmcnt(2)
	ds_write_b128 v122, v[158:161] offset:3072
	s_waitcnt vmcnt(1)
	ds_write_b128 v122, v[162:165] offset:4096
	s_waitcnt vmcnt(0)
	ds_write_b128 v122, v[166:169] offset:5120
	s_waitcnt lgkmcnt(0)
	v_and_b32_e32 v68, 64, v224
	v_xor_b32_e32 v67, 4, v224
	v_add_u32_e32 v68, 64, v68
	v_cmp_lt_i32_e32 vcc, v67, v68
	v_lshl_or_b32 v64, v71, 2, v64
	s_waitcnt vmcnt(2)
	v_and_b32_e32 v119, 3, v143
	v_cndmask_b32_e32 v67, v224, v67, vcc
	v_lshlrev_b32_e32 v118, 2, v67
	ds_bpermute_b32 v67, v118, v48
	v_mul_lo_u32 v68, v64, 24
	v_cmp_gt_u32_e64 s[6:7], 8, v129
	v_cmp_gt_u32_e32 vcc, 4, v129
	v_or_b32_e32 v100, v68, v119
	s_and_saveexec_b64 s[2:3], s[6:7]
	s_cbranch_execz .LBB0_272
	v_ashrrev_i32_e32 v101, 31, v100
	v_lshl_add_u32 v68, v100, 2, v127
	ds_read_b32 v70, v68 offset:16
	s_nop 0
	ds_read_b32 v68, v68
	s_waitcnt lgkmcnt(0)
	v_mul_f32_e32 v67, v70, v67
	v_cndmask_b32_e64 v67, v67, -v67, vcc
	s_waitcnt lgkmcnt(0)
	v_fmac_f32_e32 v67, v48, v68
	v_mov_b32_e32 v48, v67
.LBB0_272:
	s_or_b64 exec, exec, s[2:3]
	v_cmp_gt_i32_e64 s[8:9], 4, v65
	v_and_b32_e32 v65, 0xc0, v66
	v_cvt_pk_bf16_f32 v48, v48, s0
	v_cndmask_b32_e64 v178, v225, 0, s[8:9]
	v_lshl_add_u64 v[68:69], s[10:11], 0, v[178:179]
	v_lshlrev_b32_e32 v178, 1, v65
	s_waitcnt lgkmcnt(0)
	v_lshl_add_u64 v[66:67], v[68:69], 0, v[178:179]
	v_lshlrev_b32_e32 v178, 1, v129
	v_ashrrev_i32_e32 v65, 31, v64
	v_lshl_add_u64 v[66:67], v[66:67], 0, v[178:179]
	v_lshlrev_b64 v[68:69], 9, v[64:65]
	ds_bpermute_b32 v65, v118, v49
	v_lshl_add_u64 v[116:117], v[66:67], 0, v[68:69]
	global_store_short v[116:117], v48, off
	v_or_b32_e32 v48, 1, v64
	v_mul_lo_u32 v68, v48, 24
	v_or_b32_e32 v108, v68, v119
	s_and_saveexec_b64 s[2:3], s[6:7]
	s_cbranch_execz .LBB0_274
	v_ashrrev_i32_e32 v109, 31, v108
	v_lshl_add_u32 v68, v108, 2, v127
	ds_read_b32 v70, v68 offset:16
	s_nop 0
	ds_read_b32 v68, v68
	s_waitcnt lgkmcnt(0)
	v_mul_f32_e32 v65, v70, v65
	v_cndmask_b32_e64 v65, v65, -v65, vcc
	s_waitcnt lgkmcnt(0)
	v_fmac_f32_e32 v65, v49, v68
	v_mov_b32_e32 v49, v65
.LBB0_274:
	s_or_b64 exec, exec, s[2:3]
	s_waitcnt lgkmcnt(0)
	v_cvt_pk_bf16_f32 v65, v49, s0
	v_ashrrev_i32_e32 v49, 31, v48
	v_lshlrev_b64 v[48:49], 9, v[48:49]
	v_lshl_add_u64 v[114:115], v[66:67], 0, v[48:49]
	ds_bpermute_b32 v49, v118, v50
	v_or_b32_e32 v48, 2, v64
	global_store_short v[114:115], v65, off
	v_mul_lo_u32 v65, v48, 24
	v_or_b32_e32 v104, v65, v119
	s_and_saveexec_b64 s[2:3], s[6:7]
	s_cbranch_execz .LBB0_276
	v_ashrrev_i32_e32 v105, 31, v104
	v_lshl_add_u32 v68, v104, 2, v127
	ds_read_b32 v65, v68 offset:16
	s_nop 0
	ds_read_b32 v68, v68
	s_waitcnt lgkmcnt(0)
	v_mul_f32_e32 v49, v65, v49
	v_cndmask_b32_e64 v49, v49, -v49, vcc
	s_waitcnt lgkmcnt(0)
	v_fmac_f32_e32 v49, v50, v68
	v_mov_b32_e32 v50, v49
.LBB0_276:
	s_or_b64 exec, exec, s[2:3]
	s_waitcnt lgkmcnt(0)
	v_ashrrev_i32_e32 v49, 31, v48
	v_lshlrev_b64 v[48:49], 9, v[48:49]
	v_lshl_add_u64 v[112:113], v[66:67], 0, v[48:49]
	ds_bpermute_b32 v49, v118, v51
	v_cvt_pk_bf16_f32 v50, v50, s0
	v_or_b32_e32 v48, 3, v64
	global_store_short v[112:113], v50, off
	v_mul_lo_u32 v50, v48, 24
	v_or_b32_e32 v98, v50, v119
	s_and_saveexec_b64 s[2:3], s[6:7]
	s_cbranch_execz .LBB0_278
	v_ashrrev_i32_e32 v99, 31, v98
	v_lshl_add_u32 v68, v98, 2, v127
	ds_read_b32 v50, v68 offset:16
	ds_read_b32 v65, v68
	s_waitcnt lgkmcnt(0)
	v_mul_f32_e32 v49, v50, v49
	v_cndmask_b32_e64 v49, v49, -v49, vcc
	s_waitcnt lgkmcnt(0)
	v_fmac_f32_e32 v49, v51, v65
	v_mov_b32_e32 v51, v49
.LBB0_278:
	s_or_b64 exec, exec, s[2:3]
	s_waitcnt lgkmcnt(0)
	v_ashrrev_i32_e32 v49, 31, v48
	v_lshlrev_b64 v[48:49], 9, v[48:49]
	v_lshl_add_u64 v[110:111], v[66:67], 0, v[48:49]
	ds_bpermute_b32 v49, v118, v52
	v_cvt_pk_bf16_f32 v50, v51, s0
	v_or_b32_e32 v48, 8, v64
	global_store_short v[110:111], v50, off
	v_mul_lo_u32 v50, v48, 24
	v_or_b32_e32 v94, v50, v119
	s_and_saveexec_b64 s[2:3], s[6:7]
	s_cbranch_execz .LBB0_280
	v_ashrrev_i32_e32 v95, 31, v94
	v_lshl_add_u32 v50, v94, 2, v127
	ds_read_b32 v65, v50 offset:16
	s_nop 0
	ds_read_b32 v50, v50
	s_waitcnt lgkmcnt(0)
	v_mul_f32_e32 v49, v65, v49
	v_cndmask_b32_e64 v49, v49, -v49, vcc
	s_waitcnt lgkmcnt(0)
	v_fmac_f32_e32 v49, v52, v50
	v_mov_b32_e32 v52, v49
.LBB0_280:
	s_or_b64 exec, exec, s[2:3]
	s_waitcnt lgkmcnt(0)
	v_ashrrev_i32_e32 v49, 31, v48
	v_lshlrev_b64 v[48:49], 9, v[48:49]
	v_lshl_add_u64 v[106:107], v[66:67], 0, v[48:49]
	ds_bpermute_b32 v49, v118, v53
	v_cvt_pk_bf16_f32 v50, v52, s0
	v_or_b32_e32 v48, 9, v64
	global_store_short v[106:107], v50, off
	v_mul_lo_u32 v50, v48, 24
	v_or_b32_e32 v90, v50, v119
	s_and_saveexec_b64 s[2:3], s[6:7]
	s_cbranch_execz .LBB0_282
	v_ashrrev_i32_e32 v91, 31, v90
	v_lshl_add_u32 v50, v90, 2, v127
	ds_read_b32 v52, v50 offset:16
	s_nop 0
	ds_read_b32 v50, v50
	s_waitcnt lgkmcnt(0)
	v_mul_f32_e32 v49, v52, v49
	v_cndmask_b32_e64 v49, v49, -v49, vcc
	s_waitcnt lgkmcnt(0)
	v_fmac_f32_e32 v49, v53, v50
	v_mov_b32_e32 v53, v49
.LBB0_282:
	s_or_b64 exec, exec, s[2:3]
	s_waitcnt lgkmcnt(0)
	v_ashrrev_i32_e32 v49, 31, v48
	v_lshlrev_b64 v[48:49], 9, v[48:49]
	v_lshl_add_u64 v[102:103], v[66:67], 0, v[48:49]
	ds_bpermute_b32 v49, v118, v54
	v_cvt_pk_bf16_f32 v50, v53, s0
	v_or_b32_e32 v48, 10, v64
	global_store_short v[102:103], v50, off
	v_mul_lo_u32 v50, v48, 24
	v_or_b32_e32 v86, v50, v119
	s_and_saveexec_b64 s[2:3], s[6:7]
	s_cbranch_execz .LBB0_284
	v_ashrrev_i32_e32 v87, 31, v86
	v_lshl_add_u32 v50, v86, 2, v127
	ds_read_b32 v52, v50 offset:16
	s_nop 0
	ds_read_b32 v50, v50
	s_waitcnt lgkmcnt(0)
	v_mul_f32_e32 v49, v52, v49
	v_cndmask_b32_e64 v49, v49, -v49, vcc
	s_waitcnt lgkmcnt(0)
	v_fmac_f32_e32 v49, v54, v50
	v_mov_b32_e32 v54, v49
.LBB0_284:
	s_or_b64 exec, exec, s[2:3]
	s_waitcnt lgkmcnt(0)
	v_ashrrev_i32_e32 v49, 31, v48
	v_lshlrev_b64 v[48:49], 9, v[48:49]
	v_lshl_add_u64 v[96:97], v[66:67], 0, v[48:49]
	ds_bpermute_b32 v49, v118, v55
	v_cvt_pk_bf16_f32 v50, v54, s0
	v_or_b32_e32 v48, 11, v64
	global_store_short v[96:97], v50, off
	v_mul_lo_u32 v50, v48, 24
	v_or_b32_e32 v82, v50, v119
	s_and_saveexec_b64 s[2:3], s[6:7]
	s_cbranch_execz .LBB0_286
	v_ashrrev_i32_e32 v83, 31, v82
	v_lshl_add_u32 v50, v82, 2, v127
	ds_read_b32 v52, v50 offset:16
	s_nop 0
	ds_read_b32 v50, v50
	s_waitcnt lgkmcnt(0)
	v_mul_f32_e32 v49, v52, v49
	v_cndmask_b32_e64 v49, v49, -v49, vcc
	s_waitcnt lgkmcnt(0)
	v_fmac_f32_e32 v49, v55, v50
	v_mov_b32_e32 v55, v49
.LBB0_286:
	s_or_b64 exec, exec, s[2:3]
	s_waitcnt lgkmcnt(0)
	v_ashrrev_i32_e32 v49, 31, v48
	v_lshlrev_b64 v[48:49], 9, v[48:49]
	v_lshl_add_u64 v[92:93], v[66:67], 0, v[48:49]
	ds_bpermute_b32 v49, v118, v56
	v_cvt_pk_bf16_f32 v50, v55, s0
	v_or_b32_e32 v48, 16, v64
	global_store_short v[92:93], v50, off
	v_mul_lo_u32 v50, v48, 24
	v_or_b32_e32 v78, v50, v119
	s_and_saveexec_b64 s[2:3], s[6:7]
	s_cbranch_execz .LBB0_288
	v_ashrrev_i32_e32 v79, 31, v78
	v_lshl_add_u32 v50, v78, 2, v127
	ds_read_b32 v52, v50 offset:16
	s_nop 0
	ds_read_b32 v50, v50
	s_waitcnt lgkmcnt(0)
	v_mul_f32_e32 v49, v52, v49
	v_cndmask_b32_e64 v49, v49, -v49, vcc
	s_waitcnt lgkmcnt(0)
	v_fmac_f32_e32 v49, v56, v50
	v_mov_b32_e32 v56, v49
.LBB0_288:
	s_or_b64 exec, exec, s[2:3]
	s_waitcnt lgkmcnt(0)
	v_ashrrev_i32_e32 v49, 31, v48
	v_lshlrev_b64 v[48:49], 9, v[48:49]
	v_lshl_add_u64 v[88:89], v[66:67], 0, v[48:49]
	ds_bpermute_b32 v49, v118, v57
	v_cvt_pk_bf16_f32 v50, v56, s0
	v_or_b32_e32 v48, 17, v64
	global_store_short v[88:89], v50, off
	v_mul_lo_u32 v50, v48, 24
	v_or_b32_e32 v74, v50, v119
	s_and_saveexec_b64 s[2:3], s[6:7]
	s_cbranch_execz .LBB0_290
	v_ashrrev_i32_e32 v75, 31, v74
	v_lshl_add_u32 v50, v74, 2, v127
	ds_read_b32 v52, v50 offset:16
	s_nop 0
	ds_read_b32 v50, v50
	s_waitcnt lgkmcnt(0)
	v_mul_f32_e32 v49, v52, v49
	v_cndmask_b32_e64 v49, v49, -v49, vcc
	s_waitcnt lgkmcnt(0)
	v_fmac_f32_e32 v49, v57, v50
	v_mov_b32_e32 v57, v49
.LBB0_290:
	s_or_b64 exec, exec, s[2:3]
	s_waitcnt lgkmcnt(0)
	v_ashrrev_i32_e32 v49, 31, v48
	v_lshlrev_b64 v[48:49], 9, v[48:49]
	v_lshl_add_u64 v[84:85], v[66:67], 0, v[48:49]
	ds_bpermute_b32 v49, v118, v58
	v_cvt_pk_bf16_f32 v50, v57, s0
	v_or_b32_e32 v48, 18, v64
	global_store_short v[84:85], v50, off
	v_mul_lo_u32 v50, v48, 24
	v_or_b32_e32 v70, v50, v119
	s_and_saveexec_b64 s[2:3], s[6:7]
	s_cbranch_execz .LBB0_292
	v_ashrrev_i32_e32 v71, 31, v70
	v_lshl_add_u32 v50, v70, 2, v127
	ds_read_b32 v52, v50 offset:16
	s_nop 0
	ds_read_b32 v50, v50
	s_waitcnt lgkmcnt(0)
	v_mul_f32_e32 v49, v52, v49
	v_cndmask_b32_e64 v49, v49, -v49, vcc
	s_waitcnt lgkmcnt(0)
	v_fmac_f32_e32 v49, v58, v50
	v_mov_b32_e32 v58, v49
.LBB0_292:
	s_or_b64 exec, exec, s[2:3]
	s_waitcnt lgkmcnt(0)
	v_ashrrev_i32_e32 v49, 31, v48
	v_lshlrev_b64 v[48:49], 9, v[48:49]
	v_lshl_add_u64 v[80:81], v[66:67], 0, v[48:49]
	ds_bpermute_b32 v49, v118, v59
	v_cvt_pk_bf16_f32 v50, v58, s0
	v_or_b32_e32 v48, 19, v64
	global_store_short v[80:81], v50, off
	v_mul_lo_u32 v50, v48, 24
	v_or_b32_e32 v68, v50, v119
	s_and_saveexec_b64 s[2:3], s[6:7]
	s_cbranch_execz .LBB0_294
	v_ashrrev_i32_e32 v69, 31, v68
	v_lshl_add_u32 v50, v68, 2, v127
	ds_read_b32 v52, v50 offset:16
	s_nop 0
	ds_read_b32 v50, v50
	s_waitcnt lgkmcnt(0)
	v_mul_f32_e32 v49, v52, v49
	v_cndmask_b32_e64 v49, v49, -v49, vcc
	s_waitcnt lgkmcnt(0)
	v_fmac_f32_e32 v49, v59, v50
	v_mov_b32_e32 v59, v49
.LBB0_294:
	s_or_b64 exec, exec, s[2:3]
	s_waitcnt lgkmcnt(0)
	v_ashrrev_i32_e32 v49, 31, v48
	v_lshlrev_b64 v[48:49], 9, v[48:49]
	v_lshl_add_u64 v[76:77], v[66:67], 0, v[48:49]
	ds_bpermute_b32 v49, v118, v60
	v_cvt_pk_bf16_f32 v50, v59, s0
	v_or_b32_e32 v48, 24, v64
	global_store_short v[76:77], v50, off
	v_mul_lo_u32 v50, v48, 24
	v_or_b32_e32 v56, v50, v119
	s_and_saveexec_b64 s[2:3], s[6:7]
	s_cbranch_execz .LBB0_296
	v_ashrrev_i32_e32 v57, 31, v56
	v_lshl_add_u32 v50, v56, 2, v127
	ds_read_b32 v52, v50 offset:16
	s_nop 0
	ds_read_b32 v50, v50
	s_waitcnt lgkmcnt(0)
	v_mul_f32_e32 v49, v52, v49
	v_cndmask_b32_e64 v49, v49, -v49, vcc
	s_waitcnt lgkmcnt(0)
	v_fmac_f32_e32 v49, v60, v50
	v_mov_b32_e32 v60, v49
.LBB0_296:
	s_or_b64 exec, exec, s[2:3]
	s_waitcnt lgkmcnt(0)
	v_ashrrev_i32_e32 v49, 31, v48
	v_lshlrev_b64 v[48:49], 9, v[48:49]
	v_lshl_add_u64 v[72:73], v[66:67], 0, v[48:49]
	ds_bpermute_b32 v49, v118, v61
	v_cvt_pk_bf16_f32 v50, v60, s0
	v_or_b32_e32 v48, 25, v64
	global_store_short v[72:73], v50, off
	v_mul_lo_u32 v50, v48, 24
	v_or_b32_e32 v54, v50, v119
	s_and_saveexec_b64 s[2:3], s[6:7]
	s_cbranch_execz .LBB0_298
	v_ashrrev_i32_e32 v55, 31, v54
	v_lshl_add_u32 v50, v54, 2, v127
	ds_read_b32 v52, v50 offset:16
	s_nop 0
	ds_read_b32 v50, v50
	s_waitcnt lgkmcnt(0)
	v_mul_f32_e32 v49, v52, v49
	v_cndmask_b32_e64 v49, v49, -v49, vcc
	s_waitcnt lgkmcnt(0)
	v_fmac_f32_e32 v49, v61, v50
	v_mov_b32_e32 v61, v49
.LBB0_298:
	s_or_b64 exec, exec, s[2:3]
	s_waitcnt lgkmcnt(0)
	v_ashrrev_i32_e32 v49, 31, v48
	v_lshlrev_b64 v[48:49], 9, v[48:49]
	v_cvt_pk_bf16_f32 v50, v61, s0
	v_lshl_add_u64 v[60:61], v[66:67], 0, v[48:49]
	ds_bpermute_b32 v49, v118, v62
	v_or_b32_e32 v48, 26, v64
	global_store_short v[60:61], v50, off
	v_mul_lo_u32 v50, v48, 24
	v_or_b32_e32 v50, v50, v119
	s_and_saveexec_b64 s[2:3], s[6:7]
	s_cbranch_execz .LBB0_300
	v_ashrrev_i32_e32 v51, 31, v50
	v_lshl_add_u32 v52, v50, 2, v127
	ds_read_b32 v51, v52 offset:16
	s_nop 0
	ds_read_b32 v52, v52
	s_waitcnt lgkmcnt(0)
	v_mul_f32_e32 v49, v51, v49
	v_cndmask_b32_e64 v49, v49, -v49, vcc
	s_waitcnt lgkmcnt(0)
	v_fmac_f32_e32 v49, v62, v52
	v_mov_b32_e32 v62, v49
.LBB0_300:
	s_or_b64 exec, exec, s[2:3]
	s_waitcnt lgkmcnt(0)
	v_ashrrev_i32_e32 v49, 31, v48
	v_lshlrev_b64 v[48:49], 9, v[48:49]
	ds_bpermute_b32 v51, v118, v63
	v_cvt_pk_bf16_f32 v52, v62, s0
	v_lshl_add_u64 v[58:59], v[66:67], 0, v[48:49]
	global_store_short v[58:59], v52, off
	v_or_b32_e32 v52, 27, v64
	v_mul_lo_u32 v48, v52, 24
	v_or_b32_e32 v48, v48, v119
	s_and_saveexec_b64 s[2:3], s[6:7]
	s_cbranch_execz .LBB0_302
	v_ashrrev_i32_e32 v49, 31, v48
	s_waitcnt vmcnt(16)
	v_lshl_add_u32 v120, v48, 2, v127
	ds_read_b32 v49, v120 offset:16
	ds_read_b32 v53, v120
	s_waitcnt lgkmcnt(0)
	v_mul_f32_e32 v49, v49, v51
	v_cndmask_b32_e64 v49, v49, -v49, vcc
	s_waitcnt lgkmcnt(0)
	v_fmac_f32_e32 v49, v63, v53
	v_mov_b32_e32 v63, v49
.LBB0_302:
	s_or_b64 exec, exec, s[2:3]
	v_ashrrev_i32_e32 v53, 31, v52
	v_lshlrev_b64 v[52:53], 9, v[52:53]
	v_cvt_pk_bf16_f32 v49, v63, s0
	v_lshl_add_u64 v[52:53], v[66:67], 0, v[52:53]
	global_store_short v[52:53], v49, off
	ds_bpermute_b32 v49, v118, v32
	s_and_saveexec_b64 s[2:3], s[6:7]
	s_cbranch_execz .LBB0_304
	v_ashrrev_i32_e32 v101, 31, v100
	v_lshl_add_u32 v62, v100, 2, v127
	s_waitcnt lgkmcnt(1)
	ds_read_b32 v51, v62 offset:16
	ds_read_b32 v55, v62
	s_waitcnt lgkmcnt(0)
	v_mul_f32_e32 v49, v51, v49
	v_cndmask_b32_e64 v49, v49, -v49, vcc
	s_waitcnt lgkmcnt(0)
	v_fmac_f32_e32 v49, v32, v55
	v_mov_b32_e32 v32, v49
.LBB0_304:
	s_or_b64 exec, exec, s[2:3]
	v_cvt_pk_bf16_f32 v32, v32, s0
	global_store_short v[116:117], v32, off offset:64
	ds_bpermute_b32 v32, v118, v33
	s_and_saveexec_b64 s[2:3], s[6:7]
	s_cbranch_execz .LBB0_306
	v_ashrrev_i32_e32 v109, 31, v108
	v_lshl_add_u32 v62, v108, 2, v127
	s_waitcnt lgkmcnt(1)
	ds_read_b32 v49, v62 offset:16
	ds_read_b32 v51, v62
	s_waitcnt lgkmcnt(0)
	v_mul_f32_e32 v32, v49, v32
	v_cndmask_b32_e64 v32, v32, -v32, vcc
	s_waitcnt lgkmcnt(0)
	v_fmac_f32_e32 v32, v33, v51
	v_mov_b32_e32 v33, v32
.LBB0_306:
	s_or_b64 exec, exec, s[2:3]
	s_waitcnt lgkmcnt(0)
	v_cvt_pk_bf16_f32 v32, v33, s0
	global_store_short v[114:115], v32, off offset:64
	ds_bpermute_b32 v32, v118, v34
	s_and_saveexec_b64 s[2:3], s[6:7]
	s_cbranch_execz .LBB0_308
	v_ashrrev_i32_e32 v105, 31, v104
	v_lshl_add_u32 v62, v104, 2, v127
	ds_read_b32 v33, v62 offset:16
	ds_read_b32 v49, v62
	s_waitcnt lgkmcnt(0)
	v_mul_f32_e32 v32, v33, v32
	v_cndmask_b32_e64 v32, v32, -v32, vcc
	s_waitcnt lgkmcnt(0)
	v_fmac_f32_e32 v32, v34, v49
	v_mov_b32_e32 v34, v32
.LBB0_308:
	s_or_b64 exec, exec, s[2:3]
	s_waitcnt lgkmcnt(0)
	v_cvt_pk_bf16_f32 v32, v34, s0
	global_store_short v[112:113], v32, off offset:64
	ds_bpermute_b32 v32, v118, v35
	s_and_saveexec_b64 s[2:3], s[6:7]
	s_cbranch_execz .LBB0_310
	v_ashrrev_i32_e32 v99, 31, v98
	v_lshl_add_u32 v62, v98, 2, v127
	ds_read_b32 v33, v62 offset:16
	ds_read_b32 v34, v62
	s_waitcnt lgkmcnt(0)
	v_mul_f32_e32 v32, v33, v32
	v_cndmask_b32_e64 v32, v32, -v32, vcc
	s_waitcnt lgkmcnt(0)
	v_fmac_f32_e32 v32, v35, v34
	v_mov_b32_e32 v35, v32
.LBB0_310:
	s_or_b64 exec, exec, s[2:3]
	s_waitcnt lgkmcnt(0)
	v_cvt_pk_bf16_f32 v32, v35, s0
	global_store_short v[110:111], v32, off offset:64
	ds_bpermute_b32 v32, v118, v36
	s_and_saveexec_b64 s[2:3], s[6:7]
	s_cbranch_execz .LBB0_312
	v_ashrrev_i32_e32 v95, 31, v94
	v_lshl_add_u32 v34, v94, 2, v127
	ds_read_b32 v33, v34 offset:16
	s_nop 0
	ds_read_b32 v34, v34
	s_waitcnt lgkmcnt(0)
	v_mul_f32_e32 v32, v33, v32
	v_cndmask_b32_e64 v32, v32, -v32, vcc
	s_waitcnt lgkmcnt(0)
	v_fmac_f32_e32 v32, v36, v34
	v_mov_b32_e32 v36, v32
.LBB0_312:
	s_or_b64 exec, exec, s[2:3]
	s_waitcnt lgkmcnt(0)
	v_cvt_pk_bf16_f32 v32, v36, s0
	global_store_short v[106:107], v32, off offset:64
	ds_bpermute_b32 v32, v118, v37
	s_and_saveexec_b64 s[2:3], s[6:7]
	s_cbranch_execz .LBB0_314
	v_ashrrev_i32_e32 v91, 31, v90
	v_lshl_add_u32 v34, v90, 2, v127
	ds_read_b32 v33, v34 offset:16
	s_nop 0
	ds_read_b32 v34, v34
	s_waitcnt lgkmcnt(0)
	v_mul_f32_e32 v32, v33, v32
	v_cndmask_b32_e64 v32, v32, -v32, vcc
	s_waitcnt lgkmcnt(0)
	v_fmac_f32_e32 v32, v37, v34
	v_mov_b32_e32 v37, v32
.LBB0_314:
	s_or_b64 exec, exec, s[2:3]
	s_waitcnt lgkmcnt(0)
	v_cvt_pk_bf16_f32 v32, v37, s0
	global_store_short v[102:103], v32, off offset:64
	ds_bpermute_b32 v32, v118, v38
	s_and_saveexec_b64 s[2:3], s[6:7]
	s_cbranch_execz .LBB0_316
	v_ashrrev_i32_e32 v87, 31, v86
	v_lshl_add_u32 v34, v86, 2, v127
	ds_read_b32 v33, v34 offset:16
	s_nop 0
	ds_read_b32 v34, v34
	s_waitcnt lgkmcnt(0)
	v_mul_f32_e32 v32, v33, v32
	v_cndmask_b32_e64 v32, v32, -v32, vcc
	s_waitcnt lgkmcnt(0)
	v_fmac_f32_e32 v32, v38, v34
	v_mov_b32_e32 v38, v32
.LBB0_316:
	s_or_b64 exec, exec, s[2:3]
	s_waitcnt lgkmcnt(0)
	v_cvt_pk_bf16_f32 v32, v38, s0
	global_store_short v[96:97], v32, off offset:64
	ds_bpermute_b32 v32, v118, v39
	s_and_saveexec_b64 s[2:3], s[6:7]
	s_cbranch_execz .LBB0_318
	v_ashrrev_i32_e32 v83, 31, v82
	v_lshl_add_u32 v34, v82, 2, v127
	ds_read_b32 v33, v34 offset:16
	s_nop 0
	ds_read_b32 v34, v34
	s_waitcnt lgkmcnt(0)
	v_mul_f32_e32 v32, v33, v32
	v_cndmask_b32_e64 v32, v32, -v32, vcc
	s_waitcnt lgkmcnt(0)
	v_fmac_f32_e32 v32, v39, v34
	v_mov_b32_e32 v39, v32
.LBB0_318:
	s_or_b64 exec, exec, s[2:3]
	s_waitcnt lgkmcnt(0)
	v_cvt_pk_bf16_f32 v32, v39, s0
	global_store_short v[92:93], v32, off offset:64
	ds_bpermute_b32 v32, v118, v40
	s_and_saveexec_b64 s[2:3], s[6:7]
	s_cbranch_execz .LBB0_320
	v_ashrrev_i32_e32 v79, 31, v78
	v_lshl_add_u32 v34, v78, 2, v127
	ds_read_b32 v33, v34 offset:16
	s_nop 0
	ds_read_b32 v34, v34
	s_waitcnt lgkmcnt(0)
	v_mul_f32_e32 v32, v33, v32
	v_cndmask_b32_e64 v32, v32, -v32, vcc
	s_waitcnt lgkmcnt(0)
	v_fmac_f32_e32 v32, v40, v34
	v_mov_b32_e32 v40, v32
.LBB0_320:
	s_or_b64 exec, exec, s[2:3]
	s_waitcnt lgkmcnt(0)
	v_cvt_pk_bf16_f32 v32, v40, s0
	global_store_short v[88:89], v32, off offset:64
	ds_bpermute_b32 v32, v118, v41
	s_and_saveexec_b64 s[2:3], s[6:7]
	s_cbranch_execz .LBB0_322
	v_ashrrev_i32_e32 v75, 31, v74
	v_lshl_add_u32 v34, v74, 2, v127
	ds_read_b32 v33, v34 offset:16
	s_nop 0
	ds_read_b32 v34, v34
	s_waitcnt lgkmcnt(0)
	v_mul_f32_e32 v32, v33, v32
	v_cndmask_b32_e64 v32, v32, -v32, vcc
	s_waitcnt lgkmcnt(0)
	v_fmac_f32_e32 v32, v41, v34
	v_mov_b32_e32 v41, v32
.LBB0_322:
	s_or_b64 exec, exec, s[2:3]
	s_waitcnt lgkmcnt(0)
	v_cvt_pk_bf16_f32 v32, v41, s0
	global_store_short v[84:85], v32, off offset:64
	ds_bpermute_b32 v32, v118, v42
	s_and_saveexec_b64 s[2:3], s[6:7]
	s_cbranch_execz .LBB0_324
	v_ashrrev_i32_e32 v71, 31, v70
	v_lshl_add_u32 v34, v70, 2, v127
	ds_read_b32 v33, v34 offset:16
	s_nop 0
	ds_read_b32 v34, v34
	s_waitcnt lgkmcnt(0)
	v_mul_f32_e32 v32, v33, v32
	v_cndmask_b32_e64 v32, v32, -v32, vcc
	s_waitcnt lgkmcnt(0)
	v_fmac_f32_e32 v32, v42, v34
	v_mov_b32_e32 v42, v32
.LBB0_324:
	s_or_b64 exec, exec, s[2:3]
	s_waitcnt lgkmcnt(0)
	v_cvt_pk_bf16_f32 v32, v42, s0
	global_store_short v[80:81], v32, off offset:64
	ds_bpermute_b32 v32, v118, v43
	s_and_saveexec_b64 s[2:3], s[6:7]
	s_cbranch_execz .LBB0_326
	v_ashrrev_i32_e32 v69, 31, v68
	v_lshl_add_u32 v34, v68, 2, v127
	ds_read_b32 v33, v34 offset:16
	s_nop 0
	ds_read_b32 v34, v34
	s_waitcnt lgkmcnt(0)
	v_mul_f32_e32 v32, v33, v32
	v_cndmask_b32_e64 v32, v32, -v32, vcc
	s_waitcnt lgkmcnt(0)
	v_fmac_f32_e32 v32, v43, v34
	v_mov_b32_e32 v43, v32
.LBB0_326:
	s_or_b64 exec, exec, s[2:3]
	s_waitcnt lgkmcnt(0)
	v_cvt_pk_bf16_f32 v32, v43, s0
	global_store_short v[76:77], v32, off offset:64
	ds_bpermute_b32 v32, v118, v44
	s_and_saveexec_b64 s[2:3], s[6:7]
	s_cbranch_execz .LBB0_328
	v_ashrrev_i32_e32 v57, 31, v56
	v_lshl_add_u32 v34, v56, 2, v127
	ds_read_b32 v33, v34 offset:16
	s_nop 0
	ds_read_b32 v34, v34
	s_waitcnt lgkmcnt(0)
	v_mul_f32_e32 v32, v33, v32
	v_cndmask_b32_e64 v32, v32, -v32, vcc
	s_waitcnt lgkmcnt(0)
	v_fmac_f32_e32 v32, v44, v34
	v_mov_b32_e32 v44, v32
.LBB0_328:
	s_or_b64 exec, exec, s[2:3]
	s_waitcnt lgkmcnt(0)
	v_cvt_pk_bf16_f32 v32, v44, s0
	global_store_short v[72:73], v32, off offset:64
	ds_bpermute_b32 v32, v118, v45
	s_and_saveexec_b64 s[2:3], s[6:7]
	s_cbranch_execz .LBB0_330
	v_ashrrev_i32_e32 v55, 31, v54
	v_lshl_add_u32 v34, v54, 2, v127
	ds_read_b32 v33, v34 offset:16
	s_nop 0
	ds_read_b32 v34, v34
	s_waitcnt lgkmcnt(0)
	v_mul_f32_e32 v32, v33, v32
	v_cndmask_b32_e64 v32, v32, -v32, vcc
	s_waitcnt lgkmcnt(0)
	v_fmac_f32_e32 v32, v45, v34
	v_mov_b32_e32 v45, v32
.LBB0_330:
	s_or_b64 exec, exec, s[2:3]
	s_waitcnt lgkmcnt(0)
	v_cvt_pk_bf16_f32 v32, v45, s0
	global_store_short v[60:61], v32, off offset:64
	ds_bpermute_b32 v32, v118, v46
	s_and_saveexec_b64 s[2:3], s[6:7]
	s_cbranch_execz .LBB0_332
	v_ashrrev_i32_e32 v51, 31, v50
	v_lshl_add_u32 v34, v50, 2, v127
	ds_read_b32 v33, v34 offset:16
	s_nop 0
	ds_read_b32 v34, v34
	s_waitcnt lgkmcnt(0)
	v_mul_f32_e32 v32, v33, v32
	v_cndmask_b32_e64 v32, v32, -v32, vcc
	s_waitcnt lgkmcnt(0)
	v_fmac_f32_e32 v32, v46, v34
	v_mov_b32_e32 v46, v32
.LBB0_332:
	s_or_b64 exec, exec, s[2:3]
	s_waitcnt lgkmcnt(0)
	v_cvt_pk_bf16_f32 v32, v46, s0
	global_store_short v[58:59], v32, off offset:64
	ds_bpermute_b32 v32, v118, v47
	s_and_saveexec_b64 s[2:3], s[6:7]
	s_cbranch_execz .LBB0_334
	v_ashrrev_i32_e32 v49, 31, v48
	v_lshl_add_u32 v34, v48, 2, v127
	ds_read_b32 v33, v34 offset:16
	s_nop 0
	ds_read_b32 v34, v34
	s_waitcnt lgkmcnt(0)
	v_mul_f32_e32 v32, v33, v32
	v_cndmask_b32_e64 v32, v32, -v32, vcc
	s_waitcnt lgkmcnt(0)
	v_fmac_f32_e32 v32, v47, v34
	v_mov_b32_e32 v47, v32
.LBB0_334:
	s_or_b64 exec, exec, s[2:3]
	ds_bpermute_b32 v33, v118, v16
	s_waitcnt lgkmcnt(1)
	v_cvt_pk_bf16_f32 v32, v47, s0
	global_store_short v[52:53], v32, off offset:64
	v_or_b32_e32 v32, 32, v64
	v_mul_lo_u32 v34, v32, 24
	v_or_b32_e32 v78, v34, v119
	s_and_saveexec_b64 s[2:3], s[6:7]
	s_cbranch_execz .LBB0_336
	v_ashrrev_i32_e32 v79, 31, v78
	v_lshl_add_u32 v34, v78, 2, v127
	ds_read_b32 v36, v34 offset:16
	s_nop 0
	ds_read_b32 v34, v34
	s_waitcnt lgkmcnt(0)
	v_mul_f32_e32 v33, v36, v33
	v_cndmask_b32_e64 v33, v33, -v33, vcc
	s_waitcnt lgkmcnt(0)
	v_fmac_f32_e32 v33, v16, v34
	v_mov_b32_e32 v16, v33
.LBB0_336:
	s_or_b64 exec, exec, s[2:3]
	s_waitcnt lgkmcnt(0)
	v_ashrrev_i32_e32 v33, 31, v32
	v_lshlrev_b64 v[32:33], 9, v[32:33]
	v_lshl_add_u64 v[84:85], v[66:67], 0, v[32:33]
	ds_bpermute_b32 v32, v118, v17
	v_cvt_pk_bf16_f32 v16, v16, s0
	global_store_short v[84:85], v16, off
	v_or_b32_e32 v16, 33, v64
	v_mul_lo_u32 v33, v16, 24
	v_or_b32_e32 v74, v33, v119
	s_and_saveexec_b64 s[2:3], s[6:7]
	s_cbranch_execz .LBB0_338
	v_ashrrev_i32_e32 v75, 31, v74
	v_lshl_add_u32 v34, v74, 2, v127
	ds_read_b32 v33, v34 offset:16
	s_nop 0
	ds_read_b32 v34, v34
	s_waitcnt lgkmcnt(0)
	v_mul_f32_e32 v32, v33, v32
	v_cndmask_b32_e64 v32, v32, -v32, vcc
	s_waitcnt lgkmcnt(0)
	v_fmac_f32_e32 v32, v17, v34
	v_mov_b32_e32 v17, v32
.LBB0_338:
	s_or_b64 exec, exec, s[2:3]
	s_waitcnt lgkmcnt(0)
	v_cvt_pk_bf16_f32 v32, v17, s0
	v_ashrrev_i32_e32 v17, 31, v16
	v_lshlrev_b64 v[16:17], 9, v[16:17]
	v_lshl_add_u64 v[82:83], v[66:67], 0, v[16:17]
	ds_bpermute_b32 v17, v118, v18
	v_or_b32_e32 v16, 34, v64
	global_store_short v[82:83], v32, off
	v_mul_lo_u32 v32, v16, 24
	v_or_b32_e32 v70, v32, v119
	s_and_saveexec_b64 s[2:3], s[6:7]
	s_cbranch_execz .LBB0_340
	v_ashrrev_i32_e32 v71, 31, v70
	v_lshl_add_u32 v32, v70, 2, v127
	ds_read_b32 v34, v32 offset:16
	s_nop 0
	ds_read_b32 v32, v32
	s_waitcnt lgkmcnt(0)
	v_mul_f32_e32 v17, v34, v17
	v_cndmask_b32_e64 v17, v17, -v17, vcc
	s_waitcnt lgkmcnt(0)
	v_fmac_f32_e32 v17, v18, v32
	v_mov_b32_e32 v18, v17
.LBB0_340:
	s_or_b64 exec, exec, s[2:3]
	s_waitcnt lgkmcnt(0)
	v_ashrrev_i32_e32 v17, 31, v16
	v_lshlrev_b64 v[16:17], 9, v[16:17]
	v_lshl_add_u64 v[80:81], v[66:67], 0, v[16:17]
	ds_bpermute_b32 v17, v118, v19
	v_cvt_pk_bf16_f32 v18, v18, s0
	v_or_b32_e32 v16, 35, v64
	global_store_short v[80:81], v18, off
	v_mul_lo_u32 v18, v16, 24
	v_or_b32_e32 v62, v18, v119
	s_and_saveexec_b64 s[2:3], s[6:7]
	s_cbranch_execz .LBB0_342
	v_ashrrev_i32_e32 v63, 31, v62
	v_lshl_add_u32 v32, v62, 2, v127
	ds_read_b32 v18, v32 offset:16
	s_nop 0
	ds_read_b32 v32, v32
	s_waitcnt lgkmcnt(0)
	v_mul_f32_e32 v17, v18, v17
	v_cndmask_b32_e64 v17, v17, -v17, vcc
	s_waitcnt lgkmcnt(0)
	v_fmac_f32_e32 v17, v19, v32
	v_mov_b32_e32 v19, v17
.LBB0_342:
	s_or_b64 exec, exec, s[2:3]
	s_waitcnt lgkmcnt(0)
	v_ashrrev_i32_e32 v17, 31, v16
	v_lshlrev_b64 v[16:17], 9, v[16:17]
	v_lshl_add_u64 v[76:77], v[66:67], 0, v[16:17]
	ds_bpermute_b32 v17, v118, v20
	v_cvt_pk_bf16_f32 v18, v19, s0
	v_or_b32_e32 v16, 40, v64
	global_store_short v[76:77], v18, off
	v_mul_lo_u32 v18, v16, 24
	v_or_b32_e32 v58, v18, v119
	s_and_saveexec_b64 s[2:3], s[6:7]
	s_cbranch_execz .LBB0_344
	v_ashrrev_i32_e32 v59, 31, v58
	v_lshl_add_u32 v18, v58, 2, v127
	ds_read_b32 v32, v18 offset:16
	s_nop 0
	ds_read_b32 v18, v18
	s_waitcnt lgkmcnt(0)
	v_mul_f32_e32 v17, v32, v17
	v_cndmask_b32_e64 v17, v17, -v17, vcc
	s_waitcnt lgkmcnt(0)
	v_fmac_f32_e32 v17, v20, v18
	v_mov_b32_e32 v20, v17
.LBB0_344:
	s_or_b64 exec, exec, s[2:3]
	s_waitcnt lgkmcnt(0)
	v_ashrrev_i32_e32 v17, 31, v16
	v_lshlrev_b64 v[16:17], 9, v[16:17]
	v_lshl_add_u64 v[72:73], v[66:67], 0, v[16:17]
	ds_bpermute_b32 v17, v118, v21
	v_cvt_pk_bf16_f32 v18, v20, s0
	v_or_b32_e32 v16, 41, v64
	global_store_short v[72:73], v18, off
	v_mul_lo_u32 v18, v16, 24
	v_or_b32_e32 v54, v18, v119
	s_and_saveexec_b64 s[2:3], s[6:7]
	s_cbranch_execz .LBB0_346
	v_ashrrev_i32_e32 v55, 31, v54
	v_lshl_add_u32 v18, v54, 2, v127
	ds_read_b32 v20, v18 offset:16
	s_nop 0
	ds_read_b32 v18, v18
	s_waitcnt lgkmcnt(0)
	v_mul_f32_e32 v17, v20, v17
	v_cndmask_b32_e64 v17, v17, -v17, vcc
	s_waitcnt lgkmcnt(0)
	v_fmac_f32_e32 v17, v21, v18
	v_mov_b32_e32 v21, v17
.LBB0_346:
	s_or_b64 exec, exec, s[2:3]
	s_waitcnt lgkmcnt(0)
	v_ashrrev_i32_e32 v17, 31, v16
	v_lshlrev_b64 v[16:17], 9, v[16:17]
	v_lshl_add_u64 v[68:69], v[66:67], 0, v[16:17]
	ds_bpermute_b32 v17, v118, v22
	v_cvt_pk_bf16_f32 v18, v21, s0
	v_or_b32_e32 v16, 42, v64
	global_store_short v[68:69], v18, off
	v_mul_lo_u32 v18, v16, 24
	v_or_b32_e32 v50, v18, v119
	s_and_saveexec_b64 s[2:3], s[6:7]
	s_cbranch_execz .LBB0_348
	v_ashrrev_i32_e32 v51, 31, v50
	v_lshl_add_u32 v18, v50, 2, v127
	ds_read_b32 v20, v18 offset:16
	s_nop 0
	ds_read_b32 v18, v18
	s_waitcnt lgkmcnt(0)
	v_mul_f32_e32 v17, v20, v17
	v_cndmask_b32_e64 v17, v17, -v17, vcc
	s_waitcnt lgkmcnt(0)
	v_fmac_f32_e32 v17, v22, v18
	v_mov_b32_e32 v22, v17
.LBB0_348:
	s_or_b64 exec, exec, s[2:3]
	s_waitcnt lgkmcnt(0)
	v_ashrrev_i32_e32 v17, 31, v16
	v_lshlrev_b64 v[16:17], 9, v[16:17]
	v_lshl_add_u64 v[60:61], v[66:67], 0, v[16:17]
	ds_bpermute_b32 v17, v118, v23
	v_cvt_pk_bf16_f32 v18, v22, s0
	v_or_b32_e32 v16, 43, v64
	global_store_short v[60:61], v18, off
	v_mul_lo_u32 v18, v16, 24
	v_or_b32_e32 v46, v18, v119
	s_and_saveexec_b64 s[2:3], s[6:7]
	s_cbranch_execz .LBB0_350
	v_ashrrev_i32_e32 v47, 31, v46
	v_lshl_add_u32 v18, v46, 2, v127
	ds_read_b32 v20, v18 offset:16
	s_nop 0
	ds_read_b32 v18, v18
	s_waitcnt lgkmcnt(0)
	v_mul_f32_e32 v17, v20, v17
	v_cndmask_b32_e64 v17, v17, -v17, vcc
	s_waitcnt lgkmcnt(0)
	v_fmac_f32_e32 v17, v23, v18
	v_mov_b32_e32 v23, v17
.LBB0_350:
	s_or_b64 exec, exec, s[2:3]
	s_waitcnt lgkmcnt(0)
	v_ashrrev_i32_e32 v17, 31, v16
	v_lshlrev_b64 v[16:17], 9, v[16:17]
	v_lshl_add_u64 v[56:57], v[66:67], 0, v[16:17]
	ds_bpermute_b32 v17, v118, v24
	v_cvt_pk_bf16_f32 v18, v23, s0
	v_or_b32_e32 v16, 48, v64
	global_store_short v[56:57], v18, off
	v_mul_lo_u32 v18, v16, 24
	v_or_b32_e32 v42, v18, v119
	s_and_saveexec_b64 s[2:3], s[6:7]
	s_cbranch_execz .LBB0_352
	v_ashrrev_i32_e32 v43, 31, v42
	v_lshl_add_u32 v18, v42, 2, v127
	ds_read_b32 v20, v18 offset:16
	s_nop 0
	ds_read_b32 v18, v18
	s_waitcnt lgkmcnt(0)
	v_mul_f32_e32 v17, v20, v17
	v_cndmask_b32_e64 v17, v17, -v17, vcc
	s_waitcnt lgkmcnt(0)
	v_fmac_f32_e32 v17, v24, v18
	v_mov_b32_e32 v24, v17
.LBB0_352:
	s_or_b64 exec, exec, s[2:3]
	s_waitcnt lgkmcnt(0)
	v_ashrrev_i32_e32 v17, 31, v16
	v_lshlrev_b64 v[16:17], 9, v[16:17]
	v_lshl_add_u64 v[52:53], v[66:67], 0, v[16:17]
	ds_bpermute_b32 v17, v118, v25
	v_cvt_pk_bf16_f32 v18, v24, s0
	v_or_b32_e32 v16, 49, v64
	global_store_short v[52:53], v18, off
	v_mul_lo_u32 v18, v16, 24
	v_or_b32_e32 v38, v18, v119
	s_and_saveexec_b64 s[2:3], s[6:7]
	s_cbranch_execz .LBB0_354
	v_ashrrev_i32_e32 v39, 31, v38
	v_lshl_add_u32 v18, v38, 2, v127
	ds_read_b32 v20, v18 offset:16
	s_nop 0
	ds_read_b32 v18, v18
	s_waitcnt lgkmcnt(0)
	v_mul_f32_e32 v17, v20, v17
	v_cndmask_b32_e64 v17, v17, -v17, vcc
	s_waitcnt lgkmcnt(0)
	v_fmac_f32_e32 v17, v25, v18
	v_mov_b32_e32 v25, v17
.LBB0_354:
	s_or_b64 exec, exec, s[2:3]
	s_waitcnt lgkmcnt(0)
	v_ashrrev_i32_e32 v17, 31, v16
	v_lshlrev_b64 v[16:17], 9, v[16:17]
	v_lshl_add_u64 v[48:49], v[66:67], 0, v[16:17]
	ds_bpermute_b32 v17, v118, v26
	v_cvt_pk_bf16_f32 v18, v25, s0
	v_or_b32_e32 v16, 50, v64
	global_store_short v[48:49], v18, off
	v_mul_lo_u32 v18, v16, 24
	v_or_b32_e32 v34, v18, v119
	s_and_saveexec_b64 s[2:3], s[6:7]
	s_cbranch_execz .LBB0_356
	v_ashrrev_i32_e32 v35, 31, v34
	v_lshl_add_u32 v18, v34, 2, v127
	ds_read_b32 v20, v18 offset:16
	s_nop 0
	ds_read_b32 v18, v18
	s_waitcnt lgkmcnt(0)
	v_mul_f32_e32 v17, v20, v17
	v_cndmask_b32_e64 v17, v17, -v17, vcc
	s_waitcnt lgkmcnt(0)
	v_fmac_f32_e32 v17, v26, v18
	v_mov_b32_e32 v26, v17
.LBB0_356:
	s_or_b64 exec, exec, s[2:3]
	s_waitcnt lgkmcnt(0)
	v_ashrrev_i32_e32 v17, 31, v16
	v_lshlrev_b64 v[16:17], 9, v[16:17]
	v_lshl_add_u64 v[44:45], v[66:67], 0, v[16:17]
	ds_bpermute_b32 v17, v118, v27
	v_cvt_pk_bf16_f32 v18, v26, s0
	v_or_b32_e32 v16, 51, v64
	global_store_short v[44:45], v18, off
	v_mul_lo_u32 v18, v16, 24
	v_or_b32_e32 v32, v18, v119
	s_and_saveexec_b64 s[2:3], s[6:7]
	s_cbranch_execz .LBB0_358
	v_ashrrev_i32_e32 v33, 31, v32
	v_lshl_add_u32 v18, v32, 2, v127
	ds_read_b32 v20, v18 offset:16
	s_nop 0
	ds_read_b32 v18, v18
	s_waitcnt lgkmcnt(0)
	v_mul_f32_e32 v17, v20, v17
	v_cndmask_b32_e64 v17, v17, -v17, vcc
	s_waitcnt lgkmcnt(0)
	v_fmac_f32_e32 v17, v27, v18
	v_mov_b32_e32 v27, v17
.LBB0_358:
	s_or_b64 exec, exec, s[2:3]
	s_waitcnt lgkmcnt(0)
	v_ashrrev_i32_e32 v17, 31, v16
	v_lshlrev_b64 v[16:17], 9, v[16:17]
	v_lshl_add_u64 v[40:41], v[66:67], 0, v[16:17]
	ds_bpermute_b32 v17, v118, v28
	v_cvt_pk_bf16_f32 v18, v27, s0
	v_or_b32_e32 v16, 56, v64
	global_store_short v[40:41], v18, off
	v_mul_lo_u32 v18, v16, 24
	v_or_b32_e32 v24, v18, v119
	s_and_saveexec_b64 s[2:3], s[6:7]
	s_cbranch_execz .LBB0_360
	v_ashrrev_i32_e32 v25, 31, v24
	v_lshl_add_u32 v18, v24, 2, v127
	ds_read_b32 v20, v18 offset:16
	s_nop 0
	ds_read_b32 v18, v18
	s_waitcnt lgkmcnt(0)
	v_mul_f32_e32 v17, v20, v17
	v_cndmask_b32_e64 v17, v17, -v17, vcc
	s_waitcnt lgkmcnt(0)
	v_fmac_f32_e32 v17, v28, v18
	v_mov_b32_e32 v28, v17
.LBB0_360:
	s_or_b64 exec, exec, s[2:3]
	s_waitcnt lgkmcnt(0)
	v_ashrrev_i32_e32 v17, 31, v16
	v_lshlrev_b64 v[16:17], 9, v[16:17]
	v_lshl_add_u64 v[36:37], v[66:67], 0, v[16:17]
	ds_bpermute_b32 v17, v118, v29
	v_cvt_pk_bf16_f32 v18, v28, s0
	v_or_b32_e32 v16, 57, v64
	global_store_short v[36:37], v18, off
	v_mul_lo_u32 v18, v16, 24
	v_or_b32_e32 v18, v18, v119
	s_and_saveexec_b64 s[2:3], s[6:7]
	s_cbranch_execz .LBB0_362
	v_ashrrev_i32_e32 v19, 31, v18
	v_lshl_add_u32 v20, v18, 2, v127
	ds_read_b32 v19, v20 offset:16
	s_nop 0
	ds_read_b32 v20, v20
	s_waitcnt lgkmcnt(0)
	v_mul_f32_e32 v17, v19, v17
	v_cndmask_b32_e64 v17, v17, -v17, vcc
	s_waitcnt lgkmcnt(0)
	v_fmac_f32_e32 v17, v29, v20
	v_mov_b32_e32 v29, v17
.LBB0_362:
	s_or_b64 exec, exec, s[2:3]
	s_waitcnt lgkmcnt(0)
	v_ashrrev_i32_e32 v17, 31, v16
	v_lshlrev_b64 v[16:17], 9, v[16:17]
	ds_bpermute_b32 v19, v118, v30
	v_cvt_pk_bf16_f32 v20, v29, s0
	v_lshl_add_u64 v[28:29], v[66:67], 0, v[16:17]
	global_store_short v[28:29], v20, off
	v_or_b32_e32 v20, 58, v64
	v_mul_lo_u32 v16, v20, 24
	v_or_b32_e32 v16, v16, v119
	s_and_saveexec_b64 s[2:3], s[6:7]
	s_cbranch_execz .LBB0_364
	v_ashrrev_i32_e32 v17, 31, v16
	v_lshl_add_u32 v22, v16, 2, v127
	ds_read_b32 v17, v22 offset:16
	ds_read_b32 v21, v22
	s_waitcnt lgkmcnt(0)
	v_mul_f32_e32 v17, v17, v19
	v_cndmask_b32_e64 v17, v17, -v17, vcc
	s_waitcnt lgkmcnt(0)
	v_fmac_f32_e32 v17, v30, v21
	v_mov_b32_e32 v30, v17
.LBB0_364:
	s_or_b64 exec, exec, s[2:3]
	v_ashrrev_i32_e32 v21, 31, v20
	ds_bpermute_b32 v17, v118, v31
	v_lshlrev_b64 v[20:21], 9, v[20:21]
	s_waitcnt lgkmcnt(1)
	v_cvt_pk_bf16_f32 v19, v30, s0
	v_lshl_add_u64 v[22:23], v[66:67], 0, v[20:21]
	v_or_b32_e32 v26, 59, v64
	global_store_short v[22:23], v19, off
	v_mul_lo_u32 v19, v26, 24
	v_or_b32_e32 v20, v19, v119
	s_and_saveexec_b64 s[2:3], s[6:7]
	s_cbranch_execz .LBB0_366
	v_ashrrev_i32_e32 v21, 31, v20
	v_lshl_add_u32 v64, v20, 2, v127
	ds_read_b32 v19, v64 offset:16
	ds_read_b32 v21, v64
	s_waitcnt lgkmcnt(0)
	v_mul_f32_e32 v17, v19, v17
	v_cndmask_b32_e64 v17, v17, -v17, vcc
	s_waitcnt lgkmcnt(0)
	v_fmac_f32_e32 v17, v31, v21
	v_mov_b32_e32 v31, v17
.LBB0_366:
	s_or_b64 exec, exec, s[2:3]
	v_ashrrev_i32_e32 v27, 31, v26
	v_lshlrev_b64 v[26:27], 9, v[26:27]
	s_waitcnt lgkmcnt(0)
	v_cvt_pk_bf16_f32 v17, v31, s0
	v_lshl_add_u64 v[26:27], v[66:67], 0, v[26:27]
	global_store_short v[26:27], v17, off
	ds_bpermute_b32 v17, v118, v0
	s_and_saveexec_b64 s[2:3], s[6:7]
	s_cbranch_execz .LBB0_368
	v_ashrrev_i32_e32 v79, 31, v78
	v_lshl_add_u32 v30, v78, 2, v127
	ds_read_b32 v19, v30 offset:16
	ds_read_b32 v21, v30
	s_waitcnt lgkmcnt(0)
	v_mul_f32_e32 v17, v19, v17
	v_cndmask_b32_e64 v17, v17, -v17, vcc
	s_waitcnt lgkmcnt(0)
	v_fmac_f32_e32 v17, v0, v21
	v_mov_b32_e32 v0, v17
.LBB0_368:
	s_or_b64 exec, exec, s[2:3]
	v_cvt_pk_bf16_f32 v0, v0, s0
	global_store_short v[84:85], v0, off offset:64
	ds_bpermute_b32 v0, v118, v1
	s_and_saveexec_b64 s[2:3], s[6:7]
	s_cbranch_execz .LBB0_370
	v_ashrrev_i32_e32 v75, 31, v74
	v_lshl_add_u32 v30, v74, 2, v127
	s_waitcnt lgkmcnt(1)
	ds_read_b32 v17, v30 offset:16
	ds_read_b32 v19, v30
	s_waitcnt lgkmcnt(0)
	v_mul_f32_e32 v0, v17, v0
	v_cndmask_b32_e64 v0, v0, -v0, vcc
	s_waitcnt lgkmcnt(0)
	v_fmac_f32_e32 v0, v1, v19
	v_mov_b32_e32 v1, v0
.LBB0_370:
	s_or_b64 exec, exec, s[2:3]
	s_waitcnt lgkmcnt(0)
	v_cvt_pk_bf16_f32 v0, v1, s0
	global_store_short v[82:83], v0, off offset:64
	ds_bpermute_b32 v0, v118, v2
	s_and_saveexec_b64 s[2:3], s[6:7]
	s_cbranch_execz .LBB0_372
	v_ashrrev_i32_e32 v71, 31, v70
	v_lshl_add_u32 v30, v70, 2, v127
	ds_read_b32 v1, v30 offset:16
	ds_read_b32 v17, v30
	s_waitcnt lgkmcnt(0)
	v_mul_f32_e32 v0, v1, v0
	v_cndmask_b32_e64 v0, v0, -v0, vcc
	s_waitcnt lgkmcnt(0)
	v_fmac_f32_e32 v0, v2, v17
	v_mov_b32_e32 v2, v0
.LBB0_372:
	s_or_b64 exec, exec, s[2:3]
	s_waitcnt lgkmcnt(0)
	v_cvt_pk_bf16_f32 v0, v2, s0
	global_store_short v[80:81], v0, off offset:64
	ds_bpermute_b32 v0, v118, v3
	s_and_saveexec_b64 s[2:3], s[6:7]
	s_cbranch_execz .LBB0_374
	v_ashrrev_i32_e32 v63, 31, v62
	v_lshl_add_u32 v30, v62, 2, v127
	ds_read_b32 v1, v30 offset:16
	ds_read_b32 v2, v30
	s_waitcnt lgkmcnt(0)
	v_mul_f32_e32 v0, v1, v0
	v_cndmask_b32_e64 v0, v0, -v0, vcc
	s_waitcnt lgkmcnt(0)
	v_fmac_f32_e32 v0, v3, v2
	v_mov_b32_e32 v3, v0
.LBB0_374:
	s_or_b64 exec, exec, s[2:3]
	s_waitcnt lgkmcnt(0)
	v_cvt_pk_bf16_f32 v0, v3, s0
	global_store_short v[76:77], v0, off offset:64
	ds_bpermute_b32 v0, v118, v4
	s_and_saveexec_b64 s[2:3], s[6:7]
	s_cbranch_execz .LBB0_376
	v_ashrrev_i32_e32 v59, 31, v58
	v_lshl_add_u32 v2, v58, 2, v127
	ds_read_b32 v1, v2 offset:16
	s_nop 0
	ds_read_b32 v2, v2
	s_waitcnt lgkmcnt(0)
	v_mul_f32_e32 v0, v1, v0
	v_cndmask_b32_e64 v0, v0, -v0, vcc
	s_waitcnt lgkmcnt(0)
	v_fmac_f32_e32 v0, v4, v2
	v_mov_b32_e32 v4, v0
.LBB0_376:
	s_or_b64 exec, exec, s[2:3]
	s_waitcnt lgkmcnt(0)
	v_cvt_pk_bf16_f32 v0, v4, s0
	global_store_short v[72:73], v0, off offset:64
	ds_bpermute_b32 v0, v118, v5
	s_and_saveexec_b64 s[2:3], s[6:7]
	s_cbranch_execz .LBB0_378
	v_ashrrev_i32_e32 v55, 31, v54
	v_lshl_add_u32 v2, v54, 2, v127
	ds_read_b32 v1, v2 offset:16
	s_nop 0
	ds_read_b32 v2, v2
	s_waitcnt lgkmcnt(0)
	v_mul_f32_e32 v0, v1, v0
	v_cndmask_b32_e64 v0, v0, -v0, vcc
	s_waitcnt lgkmcnt(0)
	v_fmac_f32_e32 v0, v5, v2
	v_mov_b32_e32 v5, v0
.LBB0_378:
	s_or_b64 exec, exec, s[2:3]
	s_waitcnt lgkmcnt(0)
	v_cvt_pk_bf16_f32 v0, v5, s0
	global_store_short v[68:69], v0, off offset:64
	ds_bpermute_b32 v0, v118, v6
	s_and_saveexec_b64 s[2:3], s[6:7]
	s_cbranch_execz .LBB0_380
	v_ashrrev_i32_e32 v51, 31, v50
	v_lshl_add_u32 v2, v50, 2, v127
	ds_read_b32 v1, v2 offset:16
	s_nop 0
	ds_read_b32 v2, v2
	s_waitcnt lgkmcnt(0)
	v_mul_f32_e32 v0, v1, v0
	v_cndmask_b32_e64 v0, v0, -v0, vcc
	s_waitcnt lgkmcnt(0)
	v_fmac_f32_e32 v0, v6, v2
	v_mov_b32_e32 v6, v0
.LBB0_380:
	s_or_b64 exec, exec, s[2:3]
	s_waitcnt lgkmcnt(0)
	v_cvt_pk_bf16_f32 v0, v6, s0
	global_store_short v[60:61], v0, off offset:64
	ds_bpermute_b32 v0, v118, v7
	s_and_saveexec_b64 s[2:3], s[6:7]
	s_cbranch_execz .LBB0_382
	v_ashrrev_i32_e32 v47, 31, v46
	v_lshl_add_u32 v2, v46, 2, v127
	ds_read_b32 v1, v2 offset:16
	s_nop 0
	ds_read_b32 v2, v2
	s_waitcnt lgkmcnt(0)
	v_mul_f32_e32 v0, v1, v0
	v_cndmask_b32_e64 v0, v0, -v0, vcc
	s_waitcnt lgkmcnt(0)
	v_fmac_f32_e32 v0, v7, v2
	v_mov_b32_e32 v7, v0
.LBB0_382:
	s_or_b64 exec, exec, s[2:3]
	s_waitcnt lgkmcnt(0)
	v_cvt_pk_bf16_f32 v0, v7, s0
	global_store_short v[56:57], v0, off offset:64
	ds_bpermute_b32 v0, v118, v8
	s_and_saveexec_b64 s[2:3], s[6:7]
	s_cbranch_execz .LBB0_384
	v_ashrrev_i32_e32 v43, 31, v42
	v_lshl_add_u32 v2, v42, 2, v127
	ds_read_b32 v1, v2 offset:16
	s_nop 0
	ds_read_b32 v2, v2
	s_waitcnt lgkmcnt(0)
	v_mul_f32_e32 v0, v1, v0
	v_cndmask_b32_e64 v0, v0, -v0, vcc
	s_waitcnt lgkmcnt(0)
	v_fmac_f32_e32 v0, v8, v2
	v_mov_b32_e32 v8, v0
.LBB0_384:
	s_or_b64 exec, exec, s[2:3]
	s_waitcnt lgkmcnt(0)
	v_cvt_pk_bf16_f32 v0, v8, s0
	global_store_short v[52:53], v0, off offset:64
	ds_bpermute_b32 v0, v118, v9
	s_and_saveexec_b64 s[2:3], s[6:7]
	s_cbranch_execz .LBB0_386
	v_ashrrev_i32_e32 v39, 31, v38
	v_lshl_add_u32 v2, v38, 2, v127
	ds_read_b32 v1, v2 offset:16
	s_nop 0
	ds_read_b32 v2, v2
	s_waitcnt lgkmcnt(0)
	v_mul_f32_e32 v0, v1, v0
	v_cndmask_b32_e64 v0, v0, -v0, vcc
	s_waitcnt lgkmcnt(0)
	v_fmac_f32_e32 v0, v9, v2
	v_mov_b32_e32 v9, v0
.LBB0_386:
	s_or_b64 exec, exec, s[2:3]
	s_waitcnt lgkmcnt(0)
	v_cvt_pk_bf16_f32 v0, v9, s0
	global_store_short v[48:49], v0, off offset:64
	ds_bpermute_b32 v0, v118, v10
	s_and_saveexec_b64 s[2:3], s[6:7]
	s_cbranch_execz .LBB0_388
	v_ashrrev_i32_e32 v35, 31, v34
	v_lshl_add_u32 v2, v34, 2, v127
	ds_read_b32 v1, v2 offset:16
	s_nop 0
	ds_read_b32 v2, v2
	s_waitcnt lgkmcnt(0)
	v_mul_f32_e32 v0, v1, v0
	v_cndmask_b32_e64 v0, v0, -v0, vcc
	s_waitcnt lgkmcnt(0)
	v_fmac_f32_e32 v0, v10, v2
	v_mov_b32_e32 v10, v0
.LBB0_388:
	s_or_b64 exec, exec, s[2:3]
	s_waitcnt lgkmcnt(0)
	v_cvt_pk_bf16_f32 v0, v10, s0
	global_store_short v[44:45], v0, off offset:64
	ds_bpermute_b32 v0, v118, v11
	s_and_saveexec_b64 s[2:3], s[6:7]
	s_cbranch_execz .LBB0_390
	v_ashrrev_i32_e32 v33, 31, v32
	v_lshl_add_u32 v2, v32, 2, v127
	ds_read_b32 v1, v2 offset:16
	s_nop 0
	ds_read_b32 v2, v2
	s_waitcnt lgkmcnt(0)
	v_mul_f32_e32 v0, v1, v0
	v_cndmask_b32_e64 v0, v0, -v0, vcc
	s_waitcnt lgkmcnt(0)
	v_fmac_f32_e32 v0, v11, v2
	v_mov_b32_e32 v11, v0
.LBB0_390:
	s_or_b64 exec, exec, s[2:3]
	s_waitcnt lgkmcnt(0)
	v_cvt_pk_bf16_f32 v0, v11, s0
	global_store_short v[40:41], v0, off offset:64
	ds_bpermute_b32 v0, v118, v12
	s_and_saveexec_b64 s[2:3], s[6:7]
	s_cbranch_execz .LBB0_392
	v_ashrrev_i32_e32 v25, 31, v24
	v_lshl_add_u32 v2, v24, 2, v127
	ds_read_b32 v1, v2 offset:16
	s_nop 0
	ds_read_b32 v2, v2
	s_waitcnt lgkmcnt(0)
	v_mul_f32_e32 v0, v1, v0
	v_cndmask_b32_e64 v0, v0, -v0, vcc
	s_waitcnt lgkmcnt(0)
	v_fmac_f32_e32 v0, v12, v2
	v_mov_b32_e32 v12, v0
.LBB0_392:
	s_or_b64 exec, exec, s[2:3]
	s_waitcnt lgkmcnt(0)
	v_cvt_pk_bf16_f32 v0, v12, s0
	global_store_short v[36:37], v0, off offset:64
	ds_bpermute_b32 v0, v118, v13
	s_and_saveexec_b64 s[2:3], s[6:7]
	s_cbranch_execz .LBB0_394
	v_ashrrev_i32_e32 v19, 31, v18
	v_lshl_add_u32 v2, v18, 2, v127
	ds_read_b32 v1, v2 offset:16
	s_nop 0
	ds_read_b32 v2, v2
	s_waitcnt lgkmcnt(0)
	v_mul_f32_e32 v0, v1, v0
	v_cndmask_b32_e64 v0, v0, -v0, vcc
	s_waitcnt lgkmcnt(0)
	v_fmac_f32_e32 v0, v13, v2
	v_mov_b32_e32 v13, v0
.LBB0_394:
	s_or_b64 exec, exec, s[2:3]
	s_waitcnt lgkmcnt(0)
	v_cvt_pk_bf16_f32 v0, v13, s0
	global_store_short v[28:29], v0, off offset:64
	ds_bpermute_b32 v0, v118, v14
	s_and_saveexec_b64 s[2:3], s[6:7]
	s_cbranch_execz .LBB0_396
	v_ashrrev_i32_e32 v17, 31, v16
	v_lshl_add_u32 v2, v16, 2, v127
	ds_read_b32 v1, v2 offset:16
	s_nop 0
	ds_read_b32 v2, v2
	s_waitcnt lgkmcnt(0)
	v_mul_f32_e32 v0, v1, v0
	v_cndmask_b32_e64 v0, v0, -v0, vcc
	s_waitcnt lgkmcnt(0)
	v_fmac_f32_e32 v0, v14, v2
	v_mov_b32_e32 v14, v0
.LBB0_396:
	s_or_b64 exec, exec, s[2:3]
	s_waitcnt lgkmcnt(0)
	ds_bpermute_b32 v0, v118, v15
	v_cvt_pk_bf16_f32 v1, v14, s0
	global_store_short v[22:23], v1, off offset:64
	s_and_saveexec_b64 s[2:3], s[6:7]
	s_cbranch_execz .LBB0_398
	v_ashrrev_i32_e32 v21, 31, v20
	v_lshl_add_u32 v2, v20, 2, v127
	ds_read_b32 v1, v2 offset:16
	s_nop 0
	ds_read_b32 v2, v2
	s_waitcnt lgkmcnt(0)
	v_mul_f32_e32 v0, v1, v0
	v_cndmask_b32_e64 v0, v0, -v0, vcc
	s_waitcnt lgkmcnt(0)
	v_fmac_f32_e32 v0, v15, v2
	v_mov_b32_e32 v15, v0

.LBB0_635:
	v_lshrrev_b32_e32 v65, 3, v131
	v_and_b32_e32 v64, 64, v131
	v_and_b32_e32 v65, 4, v65
	v_or3_b32 v74, v64, v65, s17
	v_lshlrev_b64 v[78:79], 10, v[72:73]
	v_ashrrev_i32_e32 v75, 31, v74
	v_lshl_add_u64 v[82:83], v[78:79], 0, v[74:75]
	v_lshl_add_u64 v[80:81], v[82:83], 2, v[128:129]
	global_load_dwordx4 v[64:67], v[80:81], off
	global_load_dwordx4 v[92:95], v[80:81], off offset:32
	global_load_dwordx4 v[96:99], v[80:81], off offset:64
	global_load_dwordx4 v[100:103], v[80:81], off offset:96
	global_load_dwordx4 v[104:107], v[80:81], off offset:128
	global_load_dwordx4 v[108:111], v[80:81], off offset:160
	global_load_dwordx4 v[112:115], v[80:81], off offset:192
	global_load_dwordx4 v[116:119], v[80:81], off offset:224
	v_readlane_b32 s20, v254, 45
	v_lshlrev_b64 v[68:69], 2, v[74:75]
	v_readlane_b32 s21, v254, 46
	v_readlane_b32 s22, v254, 47
	v_readlane_b32 s23, v254, 48
	s_and_b64 vcc, exec, s[4:5]
	v_lshl_add_u64 v[70:71], s[20:21], 0, v[68:69]
	v_lshl_add_u64 v[68:69], s[22:23], 0, v[68:69]
	v_readlane_b32 s24, v254, 49
	v_readlane_b32 s25, v254, 50
	v_readlane_b32 s26, v254, 51
	v_readlane_b32 s27, v254, 52
	s_cbranch_vccnz .LBB0_637
	global_load_dwordx4 v[84:87], v[70:71], off
	global_load_dwordx4 v[120:123], v[70:71], off offset:0
	global_load_dwordx4 v[124:127], v[70:71], off offset:32
	global_load_dwordx4 v[146:149], v[70:71], off offset:64
	global_load_dwordx4 v[150:153], v[70:71], off offset:96
	global_load_dwordx4 v[154:157], v[70:71], off offset:128
	global_load_dwordx4 v[158:161], v[70:71], off offset:160
	global_load_dwordx4 v[162:165], v[70:71], off offset:192
	global_load_dwordx4 v[166:169], v[70:71], off offset:224
	global_load_dwordx4 v[88:91], v[68:69], off
	global_load_dwordx4 v[170:173], v[68:69], off offset:0
	global_load_dwordx4 v[190:193], v[68:69], off offset:32
	global_load_dwordx4 v[194:197], v[68:69], off offset:64
	global_load_dwordx4 v[198:201], v[68:69], off offset:96
	global_load_dwordx4 v[202:205], v[68:69], off offset:128
	global_load_dwordx4 v[206:209], v[68:69], off offset:160
	global_load_dwordx4 v[210:213], v[68:69], off offset:192
	global_load_dwordx4 v[236:239], v[68:69], off offset:224
	s_waitcnt vmcnt(0)
	v_pk_add_f32 v[64:65], v[64:65], v[76:77] op_sel_hi:[1,0] neg_lo:[0,1] neg_hi:[0,1]
	v_pk_add_f32 v[66:67], v[66:67], v[76:77] op_sel_hi:[1,0] neg_lo:[0,1] neg_hi:[0,1]
	v_pk_mul_f32 v[64:65], v[76:77], v[64:65] op_sel:[1,0]
	v_pk_mul_f32 v[66:67], v[76:77], v[66:67] op_sel:[1,0]
	s_waitcnt vmcnt(0)
	v_pk_fma_f32 v[64:65], v[64:65], v[84:85], v[88:89]
	v_pk_fma_f32 v[66:67], v[66:67], v[86:87], v[90:91]
.LBB0_637:
	v_lshl_add_u64 v[82:83], v[82:83], 2, s[0:1]
	s_waitcnt vmcnt(0)
	v_pk_fma_f32 v[48:49], v[64:65], s[84:85], v[48:49] op_sel_hi:[1,0,1]
	v_pk_fma_f32 v[50:51], v[66:67], s[84:85], v[50:51] op_sel_hi:[1,0,1]
	global_store_dwordx4 v[82:83], v[48:51], off
	s_nop 1
	v_mov_b64_e32 v[48:49], v[92:93]
	v_mov_b64_e32 v[50:51], v[94:95]
	s_and_b64 vcc, exec, s[4:5]
	s_cbranch_vccnz .LBB0_639
	v_mov_b64_e32 v[64:65], v[124:125]
	v_mov_b64_e32 v[66:67], v[126:127]
	v_mov_b64_e32 v[82:83], v[190:191]
	v_mov_b64_e32 v[84:85], v[192:193]
	v_pk_add_f32 v[48:49], v[48:49], v[76:77] op_sel_hi:[1,0] neg_lo:[0,1] neg_hi:[0,1]
	v_pk_add_f32 v[50:51], v[50:51], v[76:77] op_sel_hi:[1,0] neg_lo:[0,1] neg_hi:[0,1]
	v_pk_mul_f32 v[48:49], v[76:77], v[48:49] op_sel:[1,0]
	v_pk_mul_f32 v[50:51], v[76:77], v[50:51] op_sel:[1,0]
	v_pk_fma_f32 v[48:49], v[48:49], v[64:65], v[82:83]
	v_pk_fma_f32 v[50:51], v[50:51], v[66:67], v[84:85]
.LBB0_639:
	v_or_b32_e32 v64, 8, v74
	v_ashrrev_i32_e32 v65, 31, v64
	v_lshl_add_u64 v[66:67], v[78:79], 0, v[64:65]
	v_lshl_add_u64 v[66:67], v[66:67], 2, s[0:1]
	v_pk_fma_f32 v[48:49], v[48:49], s[84:85], v[52:53] op_sel_hi:[1,0,1]
	v_pk_fma_f32 v[50:51], v[50:51], s[84:85], v[54:55] op_sel_hi:[1,0,1]
	global_store_dwordx4 v[66:67], v[48:51], off
	s_nop 1
	v_mov_b64_e32 v[48:49], v[96:97]
	v_mov_b64_e32 v[50:51], v[98:99]
	s_and_b64 vcc, exec, s[4:5]
	s_cbranch_vccnz .LBB0_641
	v_mov_b64_e32 v[52:53], v[146:147]
	v_mov_b64_e32 v[54:55], v[148:149]
	v_mov_b64_e32 v[82:83], v[194:195]
	v_mov_b64_e32 v[84:85], v[196:197]
	v_pk_add_f32 v[48:49], v[48:49], v[76:77] op_sel_hi:[1,0] neg_lo:[0,1] neg_hi:[0,1]
	v_pk_add_f32 v[50:51], v[50:51], v[76:77] op_sel_hi:[1,0] neg_lo:[0,1] neg_hi:[0,1]
	v_pk_mul_f32 v[48:49], v[76:77], v[48:49] op_sel:[1,0]
	v_pk_mul_f32 v[50:51], v[76:77], v[50:51] op_sel:[1,0]
	v_pk_fma_f32 v[48:49], v[48:49], v[52:53], v[82:83]
	v_pk_fma_f32 v[50:51], v[50:51], v[54:55], v[84:85]
.LBB0_641:
	v_or_b32_e32 v52, 16, v74
	v_ashrrev_i32_e32 v53, 31, v52
	v_lshl_add_u64 v[54:55], v[78:79], 0, v[52:53]
	v_lshl_add_u64 v[54:55], v[54:55], 2, s[0:1]
	v_pk_fma_f32 v[48:49], v[48:49], s[84:85], v[56:57] op_sel_hi:[1,0,1]
	v_pk_fma_f32 v[50:51], v[50:51], s[84:85], v[58:59] op_sel_hi:[1,0,1]
	global_store_dwordx4 v[54:55], v[48:51], off
	s_nop 1
	v_mov_b64_e32 v[48:49], v[100:101]
	v_mov_b64_e32 v[50:51], v[102:103]
	s_and_b64 vcc, exec, s[4:5]
	s_cbranch_vccnz .LBB0_643
	v_mov_b64_e32 v[54:55], v[150:151]
	v_mov_b64_e32 v[56:57], v[152:153]
	v_mov_b64_e32 v[82:83], v[198:199]
	v_mov_b64_e32 v[84:85], v[200:201]
	v_pk_add_f32 v[48:49], v[48:49], v[76:77] op_sel_hi:[1,0] neg_lo:[0,1] neg_hi:[0,1]
	v_pk_add_f32 v[50:51], v[50:51], v[76:77] op_sel_hi:[1,0] neg_lo:[0,1] neg_hi:[0,1]
	v_pk_mul_f32 v[48:49], v[76:77], v[48:49] op_sel:[1,0]
	v_pk_mul_f32 v[50:51], v[76:77], v[50:51] op_sel:[1,0]
	v_pk_fma_f32 v[48:49], v[48:49], v[54:55], v[82:83]
	v_pk_fma_f32 v[50:51], v[50:51], v[56:57], v[84:85]
.LBB0_643:
	v_or_b32_e32 v54, 24, v74
	v_ashrrev_i32_e32 v55, 31, v54
	v_lshl_add_u64 v[56:57], v[78:79], 0, v[54:55]
	v_lshl_add_u64 v[56:57], v[56:57], 2, s[0:1]
	v_pk_fma_f32 v[48:49], v[48:49], s[84:85], v[60:61] op_sel_hi:[1,0,1]
	v_pk_fma_f32 v[50:51], v[50:51], s[84:85], v[62:63] op_sel_hi:[1,0,1]
	global_store_dwordx4 v[56:57], v[48:51], off
	s_nop 1
	v_mov_b64_e32 v[48:49], v[104:105]
	v_mov_b64_e32 v[50:51], v[106:107]
	s_and_b64 vcc, exec, s[4:5]
	s_cbranch_vccnz .LBB0_645
	v_mov_b64_e32 v[56:57], v[154:155]
	v_mov_b64_e32 v[58:59], v[156:157]
	v_mov_b64_e32 v[60:61], v[202:203]
	v_mov_b64_e32 v[62:63], v[204:205]
	v_pk_add_f32 v[48:49], v[48:49], v[76:77] op_sel_hi:[1,0] neg_lo:[0,1] neg_hi:[0,1]
	v_pk_add_f32 v[50:51], v[50:51], v[76:77] op_sel_hi:[1,0] neg_lo:[0,1] neg_hi:[0,1]
	v_pk_mul_f32 v[48:49], v[76:77], v[48:49] op_sel:[1,0]
	v_pk_mul_f32 v[50:51], v[76:77], v[50:51] op_sel:[1,0]
	v_pk_fma_f32 v[48:49], v[48:49], v[56:57], v[60:61]
	v_pk_fma_f32 v[50:51], v[50:51], v[58:59], v[62:63]
.LBB0_645:
	v_or_b32_e32 v56, 32, v74
	v_ashrrev_i32_e32 v57, 31, v56
	v_lshl_add_u64 v[58:59], v[78:79], 0, v[56:57]
	v_lshl_add_u64 v[58:59], v[58:59], 2, s[0:1]
	v_pk_fma_f32 v[32:33], v[48:49], s[84:85], v[32:33] op_sel_hi:[1,0,1]
	v_pk_fma_f32 v[34:35], v[50:51], s[84:85], v[34:35] op_sel_hi:[1,0,1]
	global_store_dwordx4 v[58:59], v[32:35], off
	s_nop 1
	v_mov_b64_e32 v[32:33], v[108:109]
	v_mov_b64_e32 v[34:35], v[110:111]
	s_and_b64 vcc, exec, s[4:5]
	s_cbranch_vccnz .LBB0_647
	v_mov_b64_e32 v[48:49], v[158:159]
	v_mov_b64_e32 v[50:51], v[160:161]
	v_mov_b64_e32 v[58:59], v[206:207]
	v_mov_b64_e32 v[60:61], v[208:209]
	v_pk_add_f32 v[32:33], v[32:33], v[76:77] op_sel_hi:[1,0] neg_lo:[0,1] neg_hi:[0,1]
	v_pk_add_f32 v[34:35], v[34:35], v[76:77] op_sel_hi:[1,0] neg_lo:[0,1] neg_hi:[0,1]
	v_pk_mul_f32 v[32:33], v[76:77], v[32:33] op_sel:[1,0]
	v_pk_mul_f32 v[34:35], v[76:77], v[34:35] op_sel:[1,0]
	v_pk_fma_f32 v[32:33], v[32:33], v[48:49], v[58:59]
	v_pk_fma_f32 v[34:35], v[34:35], v[50:51], v[60:61]
.LBB0_647:
	v_or_b32_e32 v48, 40, v74
	v_ashrrev_i32_e32 v49, 31, v48
	v_lshl_add_u64 v[50:51], v[78:79], 0, v[48:49]
	v_lshl_add_u64 v[50:51], v[50:51], 2, s[0:1]
	v_pk_fma_f32 v[32:33], v[32:33], s[84:85], v[36:37] op_sel_hi:[1,0,1]
	v_pk_fma_f32 v[34:35], v[34:35], s[84:85], v[38:39] op_sel_hi:[1,0,1]
	global_store_dwordx4 v[50:51], v[32:35], off
	s_nop 1
	v_mov_b64_e32 v[32:33], v[112:113]
	v_mov_b64_e32 v[34:35], v[114:115]
	s_and_b64 vcc, exec, s[4:5]
	s_cbranch_vccnz .LBB0_649
	v_mov_b64_e32 v[36:37], v[162:163]
	v_mov_b64_e32 v[38:39], v[164:165]
	v_mov_b64_e32 v[58:59], v[210:211]
	v_mov_b64_e32 v[60:61], v[212:213]
	v_pk_add_f32 v[32:33], v[32:33], v[76:77] op_sel_hi:[1,0] neg_lo:[0,1] neg_hi:[0,1]
	v_pk_add_f32 v[34:35], v[34:35], v[76:77] op_sel_hi:[1,0] neg_lo:[0,1] neg_hi:[0,1]
	v_pk_mul_f32 v[32:33], v[76:77], v[32:33] op_sel:[1,0]
	v_pk_mul_f32 v[34:35], v[76:77], v[34:35] op_sel:[1,0]
	v_pk_fma_f32 v[32:33], v[32:33], v[36:37], v[58:59]
	v_pk_fma_f32 v[34:35], v[34:35], v[38:39], v[60:61]
.LBB0_649:
	v_or_b32_e32 v36, 48, v74
	v_ashrrev_i32_e32 v37, 31, v36
	v_lshl_add_u64 v[38:39], v[78:79], 0, v[36:37]
	v_lshl_add_u64 v[38:39], v[38:39], 2, s[0:1]
	v_pk_fma_f32 v[32:33], v[32:33], s[84:85], v[40:41] op_sel_hi:[1,0,1]
	v_pk_fma_f32 v[34:35], v[34:35], s[84:85], v[42:43] op_sel_hi:[1,0,1]
	global_store_dwordx4 v[38:39], v[32:35], off
	s_nop 1
	v_mov_b64_e32 v[32:33], v[116:117]
	v_mov_b64_e32 v[34:35], v[118:119]
	s_and_b64 vcc, exec, s[4:5]
	s_cbranch_vccnz .LBB0_651
	v_mov_b64_e32 v[38:39], v[166:167]
	v_mov_b64_e32 v[40:41], v[168:169]
	v_mov_b64_e32 v[58:59], v[236:237]
	v_mov_b64_e32 v[60:61], v[238:239]
	v_pk_add_f32 v[32:33], v[32:33], v[76:77] op_sel_hi:[1,0] neg_lo:[0,1] neg_hi:[0,1]
	v_pk_add_f32 v[34:35], v[34:35], v[76:77] op_sel_hi:[1,0] neg_lo:[0,1] neg_hi:[0,1]
	v_pk_mul_f32 v[32:33], v[76:77], v[32:33] op_sel:[1,0]
	v_pk_mul_f32 v[34:35], v[76:77], v[34:35] op_sel:[1,0]
	v_pk_fma_f32 v[32:33], v[32:33], v[38:39], v[58:59]
	v_pk_fma_f32 v[34:35], v[34:35], v[40:41], v[60:61]
.LBB0_651:
	v_or_b32_e32 v38, 56, v74
	v_ashrrev_i32_e32 v39, 31, v38
	v_lshl_add_u64 v[40:41], v[78:79], 0, v[38:39]
	v_lshl_add_u64 v[40:41], v[40:41], 2, s[0:1]
	v_pk_fma_f32 v[32:33], v[32:33], s[84:85], v[44:45] op_sel_hi:[1,0,1]
	v_pk_fma_f32 v[34:35], v[34:35], s[84:85], v[46:47] op_sel_hi:[1,0,1]
	global_store_dwordx4 v[40:41], v[32:35], off
	s_and_b64 vcc, exec, s[4:5]
	s_nop 0
	v_or_b32_e32 v32, 32, v72
	v_ashrrev_i32_e32 v33, 31, v32
	s_cbranch_vccnz .LBB0_653
	v_lshl_add_u64 v[34:35], v[32:33], 3, s[6:7]
	global_load_dwordx2 v[40:41], v[34:35], off
	s_branch .LBB0_654

.LBB0_654:
	v_lshlrev_b64 v[42:43], 10, v[32:33]
	v_lshl_add_u64 v[46:47], v[42:43], 0, v[74:75]
	v_lshl_add_u64 v[44:45], v[46:47], 2, v[128:129]
	global_load_dwordx4 v[32:35], v[44:45], off
	global_load_dwordx4 v[92:95], v[44:45], off offset:32
	global_load_dwordx4 v[96:99], v[44:45], off offset:64
	global_load_dwordx4 v[100:103], v[44:45], off offset:96
	global_load_dwordx4 v[104:107], v[44:45], off offset:128
	global_load_dwordx4 v[108:111], v[44:45], off offset:160
	global_load_dwordx4 v[112:115], v[44:45], off offset:192
	global_load_dwordx4 v[116:119], v[44:45], off offset:224
	s_and_b64 vcc, exec, s[4:5]
	s_cbranch_vccnz .LBB0_656
	v_mov_b64_e32 v[58:59], v[120:121]
	v_mov_b64_e32 v[60:61], v[122:123]
	v_mov_b64_e32 v[72:73], v[170:171]
	v_mov_b64_e32 v[74:75], v[172:173]
	s_waitcnt vmcnt(0)
	v_pk_add_f32 v[32:33], v[32:33], v[40:41] op_sel_hi:[1,0] neg_lo:[0,1] neg_hi:[0,1]
	v_pk_add_f32 v[34:35], v[34:35], v[40:41] op_sel_hi:[1,0] neg_lo:[0,1] neg_hi:[0,1]
	v_pk_mul_f32 v[32:33], v[40:41], v[32:33] op_sel:[1,0]
	v_pk_mul_f32 v[34:35], v[40:41], v[34:35] op_sel:[1,0]
	s_waitcnt vmcnt(0)
	v_pk_fma_f32 v[32:33], v[32:33], v[58:59], v[72:73]
	v_pk_fma_f32 v[34:35], v[34:35], v[60:61], v[74:75]
.LBB0_656:
	v_lshl_add_u64 v[46:47], v[46:47], 2, s[0:1]
	s_waitcnt vmcnt(0)
	v_pk_fma_f32 v[16:17], v[32:33], s[84:85], v[16:17] op_sel_hi:[1,0,1]
	v_pk_fma_f32 v[18:19], v[34:35], s[84:85], v[18:19] op_sel_hi:[1,0,1]
	global_store_dwordx4 v[46:47], v[16:19], off
	s_nop 1
	v_mov_b64_e32 v[16:17], v[92:93]
	v_mov_b64_e32 v[18:19], v[94:95]
	s_and_b64 vcc, exec, s[4:5]
	s_cbranch_vccnz .LBB0_658
	v_mov_b64_e32 v[32:33], v[124:125]
	v_mov_b64_e32 v[34:35], v[126:127]
	v_mov_b64_e32 v[58:59], v[190:191]
	v_mov_b64_e32 v[60:61], v[192:193]
	v_pk_add_f32 v[16:17], v[16:17], v[40:41] op_sel_hi:[1,0] neg_lo:[0,1] neg_hi:[0,1]
	v_pk_add_f32 v[18:19], v[18:19], v[40:41] op_sel_hi:[1,0] neg_lo:[0,1] neg_hi:[0,1]
	v_pk_mul_f32 v[16:17], v[40:41], v[16:17] op_sel:[1,0]
	v_pk_mul_f32 v[18:19], v[40:41], v[18:19] op_sel:[1,0]
	v_pk_fma_f32 v[16:17], v[16:17], v[32:33], v[58:59]
	v_pk_fma_f32 v[18:19], v[18:19], v[34:35], v[60:61]
.LBB0_658:
	v_lshl_add_u64 v[32:33], v[42:43], 0, v[64:65]
	v_lshl_add_u64 v[32:33], v[32:33], 2, s[0:1]
	v_pk_fma_f32 v[16:17], v[16:17], s[84:85], v[20:21] op_sel_hi:[1,0,1]
	v_pk_fma_f32 v[18:19], v[18:19], s[84:85], v[22:23] op_sel_hi:[1,0,1]
	global_store_dwordx4 v[32:33], v[16:19], off
	s_nop 1
	v_mov_b64_e32 v[16:17], v[96:97]
	v_mov_b64_e32 v[18:19], v[98:99]
	s_and_b64 vcc, exec, s[4:5]
	s_cbranch_vccnz .LBB0_660
	v_mov_b64_e32 v[20:21], v[146:147]
	v_mov_b64_e32 v[22:23], v[148:149]
	v_mov_b64_e32 v[32:33], v[194:195]
	v_mov_b64_e32 v[34:35], v[196:197]
	v_pk_add_f32 v[16:17], v[16:17], v[40:41] op_sel_hi:[1,0] neg_lo:[0,1] neg_hi:[0,1]
	v_pk_add_f32 v[18:19], v[18:19], v[40:41] op_sel_hi:[1,0] neg_lo:[0,1] neg_hi:[0,1]
	v_pk_mul_f32 v[16:17], v[40:41], v[16:17] op_sel:[1,0]
	v_pk_mul_f32 v[18:19], v[40:41], v[18:19] op_sel:[1,0]
	v_pk_fma_f32 v[16:17], v[16:17], v[20:21], v[32:33]
	v_pk_fma_f32 v[18:19], v[18:19], v[22:23], v[34:35]
.LBB0_660:
	v_lshl_add_u64 v[20:21], v[42:43], 0, v[52:53]
	v_lshl_add_u64 v[20:21], v[20:21], 2, s[0:1]
	v_pk_fma_f32 v[16:17], v[16:17], s[84:85], v[24:25] op_sel_hi:[1,0,1]
	v_pk_fma_f32 v[18:19], v[18:19], s[84:85], v[26:27] op_sel_hi:[1,0,1]
	global_store_dwordx4 v[20:21], v[16:19], off
	s_nop 1
	v_mov_b64_e32 v[16:17], v[100:101]
	v_mov_b64_e32 v[18:19], v[102:103]
	s_and_b64 vcc, exec, s[4:5]
	s_cbranch_vccnz .LBB0_662
	v_mov_b64_e32 v[20:21], v[150:151]
	v_mov_b64_e32 v[22:23], v[152:153]
	v_mov_b64_e32 v[24:25], v[198:199]
	v_mov_b64_e32 v[26:27], v[200:201]
	v_pk_add_f32 v[16:17], v[16:17], v[40:41] op_sel_hi:[1,0] neg_lo:[0,1] neg_hi:[0,1]
	v_pk_add_f32 v[18:19], v[18:19], v[40:41] op_sel_hi:[1,0] neg_lo:[0,1] neg_hi:[0,1]
	v_pk_mul_f32 v[16:17], v[40:41], v[16:17] op_sel:[1,0]
	v_pk_mul_f32 v[18:19], v[40:41], v[18:19] op_sel:[1,0]
	v_pk_fma_f32 v[16:17], v[16:17], v[20:21], v[24:25]
	v_pk_fma_f32 v[18:19], v[18:19], v[22:23], v[26:27]
.LBB0_662:
	v_lshl_add_u64 v[20:21], v[42:43], 0, v[54:55]
	v_lshl_add_u64 v[20:21], v[20:21], 2, s[0:1]
	v_pk_fma_f32 v[16:17], v[16:17], s[84:85], v[28:29] op_sel_hi:[1,0,1]
	v_pk_fma_f32 v[18:19], v[18:19], s[84:85], v[30:31] op_sel_hi:[1,0,1]
	global_store_dwordx4 v[20:21], v[16:19], off
	s_nop 1
	v_mov_b64_e32 v[16:17], v[104:105]
	v_mov_b64_e32 v[18:19], v[106:107]
	s_and_b64 vcc, exec, s[4:5]
	s_cbranch_vccnz .LBB0_664
	v_mov_b64_e32 v[20:21], v[154:155]
	v_mov_b64_e32 v[22:23], v[156:157]
	v_mov_b64_e32 v[24:25], v[202:203]
	v_mov_b64_e32 v[26:27], v[204:205]
	v_pk_add_f32 v[16:17], v[16:17], v[40:41] op_sel_hi:[1,0] neg_lo:[0,1] neg_hi:[0,1]
	v_pk_add_f32 v[18:19], v[18:19], v[40:41] op_sel_hi:[1,0] neg_lo:[0,1] neg_hi:[0,1]
	v_pk_mul_f32 v[16:17], v[40:41], v[16:17] op_sel:[1,0]
	v_pk_mul_f32 v[18:19], v[40:41], v[18:19] op_sel:[1,0]
	v_pk_fma_f32 v[16:17], v[16:17], v[20:21], v[24:25]
	v_pk_fma_f32 v[18:19], v[18:19], v[22:23], v[26:27]
.LBB0_664:
	v_lshl_add_u64 v[20:21], v[42:43], 0, v[56:57]
	v_lshl_add_u64 v[20:21], v[20:21], 2, s[0:1]
	v_pk_fma_f32 v[0:1], v[16:17], s[84:85], v[0:1] op_sel_hi:[1,0,1]
	v_pk_fma_f32 v[2:3], v[18:19], s[84:85], v[2:3] op_sel_hi:[1,0,1]
	global_store_dwordx4 v[20:21], v[0:3], off
	s_nop 1
	v_mov_b64_e32 v[0:1], v[108:109]
	v_mov_b64_e32 v[2:3], v[110:111]
	s_and_b64 vcc, exec, s[4:5]
	s_cbranch_vccnz .LBB0_666
	v_mov_b64_e32 v[16:17], v[158:159]
	v_mov_b64_e32 v[18:19], v[160:161]
	v_mov_b64_e32 v[20:21], v[206:207]
	v_mov_b64_e32 v[22:23], v[208:209]
	v_pk_add_f32 v[0:1], v[0:1], v[40:41] op_sel_hi:[1,0] neg_lo:[0,1] neg_hi:[0,1]
	v_pk_add_f32 v[2:3], v[2:3], v[40:41] op_sel_hi:[1,0] neg_lo:[0,1] neg_hi:[0,1]
	v_pk_mul_f32 v[0:1], v[40:41], v[0:1] op_sel:[1,0]
	v_pk_mul_f32 v[2:3], v[40:41], v[2:3] op_sel:[1,0]
	v_pk_fma_f32 v[0:1], v[0:1], v[16:17], v[20:21]
	v_pk_fma_f32 v[2:3], v[2:3], v[18:19], v[22:23]
.LBB0_666:
	v_lshl_add_u64 v[16:17], v[42:43], 0, v[48:49]
	v_lshl_add_u64 v[16:17], v[16:17], 2, s[0:1]
	v_pk_fma_f32 v[0:1], v[0:1], s[84:85], v[4:5] op_sel_hi:[1,0,1]
	v_pk_fma_f32 v[2:3], v[2:3], s[84:85], v[6:7] op_sel_hi:[1,0,1]
	global_store_dwordx4 v[16:17], v[0:3], off
	s_nop 1
	v_mov_b64_e32 v[0:1], v[112:113]
	v_mov_b64_e32 v[2:3], v[114:115]
	s_and_b64 vcc, exec, s[4:5]
	s_cbranch_vccnz .LBB0_668
	v_mov_b64_e32 v[4:5], v[162:163]
	v_mov_b64_e32 v[6:7], v[164:165]
	v_mov_b64_e32 v[16:17], v[210:211]
	v_mov_b64_e32 v[18:19], v[212:213]
	v_pk_add_f32 v[0:1], v[0:1], v[40:41] op_sel_hi:[1,0] neg_lo:[0,1] neg_hi:[0,1]
	v_pk_add_f32 v[2:3], v[2:3], v[40:41] op_sel_hi:[1,0] neg_lo:[0,1] neg_hi:[0,1]
	v_pk_mul_f32 v[0:1], v[40:41], v[0:1] op_sel:[1,0]
	v_pk_mul_f32 v[2:3], v[40:41], v[2:3] op_sel:[1,0]
	v_pk_fma_f32 v[0:1], v[0:1], v[4:5], v[16:17]
	v_pk_fma_f32 v[2:3], v[2:3], v[6:7], v[18:19]
.LBB0_668:
	v_lshl_add_u64 v[4:5], v[42:43], 0, v[36:37]
	v_lshl_add_u64 v[4:5], v[4:5], 2, s[0:1]
	v_pk_fma_f32 v[0:1], v[0:1], s[84:85], v[8:9] op_sel_hi:[1,0,1]
	v_pk_fma_f32 v[2:3], v[2:3], s[84:85], v[10:11] op_sel_hi:[1,0,1]
	global_store_dwordx4 v[4:5], v[0:3], off
	s_nop 1
	v_mov_b64_e32 v[0:1], v[116:117]
	v_mov_b64_e32 v[2:3], v[118:119]
	s_and_b64 vcc, exec, s[4:5]
	s_cbranch_vccnz .LBB0_619
	v_mov_b64_e32 v[4:5], v[166:167]
	v_mov_b64_e32 v[6:7], v[168:169]
	v_mov_b64_e32 v[8:9], v[236:237]
	v_mov_b64_e32 v[10:11], v[238:239]
	v_pk_add_f32 v[0:1], v[0:1], v[40:41] op_sel_hi:[1,0] neg_lo:[0,1] neg_hi:[0,1]
	v_pk_add_f32 v[2:3], v[2:3], v[40:41] op_sel_hi:[1,0] neg_lo:[0,1] neg_hi:[0,1]
	v_pk_mul_f32 v[0:1], v[40:41], v[0:1] op_sel:[1,0]
	v_pk_mul_f32 v[2:3], v[40:41], v[2:3] op_sel:[1,0]
	v_pk_fma_f32 v[0:1], v[0:1], v[4:5], v[8:9]
	v_pk_fma_f32 v[2:3], v[2:3], v[6:7], v[10:11]
	s_branch .LBB0_619

.LBB0_780:
	v_or_b32_e32 v65, s24, v136
	v_add_u32_e32 v68, v65, v131
	v_lshrrev_b32_e32 v65, 3, v129
	v_and_b32_e32 v64, 64, v129
	v_and_b32_e32 v65, 4, v65
	v_ashrrev_i32_e32 v69, 31, v68
	v_or3_b32 v64, v64, v65, s23
	v_lshl_add_u64 v[66:67], v[68:69], 3, s[4:5]
	global_load_dwordx2 v[72:73], v[66:67], off
	v_ashrrev_i32_e32 v65, 31, v64
	v_lshlrev_b64 v[66:67], 12, v[68:69]
	v_lshl_add_u64 v[66:67], s[0:1], 0, v[66:67]
	v_lshlrev_b64 v[70:71], 2, v[64:65]
	v_lshl_add_u64 v[74:75], v[66:67], 0, v[70:71]
	v_lshl_add_u64 v[66:67], s[8:9], 0, v[70:71]
	v_lshl_add_u64 v[64:65], s[10:11], 0, v[70:71]
	global_load_dwordx4 v[76:79], v[74:75], off
	global_load_dwordx4 v[92:95], v[74:75], off offset:32
	global_load_dwordx4 v[96:99], v[74:75], off offset:64
	global_load_dwordx4 v[100:103], v[74:75], off offset:96
	global_load_dwordx4 v[104:107], v[74:75], off offset:128
	global_load_dwordx4 v[108:111], v[74:75], off offset:160
	global_load_dwordx4 v[112:115], v[74:75], off offset:192
	global_load_dwordx4 v[116:119], v[74:75], off offset:224
	global_load_dwordx4 v[80:83], v[66:67], off
	global_load_dwordx4 v[120:123], v[66:67], off offset:0
	global_load_dwordx4 v[124:127], v[66:67], off offset:32
	global_load_dwordx4 v[146:149], v[66:67], off offset:64
	global_load_dwordx4 v[150:153], v[66:67], off offset:96
	global_load_dwordx4 v[154:157], v[66:67], off offset:128
	global_load_dwordx4 v[158:161], v[66:67], off offset:160
	global_load_dwordx4 v[162:165], v[66:67], off offset:192
	global_load_dwordx4 v[166:169], v[66:67], off offset:224
	global_load_dwordx4 v[84:87], v[64:65], off
	global_load_dwordx4 v[170:173], v[64:65], off offset:0
	global_load_dwordx4 v[190:193], v[64:65], off offset:32
	global_load_dwordx4 v[194:197], v[64:65], off offset:64
	global_load_dwordx4 v[198:201], v[64:65], off offset:96
	global_load_dwordx4 v[202:205], v[64:65], off offset:128
	global_load_dwordx4 v[206:209], v[64:65], off offset:160
	global_load_dwordx4 v[210:213], v[64:65], off offset:192
	global_load_dwordx4 v[236:239], v[64:65], off offset:224
	s_add_i32 s22, s22, s85
	s_mov_b64 s[2:3], 0
	s_waitcnt vmcnt(0)
	v_pk_add_f32 v[76:77], v[76:77], v[72:73] op_sel_hi:[1,0] neg_lo:[0,1] neg_hi:[0,1]
	s_nop 0
	v_pk_mul_f32 v[76:77], v[72:73], v[76:77] op_sel:[1,0]
	s_waitcnt vmcnt(0)
	v_pk_fma_f32 v[76:77], v[76:77], v[80:81], v[84:85]
	s_nop 0
	v_pk_fma_f32 v[48:49], v[76:77], s[84:85], v[48:49] op_sel_hi:[1,0,1]
	v_pk_add_f32 v[76:77], v[78:79], v[72:73] op_sel_hi:[1,0] neg_lo:[0,1] neg_hi:[0,1]
	s_nop 0
	v_pk_mul_f32 v[76:77], v[72:73], v[76:77] op_sel:[1,0]
	s_nop 0
	v_pk_fma_f32 v[76:77], v[76:77], v[82:83], v[86:87]
	s_nop 0
	v_pk_fma_f32 v[50:51], v[76:77], s[84:85], v[50:51] op_sel_hi:[1,0,1]
	global_store_dwordx4 v[74:75], v[48:51], off
	s_nop 1
	v_mov_b64_e32 v[48:49], v[92:93]
	v_mov_b64_e32 v[50:51], v[94:95]
	s_nop 0
	v_mov_b64_e32 v[76:77], v[124:125]
	v_mov_b64_e32 v[78:79], v[126:127]
	v_mov_b64_e32 v[80:81], v[190:191]
	v_mov_b64_e32 v[82:83], v[192:193]
	v_pk_add_f32 v[48:49], v[48:49], v[72:73] op_sel_hi:[1,0] neg_lo:[0,1] neg_hi:[0,1]
	v_pk_add_f32 v[50:51], v[50:51], v[72:73] op_sel_hi:[1,0] neg_lo:[0,1] neg_hi:[0,1]
	v_pk_mul_f32 v[48:49], v[72:73], v[48:49] op_sel:[1,0]
	v_pk_mul_f32 v[50:51], v[72:73], v[50:51] op_sel:[1,0]
	v_pk_fma_f32 v[48:49], v[48:49], v[76:77], v[80:81]
	v_pk_fma_f32 v[50:51], v[50:51], v[78:79], v[82:83]
	v_pk_fma_f32 v[48:49], v[48:49], s[84:85], v[52:53] op_sel_hi:[1,0,1]
	v_pk_fma_f32 v[50:51], v[50:51], s[84:85], v[54:55] op_sel_hi:[1,0,1]
	global_store_dwordx4 v[74:75], v[48:51], off offset:32
	s_nop 1
	v_mov_b64_e32 v[48:49], v[96:97]
	v_mov_b64_e32 v[50:51], v[98:99]
	s_nop 0
	v_mov_b64_e32 v[52:53], v[146:147]
	v_mov_b64_e32 v[54:55], v[148:149]
	v_mov_b64_e32 v[76:77], v[194:195]
	v_mov_b64_e32 v[78:79], v[196:197]
	v_pk_add_f32 v[48:49], v[48:49], v[72:73] op_sel_hi:[1,0] neg_lo:[0,1] neg_hi:[0,1]
	v_pk_add_f32 v[50:51], v[50:51], v[72:73] op_sel_hi:[1,0] neg_lo:[0,1] neg_hi:[0,1]
	v_pk_mul_f32 v[48:49], v[72:73], v[48:49] op_sel:[1,0]
	v_pk_mul_f32 v[50:51], v[72:73], v[50:51] op_sel:[1,0]
	v_pk_fma_f32 v[48:49], v[48:49], v[52:53], v[76:77]
	v_pk_fma_f32 v[50:51], v[50:51], v[54:55], v[78:79]
	v_pk_fma_f32 v[48:49], v[48:49], s[84:85], v[56:57] op_sel_hi:[1,0,1]
	v_pk_fma_f32 v[50:51], v[50:51], s[84:85], v[58:59] op_sel_hi:[1,0,1]
	global_store_dwordx4 v[74:75], v[48:51], off offset:64
	s_nop 1
	v_mov_b64_e32 v[48:49], v[100:101]
	v_mov_b64_e32 v[50:51], v[102:103]
	s_nop 0
	v_mov_b64_e32 v[52:53], v[150:151]
	v_mov_b64_e32 v[54:55], v[152:153]
	v_mov_b64_e32 v[56:57], v[198:199]
	v_mov_b64_e32 v[58:59], v[200:201]
	v_pk_add_f32 v[48:49], v[48:49], v[72:73] op_sel_hi:[1,0] neg_lo:[0,1] neg_hi:[0,1]
	v_pk_add_f32 v[50:51], v[50:51], v[72:73] op_sel_hi:[1,0] neg_lo:[0,1] neg_hi:[0,1]
	v_pk_mul_f32 v[48:49], v[72:73], v[48:49] op_sel:[1,0]
	v_pk_mul_f32 v[50:51], v[72:73], v[50:51] op_sel:[1,0]
	v_pk_fma_f32 v[48:49], v[48:49], v[52:53], v[56:57]
	v_pk_fma_f32 v[50:51], v[50:51], v[54:55], v[58:59]
	v_pk_fma_f32 v[48:49], v[48:49], s[84:85], v[60:61] op_sel_hi:[1,0,1]
	v_pk_fma_f32 v[50:51], v[50:51], s[84:85], v[62:63] op_sel_hi:[1,0,1]
	global_store_dwordx4 v[74:75], v[48:51], off offset:96
	s_nop 1
	v_mov_b64_e32 v[48:49], v[104:105]
	v_mov_b64_e32 v[50:51], v[106:107]
	s_nop 0
	v_mov_b64_e32 v[52:53], v[154:155]
	v_mov_b64_e32 v[54:55], v[156:157]
	v_mov_b64_e32 v[56:57], v[202:203]
	v_mov_b64_e32 v[58:59], v[204:205]
	v_pk_add_f32 v[48:49], v[48:49], v[72:73] op_sel_hi:[1,0] neg_lo:[0,1] neg_hi:[0,1]
	s_nop 0
	v_pk_mul_f32 v[48:49], v[72:73], v[48:49] op_sel:[1,0]
	v_pk_fma_f32 v[48:49], v[48:49], v[52:53], v[56:57]
	s_nop 0
	v_pk_fma_f32 v[32:33], v[48:49], s[84:85], v[32:33] op_sel_hi:[1,0,1]
	v_pk_add_f32 v[48:49], v[50:51], v[72:73] op_sel_hi:[1,0] neg_lo:[0,1] neg_hi:[0,1]
	s_nop 0
	v_pk_mul_f32 v[48:49], v[72:73], v[48:49] op_sel:[1,0]
	s_nop 0
	v_pk_fma_f32 v[48:49], v[48:49], v[54:55], v[58:59]
	s_nop 0
	v_pk_fma_f32 v[34:35], v[48:49], s[84:85], v[34:35] op_sel_hi:[1,0,1]
	global_store_dwordx4 v[74:75], v[32:35], off offset:128
	s_nop 1
	v_mov_b64_e32 v[32:33], v[108:109]
	v_mov_b64_e32 v[34:35], v[110:111]
	s_nop 0
	v_mov_b64_e32 v[48:49], v[158:159]
	v_mov_b64_e32 v[50:51], v[160:161]
	v_mov_b64_e32 v[52:53], v[206:207]
	v_mov_b64_e32 v[54:55], v[208:209]
	v_pk_add_f32 v[32:33], v[32:33], v[72:73] op_sel_hi:[1,0] neg_lo:[0,1] neg_hi:[0,1]
	v_pk_add_f32 v[34:35], v[34:35], v[72:73] op_sel_hi:[1,0] neg_lo:[0,1] neg_hi:[0,1]
	v_pk_mul_f32 v[32:33], v[72:73], v[32:33] op_sel:[1,0]
	v_pk_mul_f32 v[34:35], v[72:73], v[34:35] op_sel:[1,0]
	v_pk_fma_f32 v[32:33], v[32:33], v[48:49], v[52:53]
	v_pk_fma_f32 v[34:35], v[34:35], v[50:51], v[54:55]
	v_pk_fma_f32 v[32:33], v[32:33], s[84:85], v[36:37] op_sel_hi:[1,0,1]
	v_pk_fma_f32 v[34:35], v[34:35], s[84:85], v[38:39] op_sel_hi:[1,0,1]
	global_store_dwordx4 v[74:75], v[32:35], off offset:160
	s_nop 1
	v_mov_b64_e32 v[32:33], v[112:113]
	v_mov_b64_e32 v[34:35], v[114:115]
	s_nop 0
	v_mov_b64_e32 v[36:37], v[162:163]
	v_mov_b64_e32 v[38:39], v[164:165]
	v_mov_b64_e32 v[48:49], v[210:211]
	v_mov_b64_e32 v[50:51], v[212:213]
	v_pk_add_f32 v[32:33], v[32:33], v[72:73] op_sel_hi:[1,0] neg_lo:[0,1] neg_hi:[0,1]
	v_pk_add_f32 v[34:35], v[34:35], v[72:73] op_sel_hi:[1,0] neg_lo:[0,1] neg_hi:[0,1]
	v_pk_mul_f32 v[32:33], v[72:73], v[32:33] op_sel:[1,0]
	v_pk_mul_f32 v[34:35], v[72:73], v[34:35] op_sel:[1,0]
	v_pk_fma_f32 v[32:33], v[32:33], v[36:37], v[48:49]
	v_pk_fma_f32 v[34:35], v[34:35], v[38:39], v[50:51]
	v_pk_fma_f32 v[32:33], v[32:33], s[84:85], v[40:41] op_sel_hi:[1,0,1]
	v_pk_fma_f32 v[34:35], v[34:35], s[84:85], v[42:43] op_sel_hi:[1,0,1]
	global_store_dwordx4 v[74:75], v[32:35], off offset:192
	s_nop 1
	v_mov_b64_e32 v[32:33], v[116:117]
	v_mov_b64_e32 v[34:35], v[118:119]
	s_nop 0
	v_mov_b64_e32 v[36:37], v[166:167]
	v_mov_b64_e32 v[38:39], v[168:169]
	v_mov_b64_e32 v[40:41], v[236:237]
	v_mov_b64_e32 v[42:43], v[238:239]
	v_pk_add_f32 v[32:33], v[32:33], v[72:73] op_sel_hi:[1,0] neg_lo:[0,1] neg_hi:[0,1]
	v_pk_add_f32 v[34:35], v[34:35], v[72:73] op_sel_hi:[1,0] neg_lo:[0,1] neg_hi:[0,1]
	v_pk_mul_f32 v[32:33], v[72:73], v[32:33] op_sel:[1,0]
	v_pk_mul_f32 v[34:35], v[72:73], v[34:35] op_sel:[1,0]
	v_pk_fma_f32 v[32:33], v[32:33], v[36:37], v[40:41]
	v_pk_fma_f32 v[34:35], v[34:35], v[38:39], v[42:43]
	v_pk_fma_f32 v[32:33], v[32:33], s[84:85], v[44:45] op_sel_hi:[1,0,1]
	v_pk_fma_f32 v[34:35], v[34:35], s[84:85], v[46:47] op_sel_hi:[1,0,1]
	global_store_dwordx4 v[74:75], v[32:35], off offset:224
	s_nop 1
	v_or_b32_e32 v34, 32, v68
	v_ashrrev_i32_e32 v35, 31, v34
	v_lshl_add_u64 v[32:33], v[34:35], 3, s[4:5]
	v_lshlrev_b64 v[34:35], 12, v[34:35]
	global_load_dwordx2 v[32:33], v[32:33], off
	v_lshl_add_u64 v[34:35], s[0:1], 0, v[34:35]
	v_lshl_add_u64 v[34:35], v[34:35], 0, v[70:71]
	global_load_dwordx4 v[36:39], v[34:35], off
	global_load_dwordx4 v[92:95], v[34:35], off offset:32
	global_load_dwordx4 v[96:99], v[34:35], off offset:64
	global_load_dwordx4 v[100:103], v[34:35], off offset:96
	global_load_dwordx4 v[104:107], v[34:35], off offset:128
	global_load_dwordx4 v[108:111], v[34:35], off offset:160
	global_load_dwordx4 v[112:115], v[34:35], off offset:192
	global_load_dwordx4 v[116:119], v[34:35], off offset:224
	v_mov_b64_e32 v[40:41], v[120:121]
	v_mov_b64_e32 v[42:43], v[122:123]
	v_mov_b64_e32 v[44:45], v[170:171]
	v_mov_b64_e32 v[46:47], v[172:173]
	s_waitcnt vmcnt(0)
	v_pk_add_f32 v[36:37], v[36:37], v[32:33] op_sel_hi:[1,0] neg_lo:[0,1] neg_hi:[0,1]
	s_nop 0
	v_pk_mul_f32 v[36:37], v[32:33], v[36:37] op_sel:[1,0]
	s_waitcnt vmcnt(0)
	v_pk_fma_f32 v[36:37], v[36:37], v[40:41], v[44:45]
	s_nop 0
	v_pk_fma_f32 v[16:17], v[36:37], s[84:85], v[16:17] op_sel_hi:[1,0,1]
	v_pk_add_f32 v[36:37], v[38:39], v[32:33] op_sel_hi:[1,0] neg_lo:[0,1] neg_hi:[0,1]
	s_nop 0
	v_pk_mul_f32 v[36:37], v[32:33], v[36:37] op_sel:[1,0]
	s_nop 0
	v_pk_fma_f32 v[36:37], v[36:37], v[42:43], v[46:47]
	s_nop 0
	v_pk_fma_f32 v[18:19], v[36:37], s[84:85], v[18:19] op_sel_hi:[1,0,1]
	global_store_dwordx4 v[34:35], v[16:19], off
	s_nop 1
	v_mov_b64_e32 v[16:17], v[92:93]
	v_mov_b64_e32 v[18:19], v[94:95]
	s_nop 0
	v_mov_b64_e32 v[36:37], v[124:125]
	v_mov_b64_e32 v[38:39], v[126:127]
	v_mov_b64_e32 v[40:41], v[190:191]
	v_mov_b64_e32 v[42:43], v[192:193]
	v_pk_add_f32 v[16:17], v[16:17], v[32:33] op_sel_hi:[1,0] neg_lo:[0,1] neg_hi:[0,1]
	v_pk_add_f32 v[18:19], v[18:19], v[32:33] op_sel_hi:[1,0] neg_lo:[0,1] neg_hi:[0,1]
	v_pk_mul_f32 v[16:17], v[32:33], v[16:17] op_sel:[1,0]
	v_pk_mul_f32 v[18:19], v[32:33], v[18:19] op_sel:[1,0]
	v_pk_fma_f32 v[16:17], v[16:17], v[36:37], v[40:41]
	v_pk_fma_f32 v[18:19], v[18:19], v[38:39], v[42:43]
	v_pk_fma_f32 v[16:17], v[16:17], s[84:85], v[20:21] op_sel_hi:[1,0,1]
	v_pk_fma_f32 v[18:19], v[18:19], s[84:85], v[22:23] op_sel_hi:[1,0,1]
	global_store_dwordx4 v[34:35], v[16:19], off offset:32
	s_nop 1
	v_mov_b64_e32 v[16:17], v[96:97]
	v_mov_b64_e32 v[18:19], v[98:99]
	s_nop 0
	v_mov_b64_e32 v[20:21], v[146:147]
	v_mov_b64_e32 v[22:23], v[148:149]
	v_mov_b64_e32 v[36:37], v[194:195]
	v_mov_b64_e32 v[38:39], v[196:197]
	v_pk_add_f32 v[16:17], v[16:17], v[32:33] op_sel_hi:[1,0] neg_lo:[0,1] neg_hi:[0,1]
	v_pk_add_f32 v[18:19], v[18:19], v[32:33] op_sel_hi:[1,0] neg_lo:[0,1] neg_hi:[0,1]
	v_pk_mul_f32 v[16:17], v[32:33], v[16:17] op_sel:[1,0]
	v_pk_mul_f32 v[18:19], v[32:33], v[18:19] op_sel:[1,0]
	v_pk_fma_f32 v[16:17], v[16:17], v[20:21], v[36:37]
	v_pk_fma_f32 v[18:19], v[18:19], v[22:23], v[38:39]
	v_pk_fma_f32 v[16:17], v[16:17], s[84:85], v[24:25] op_sel_hi:[1,0,1]
	v_pk_fma_f32 v[18:19], v[18:19], s[84:85], v[26:27] op_sel_hi:[1,0,1]
	global_store_dwordx4 v[34:35], v[16:19], off offset:64
	s_nop 1
	v_mov_b64_e32 v[16:17], v[100:101]
	v_mov_b64_e32 v[18:19], v[102:103]
	s_nop 0
	v_mov_b64_e32 v[20:21], v[150:151]
	v_mov_b64_e32 v[22:23], v[152:153]
	v_mov_b64_e32 v[24:25], v[198:199]
	v_mov_b64_e32 v[26:27], v[200:201]
	v_pk_add_f32 v[16:17], v[16:17], v[32:33] op_sel_hi:[1,0] neg_lo:[0,1] neg_hi:[0,1]
	v_pk_add_f32 v[18:19], v[18:19], v[32:33] op_sel_hi:[1,0] neg_lo:[0,1] neg_hi:[0,1]
	v_pk_mul_f32 v[16:17], v[32:33], v[16:17] op_sel:[1,0]
	v_pk_mul_f32 v[18:19], v[32:33], v[18:19] op_sel:[1,0]
	v_pk_fma_f32 v[16:17], v[16:17], v[20:21], v[24:25]
	v_pk_fma_f32 v[18:19], v[18:19], v[22:23], v[26:27]
	v_pk_fma_f32 v[16:17], v[16:17], s[84:85], v[28:29] op_sel_hi:[1,0,1]
	v_pk_fma_f32 v[18:19], v[18:19], s[84:85], v[30:31] op_sel_hi:[1,0,1]
	global_store_dwordx4 v[34:35], v[16:19], off offset:96
	s_nop 1
	v_mov_b64_e32 v[16:17], v[104:105]
	v_mov_b64_e32 v[18:19], v[106:107]
	s_nop 0
	v_mov_b64_e32 v[20:21], v[154:155]
	v_mov_b64_e32 v[22:23], v[156:157]
	v_mov_b64_e32 v[24:25], v[202:203]
	v_mov_b64_e32 v[26:27], v[204:205]
	v_pk_add_f32 v[16:17], v[16:17], v[32:33] op_sel_hi:[1,0] neg_lo:[0,1] neg_hi:[0,1]
	s_nop 0
	v_pk_mul_f32 v[16:17], v[32:33], v[16:17] op_sel:[1,0]
	v_pk_fma_f32 v[16:17], v[16:17], v[20:21], v[24:25]
	s_nop 0
	v_pk_fma_f32 v[0:1], v[16:17], s[84:85], v[0:1] op_sel_hi:[1,0,1]
	v_pk_add_f32 v[16:17], v[18:19], v[32:33] op_sel_hi:[1,0] neg_lo:[0,1] neg_hi:[0,1]
	s_nop 0
	v_pk_mul_f32 v[16:17], v[32:33], v[16:17] op_sel:[1,0]
	s_nop 0
	v_pk_fma_f32 v[16:17], v[16:17], v[22:23], v[26:27]
	s_nop 0
	v_pk_fma_f32 v[2:3], v[16:17], s[84:85], v[2:3] op_sel_hi:[1,0,1]
	global_store_dwordx4 v[34:35], v[0:3], off offset:128
	s_nop 1
	v_mov_b64_e32 v[0:1], v[108:109]
	v_mov_b64_e32 v[2:3], v[110:111]
	s_nop 0
	v_mov_b64_e32 v[16:17], v[158:159]
	v_mov_b64_e32 v[18:19], v[160:161]
	v_mov_b64_e32 v[20:21], v[206:207]
	v_mov_b64_e32 v[22:23], v[208:209]
	v_pk_add_f32 v[0:1], v[0:1], v[32:33] op_sel_hi:[1,0] neg_lo:[0,1] neg_hi:[0,1]
	v_pk_add_f32 v[2:3], v[2:3], v[32:33] op_sel_hi:[1,0] neg_lo:[0,1] neg_hi:[0,1]
	v_pk_mul_f32 v[0:1], v[32:33], v[0:1] op_sel:[1,0]
	v_pk_mul_f32 v[2:3], v[32:33], v[2:3] op_sel:[1,0]
	v_pk_fma_f32 v[0:1], v[0:1], v[16:17], v[20:21]
	v_pk_fma_f32 v[2:3], v[2:3], v[18:19], v[22:23]
	v_pk_fma_f32 v[0:1], v[0:1], s[84:85], v[4:5] op_sel_hi:[1,0,1]
	v_pk_fma_f32 v[2:3], v[2:3], s[84:85], v[6:7] op_sel_hi:[1,0,1]
	global_store_dwordx4 v[34:35], v[0:3], off offset:160
	s_nop 1
	v_mov_b64_e32 v[0:1], v[112:113]
	v_mov_b64_e32 v[2:3], v[114:115]
	s_nop 0
	v_mov_b64_e32 v[4:5], v[162:163]
	v_mov_b64_e32 v[6:7], v[164:165]
	v_mov_b64_e32 v[16:17], v[210:211]
	v_mov_b64_e32 v[18:19], v[212:213]
	v_pk_add_f32 v[0:1], v[0:1], v[32:33] op_sel_hi:[1,0] neg_lo:[0,1] neg_hi:[0,1]
	v_pk_add_f32 v[2:3], v[2:3], v[32:33] op_sel_hi:[1,0] neg_lo:[0,1] neg_hi:[0,1]
	v_pk_mul_f32 v[0:1], v[32:33], v[0:1] op_sel:[1,0]
	v_pk_mul_f32 v[2:3], v[32:33], v[2:3] op_sel:[1,0]
	v_pk_fma_f32 v[0:1], v[0:1], v[4:5], v[16:17]
	v_pk_fma_f32 v[2:3], v[2:3], v[6:7], v[18:19]
	v_pk_fma_f32 v[0:1], v[0:1], s[84:85], v[8:9] op_sel_hi:[1,0,1]
	v_pk_fma_f32 v[2:3], v[2:3], s[84:85], v[10:11] op_sel_hi:[1,0,1]
	global_store_dwordx4 v[34:35], v[0:3], off offset:192
	s_nop 1
	v_mov_b64_e32 v[0:1], v[116:117]
	v_mov_b64_e32 v[2:3], v[118:119]
	s_nop 0
	v_mov_b64_e32 v[4:5], v[166:167]
	v_mov_b64_e32 v[6:7], v[168:169]
	v_mov_b64_e32 v[8:9], v[236:237]
	v_mov_b64_e32 v[10:11], v[238:239]
	v_pk_add_f32 v[0:1], v[0:1], v[32:33] op_sel_hi:[1,0] neg_lo:[0,1] neg_hi:[0,1]
	v_pk_add_f32 v[2:3], v[2:3], v[32:33] op_sel_hi:[1,0] neg_lo:[0,1] neg_hi:[0,1]
	v_pk_mul_f32 v[0:1], v[32:33], v[0:1] op_sel:[1,0]
	v_pk_mul_f32 v[2:3], v[32:33], v[2:3] op_sel:[1,0]
	v_pk_fma_f32 v[0:1], v[0:1], v[4:5], v[8:9]
	v_pk_fma_f32 v[2:3], v[2:3], v[6:7], v[10:11]
	v_pk_fma_f32 v[0:1], v[0:1], s[84:85], v[12:13] op_sel_hi:[1,0,1]
	v_pk_fma_f32 v[2:3], v[2:3], s[84:85], v[14:15] op_sel_hi:[1,0,1]
	global_store_dwordx4 v[34:35], v[0:3], off offset:224

.LBB0_1043:
	v_or_b32_e32 v65, s14, v136
	v_add_u32_e32 v68, v65, v131
	v_lshrrev_b32_e32 v65, 3, v129
	v_and_b32_e32 v64, 64, v129
	v_and_b32_e32 v65, 4, v65
	v_ashrrev_i32_e32 v69, 31, v68
	v_or3_b32 v64, v64, v65, s13
	v_lshl_add_u64 v[66:67], v[68:69], 3, s[6:7]
	global_load_dwordx2 v[72:73], v[66:67], off
	v_ashrrev_i32_e32 v65, 31, v64
	v_lshlrev_b64 v[66:67], 12, v[68:69]
	v_lshl_add_u64 v[66:67], s[4:5], 0, v[66:67]
	v_lshlrev_b64 v[70:71], 2, v[64:65]
	v_lshl_add_u64 v[74:75], v[66:67], 0, v[70:71]
	v_lshl_add_u64 v[66:67], s[36:37], 0, v[70:71]
	v_lshl_add_u64 v[64:65], s[38:39], 0, v[70:71]
	global_load_dwordx4 v[76:79], v[74:75], off
	global_load_dwordx4 v[92:95], v[74:75], off offset:32
	global_load_dwordx4 v[96:99], v[74:75], off offset:64
	global_load_dwordx4 v[100:103], v[74:75], off offset:96
	global_load_dwordx4 v[104:107], v[74:75], off offset:128
	global_load_dwordx4 v[108:111], v[74:75], off offset:160
	global_load_dwordx4 v[112:115], v[74:75], off offset:192
	global_load_dwordx4 v[116:119], v[74:75], off offset:224
	global_load_dwordx4 v[80:83], v[66:67], off
	global_load_dwordx4 v[120:123], v[66:67], off offset:0
	global_load_dwordx4 v[124:127], v[66:67], off offset:32
	global_load_dwordx4 v[146:149], v[66:67], off offset:64
	global_load_dwordx4 v[150:153], v[66:67], off offset:96
	global_load_dwordx4 v[154:157], v[66:67], off offset:128
	global_load_dwordx4 v[158:161], v[66:67], off offset:160
	global_load_dwordx4 v[162:165], v[66:67], off offset:192
	global_load_dwordx4 v[166:169], v[66:67], off offset:224
	global_load_dwordx4 v[84:87], v[64:65], off
	global_load_dwordx4 v[170:173], v[64:65], off offset:0
	global_load_dwordx4 v[190:193], v[64:65], off offset:32
	global_load_dwordx4 v[194:197], v[64:65], off offset:64
	global_load_dwordx4 v[198:201], v[64:65], off offset:96
	global_load_dwordx4 v[202:205], v[64:65], off offset:128
	global_load_dwordx4 v[206:209], v[64:65], off offset:160
	global_load_dwordx4 v[210:213], v[64:65], off offset:192
	global_load_dwordx4 v[236:239], v[64:65], off offset:224
	s_add_i32 s12, s12, s85
	s_mov_b64 s[2:3], 0
	s_waitcnt vmcnt(0)
	v_pk_add_f32 v[76:77], v[76:77], v[72:73] op_sel_hi:[1,0] neg_lo:[0,1] neg_hi:[0,1]
	s_nop 0
	v_pk_mul_f32 v[76:77], v[72:73], v[76:77] op_sel:[1,0]
	s_waitcnt vmcnt(0)
	v_pk_fma_f32 v[76:77], v[76:77], v[80:81], v[84:85]
	s_nop 0
	v_pk_fma_f32 v[48:49], v[76:77], s[84:85], v[48:49] op_sel_hi:[1,0,1]
	v_pk_add_f32 v[76:77], v[78:79], v[72:73] op_sel_hi:[1,0] neg_lo:[0,1] neg_hi:[0,1]
	s_nop 0
	v_pk_mul_f32 v[76:77], v[72:73], v[76:77] op_sel:[1,0]
	s_nop 0
	v_pk_fma_f32 v[76:77], v[76:77], v[82:83], v[86:87]
	s_nop 0
	v_pk_fma_f32 v[50:51], v[76:77], s[84:85], v[50:51] op_sel_hi:[1,0,1]
	global_store_dwordx4 v[74:75], v[48:51], off
	s_nop 1
	v_mov_b64_e32 v[48:49], v[92:93]
	v_mov_b64_e32 v[50:51], v[94:95]
	s_nop 0
	v_mov_b64_e32 v[76:77], v[124:125]
	v_mov_b64_e32 v[78:79], v[126:127]
	v_mov_b64_e32 v[80:81], v[190:191]
	v_mov_b64_e32 v[82:83], v[192:193]
	v_pk_add_f32 v[48:49], v[48:49], v[72:73] op_sel_hi:[1,0] neg_lo:[0,1] neg_hi:[0,1]
	v_pk_add_f32 v[50:51], v[50:51], v[72:73] op_sel_hi:[1,0] neg_lo:[0,1] neg_hi:[0,1]
	v_pk_mul_f32 v[48:49], v[72:73], v[48:49] op_sel:[1,0]
	v_pk_mul_f32 v[50:51], v[72:73], v[50:51] op_sel:[1,0]
	v_pk_fma_f32 v[48:49], v[48:49], v[76:77], v[80:81]
	v_pk_fma_f32 v[50:51], v[50:51], v[78:79], v[82:83]
	v_pk_fma_f32 v[48:49], v[48:49], s[84:85], v[52:53] op_sel_hi:[1,0,1]
	v_pk_fma_f32 v[50:51], v[50:51], s[84:85], v[54:55] op_sel_hi:[1,0,1]
	global_store_dwordx4 v[74:75], v[48:51], off offset:32
	s_nop 1
	v_mov_b64_e32 v[48:49], v[96:97]
	v_mov_b64_e32 v[50:51], v[98:99]
	s_nop 0
	v_mov_b64_e32 v[52:53], v[146:147]
	v_mov_b64_e32 v[54:55], v[148:149]
	v_mov_b64_e32 v[76:77], v[194:195]
	v_mov_b64_e32 v[78:79], v[196:197]
	v_pk_add_f32 v[48:49], v[48:49], v[72:73] op_sel_hi:[1,0] neg_lo:[0,1] neg_hi:[0,1]
	v_pk_add_f32 v[50:51], v[50:51], v[72:73] op_sel_hi:[1,0] neg_lo:[0,1] neg_hi:[0,1]
	v_pk_mul_f32 v[48:49], v[72:73], v[48:49] op_sel:[1,0]
	v_pk_mul_f32 v[50:51], v[72:73], v[50:51] op_sel:[1,0]
	v_pk_fma_f32 v[48:49], v[48:49], v[52:53], v[76:77]
	v_pk_fma_f32 v[50:51], v[50:51], v[54:55], v[78:79]
	v_pk_fma_f32 v[48:49], v[48:49], s[84:85], v[56:57] op_sel_hi:[1,0,1]
	v_pk_fma_f32 v[50:51], v[50:51], s[84:85], v[58:59] op_sel_hi:[1,0,1]
	global_store_dwordx4 v[74:75], v[48:51], off offset:64
	s_nop 1
	v_mov_b64_e32 v[48:49], v[100:101]
	v_mov_b64_e32 v[50:51], v[102:103]
	s_nop 0
	v_mov_b64_e32 v[52:53], v[150:151]
	v_mov_b64_e32 v[54:55], v[152:153]
	v_mov_b64_e32 v[56:57], v[198:199]
	v_mov_b64_e32 v[58:59], v[200:201]
	v_pk_add_f32 v[48:49], v[48:49], v[72:73] op_sel_hi:[1,0] neg_lo:[0,1] neg_hi:[0,1]
	v_pk_add_f32 v[50:51], v[50:51], v[72:73] op_sel_hi:[1,0] neg_lo:[0,1] neg_hi:[0,1]
	v_pk_mul_f32 v[48:49], v[72:73], v[48:49] op_sel:[1,0]
	v_pk_mul_f32 v[50:51], v[72:73], v[50:51] op_sel:[1,0]
	v_pk_fma_f32 v[48:49], v[48:49], v[52:53], v[56:57]
	v_pk_fma_f32 v[50:51], v[50:51], v[54:55], v[58:59]
	v_pk_fma_f32 v[48:49], v[48:49], s[84:85], v[60:61] op_sel_hi:[1,0,1]
	v_pk_fma_f32 v[50:51], v[50:51], s[84:85], v[62:63] op_sel_hi:[1,0,1]
	global_store_dwordx4 v[74:75], v[48:51], off offset:96
	s_nop 1
	v_mov_b64_e32 v[48:49], v[104:105]
	v_mov_b64_e32 v[50:51], v[106:107]
	s_nop 0
	v_mov_b64_e32 v[52:53], v[154:155]
	v_mov_b64_e32 v[54:55], v[156:157]
	v_mov_b64_e32 v[56:57], v[202:203]
	v_mov_b64_e32 v[58:59], v[204:205]
	v_pk_add_f32 v[48:49], v[48:49], v[72:73] op_sel_hi:[1,0] neg_lo:[0,1] neg_hi:[0,1]
	s_nop 0
	v_pk_mul_f32 v[48:49], v[72:73], v[48:49] op_sel:[1,0]
	v_pk_fma_f32 v[48:49], v[48:49], v[52:53], v[56:57]
	s_nop 0
	v_pk_fma_f32 v[32:33], v[48:49], s[84:85], v[32:33] op_sel_hi:[1,0,1]
	v_pk_add_f32 v[48:49], v[50:51], v[72:73] op_sel_hi:[1,0] neg_lo:[0,1] neg_hi:[0,1]
	s_nop 0
	v_pk_mul_f32 v[48:49], v[72:73], v[48:49] op_sel:[1,0]
	s_nop 0
	v_pk_fma_f32 v[48:49], v[48:49], v[54:55], v[58:59]
	s_nop 0
	v_pk_fma_f32 v[34:35], v[48:49], s[84:85], v[34:35] op_sel_hi:[1,0,1]
	global_store_dwordx4 v[74:75], v[32:35], off offset:128
	s_nop 1
	v_mov_b64_e32 v[32:33], v[108:109]
	v_mov_b64_e32 v[34:35], v[110:111]
	s_nop 0
	v_mov_b64_e32 v[48:49], v[158:159]
	v_mov_b64_e32 v[50:51], v[160:161]
	v_mov_b64_e32 v[52:53], v[206:207]
	v_mov_b64_e32 v[54:55], v[208:209]
	v_pk_add_f32 v[32:33], v[32:33], v[72:73] op_sel_hi:[1,0] neg_lo:[0,1] neg_hi:[0,1]
	v_pk_add_f32 v[34:35], v[34:35], v[72:73] op_sel_hi:[1,0] neg_lo:[0,1] neg_hi:[0,1]
	v_pk_mul_f32 v[32:33], v[72:73], v[32:33] op_sel:[1,0]
	v_pk_mul_f32 v[34:35], v[72:73], v[34:35] op_sel:[1,0]
	v_pk_fma_f32 v[32:33], v[32:33], v[48:49], v[52:53]
	v_pk_fma_f32 v[34:35], v[34:35], v[50:51], v[54:55]
	v_pk_fma_f32 v[32:33], v[32:33], s[84:85], v[36:37] op_sel_hi:[1,0,1]
	v_pk_fma_f32 v[34:35], v[34:35], s[84:85], v[38:39] op_sel_hi:[1,0,1]
	global_store_dwordx4 v[74:75], v[32:35], off offset:160
	s_nop 1
	v_mov_b64_e32 v[32:33], v[112:113]
	v_mov_b64_e32 v[34:35], v[114:115]
	s_nop 0
	v_mov_b64_e32 v[36:37], v[162:163]
	v_mov_b64_e32 v[38:39], v[164:165]
	v_mov_b64_e32 v[48:49], v[210:211]
	v_mov_b64_e32 v[50:51], v[212:213]
	v_pk_add_f32 v[32:33], v[32:33], v[72:73] op_sel_hi:[1,0] neg_lo:[0,1] neg_hi:[0,1]
	v_pk_add_f32 v[34:35], v[34:35], v[72:73] op_sel_hi:[1,0] neg_lo:[0,1] neg_hi:[0,1]
	v_pk_mul_f32 v[32:33], v[72:73], v[32:33] op_sel:[1,0]
	v_pk_mul_f32 v[34:35], v[72:73], v[34:35] op_sel:[1,0]
	v_pk_fma_f32 v[32:33], v[32:33], v[36:37], v[48:49]
	v_pk_fma_f32 v[34:35], v[34:35], v[38:39], v[50:51]
	v_pk_fma_f32 v[32:33], v[32:33], s[84:85], v[40:41] op_sel_hi:[1,0,1]
	v_pk_fma_f32 v[34:35], v[34:35], s[84:85], v[42:43] op_sel_hi:[1,0,1]
	global_store_dwordx4 v[74:75], v[32:35], off offset:192
	s_nop 1
	v_mov_b64_e32 v[32:33], v[116:117]
	v_mov_b64_e32 v[34:35], v[118:119]
	s_nop 0
	v_mov_b64_e32 v[36:37], v[166:167]
	v_mov_b64_e32 v[38:39], v[168:169]
	v_mov_b64_e32 v[40:41], v[236:237]
	v_mov_b64_e32 v[42:43], v[238:239]
	v_pk_add_f32 v[32:33], v[32:33], v[72:73] op_sel_hi:[1,0] neg_lo:[0,1] neg_hi:[0,1]
	v_pk_add_f32 v[34:35], v[34:35], v[72:73] op_sel_hi:[1,0] neg_lo:[0,1] neg_hi:[0,1]
	v_pk_mul_f32 v[32:33], v[72:73], v[32:33] op_sel:[1,0]
	v_pk_mul_f32 v[34:35], v[72:73], v[34:35] op_sel:[1,0]
	v_pk_fma_f32 v[32:33], v[32:33], v[36:37], v[40:41]
	v_pk_fma_f32 v[34:35], v[34:35], v[38:39], v[42:43]
	v_pk_fma_f32 v[32:33], v[32:33], s[84:85], v[44:45] op_sel_hi:[1,0,1]
	v_pk_fma_f32 v[34:35], v[34:35], s[84:85], v[46:47] op_sel_hi:[1,0,1]
	global_store_dwordx4 v[74:75], v[32:35], off offset:224
	s_nop 1
	v_or_b32_e32 v34, 32, v68
	v_ashrrev_i32_e32 v35, 31, v34
	v_lshl_add_u64 v[32:33], v[34:35], 3, s[6:7]
	v_lshlrev_b64 v[34:35], 12, v[34:35]
	global_load_dwordx2 v[32:33], v[32:33], off
	v_lshl_add_u64 v[34:35], s[4:5], 0, v[34:35]
	v_lshl_add_u64 v[34:35], v[34:35], 0, v[70:71]
	global_load_dwordx4 v[36:39], v[34:35], off
	global_load_dwordx4 v[92:95], v[34:35], off offset:32
	global_load_dwordx4 v[96:99], v[34:35], off offset:64
	global_load_dwordx4 v[100:103], v[34:35], off offset:96
	global_load_dwordx4 v[104:107], v[34:35], off offset:128
	global_load_dwordx4 v[108:111], v[34:35], off offset:160
	global_load_dwordx4 v[112:115], v[34:35], off offset:192
	global_load_dwordx4 v[116:119], v[34:35], off offset:224
	v_mov_b64_e32 v[40:41], v[120:121]
	v_mov_b64_e32 v[42:43], v[122:123]
	v_mov_b64_e32 v[44:45], v[170:171]
	v_mov_b64_e32 v[46:47], v[172:173]
	s_waitcnt vmcnt(0)
	v_pk_add_f32 v[36:37], v[36:37], v[32:33] op_sel_hi:[1,0] neg_lo:[0,1] neg_hi:[0,1]
	s_nop 0
	v_pk_mul_f32 v[36:37], v[32:33], v[36:37] op_sel:[1,0]
	s_waitcnt vmcnt(0)
	v_pk_fma_f32 v[36:37], v[36:37], v[40:41], v[44:45]
	s_nop 0
	v_pk_fma_f32 v[16:17], v[36:37], s[84:85], v[16:17] op_sel_hi:[1,0,1]
	v_pk_add_f32 v[36:37], v[38:39], v[32:33] op_sel_hi:[1,0] neg_lo:[0,1] neg_hi:[0,1]
	s_nop 0
	v_pk_mul_f32 v[36:37], v[32:33], v[36:37] op_sel:[1,0]
	s_nop 0
	v_pk_fma_f32 v[36:37], v[36:37], v[42:43], v[46:47]
	s_nop 0
	v_pk_fma_f32 v[18:19], v[36:37], s[84:85], v[18:19] op_sel_hi:[1,0,1]
	global_store_dwordx4 v[34:35], v[16:19], off
	s_nop 1
	v_mov_b64_e32 v[16:17], v[92:93]
	v_mov_b64_e32 v[18:19], v[94:95]
	s_nop 0
	v_mov_b64_e32 v[36:37], v[124:125]
	v_mov_b64_e32 v[38:39], v[126:127]
	v_mov_b64_e32 v[40:41], v[190:191]
	v_mov_b64_e32 v[42:43], v[192:193]
	v_pk_add_f32 v[16:17], v[16:17], v[32:33] op_sel_hi:[1,0] neg_lo:[0,1] neg_hi:[0,1]
	v_pk_add_f32 v[18:19], v[18:19], v[32:33] op_sel_hi:[1,0] neg_lo:[0,1] neg_hi:[0,1]
	v_pk_mul_f32 v[16:17], v[32:33], v[16:17] op_sel:[1,0]
	v_pk_mul_f32 v[18:19], v[32:33], v[18:19] op_sel:[1,0]
	v_pk_fma_f32 v[16:17], v[16:17], v[36:37], v[40:41]
	v_pk_fma_f32 v[18:19], v[18:19], v[38:39], v[42:43]
	v_pk_fma_f32 v[16:17], v[16:17], s[84:85], v[20:21] op_sel_hi:[1,0,1]
	v_pk_fma_f32 v[18:19], v[18:19], s[84:85], v[22:23] op_sel_hi:[1,0,1]
	global_store_dwordx4 v[34:35], v[16:19], off offset:32
	s_nop 1
	v_mov_b64_e32 v[16:17], v[96:97]
	v_mov_b64_e32 v[18:19], v[98:99]
	s_nop 0
	v_mov_b64_e32 v[20:21], v[146:147]
	v_mov_b64_e32 v[22:23], v[148:149]
	v_mov_b64_e32 v[36:37], v[194:195]
	v_mov_b64_e32 v[38:39], v[196:197]
	v_pk_add_f32 v[16:17], v[16:17], v[32:33] op_sel_hi:[1,0] neg_lo:[0,1] neg_hi:[0,1]
	v_pk_add_f32 v[18:19], v[18:19], v[32:33] op_sel_hi:[1,0] neg_lo:[0,1] neg_hi:[0,1]
	v_pk_mul_f32 v[16:17], v[32:33], v[16:17] op_sel:[1,0]
	v_pk_mul_f32 v[18:19], v[32:33], v[18:19] op_sel:[1,0]
	v_pk_fma_f32 v[16:17], v[16:17], v[20:21], v[36:37]
	v_pk_fma_f32 v[18:19], v[18:19], v[22:23], v[38:39]
	v_pk_fma_f32 v[16:17], v[16:17], s[84:85], v[24:25] op_sel_hi:[1,0,1]
	v_pk_fma_f32 v[18:19], v[18:19], s[84:85], v[26:27] op_sel_hi:[1,0,1]
	global_store_dwordx4 v[34:35], v[16:19], off offset:64
	s_nop 1
	v_mov_b64_e32 v[16:17], v[100:101]
	v_mov_b64_e32 v[18:19], v[102:103]
	s_nop 0
	v_mov_b64_e32 v[20:21], v[150:151]
	v_mov_b64_e32 v[22:23], v[152:153]
	v_mov_b64_e32 v[24:25], v[198:199]
	v_mov_b64_e32 v[26:27], v[200:201]
	v_pk_add_f32 v[16:17], v[16:17], v[32:33] op_sel_hi:[1,0] neg_lo:[0,1] neg_hi:[0,1]
	v_pk_add_f32 v[18:19], v[18:19], v[32:33] op_sel_hi:[1,0] neg_lo:[0,1] neg_hi:[0,1]
	v_pk_mul_f32 v[16:17], v[32:33], v[16:17] op_sel:[1,0]
	v_pk_mul_f32 v[18:19], v[32:33], v[18:19] op_sel:[1,0]
	v_pk_fma_f32 v[16:17], v[16:17], v[20:21], v[24:25]
	v_pk_fma_f32 v[18:19], v[18:19], v[22:23], v[26:27]
	v_pk_fma_f32 v[16:17], v[16:17], s[84:85], v[28:29] op_sel_hi:[1,0,1]
	v_pk_fma_f32 v[18:19], v[18:19], s[84:85], v[30:31] op_sel_hi:[1,0,1]
	global_store_dwordx4 v[34:35], v[16:19], off offset:96
	s_nop 1
	v_mov_b64_e32 v[16:17], v[104:105]
	v_mov_b64_e32 v[18:19], v[106:107]
	s_nop 0
	v_mov_b64_e32 v[20:21], v[154:155]
	v_mov_b64_e32 v[22:23], v[156:157]
	v_mov_b64_e32 v[24:25], v[202:203]
	v_mov_b64_e32 v[26:27], v[204:205]
	v_pk_add_f32 v[16:17], v[16:17], v[32:33] op_sel_hi:[1,0] neg_lo:[0,1] neg_hi:[0,1]
	s_nop 0
	v_pk_mul_f32 v[16:17], v[32:33], v[16:17] op_sel:[1,0]
	v_pk_fma_f32 v[16:17], v[16:17], v[20:21], v[24:25]
	s_nop 0
	v_pk_fma_f32 v[0:1], v[16:17], s[84:85], v[0:1] op_sel_hi:[1,0,1]
	v_pk_add_f32 v[16:17], v[18:19], v[32:33] op_sel_hi:[1,0] neg_lo:[0,1] neg_hi:[0,1]
	s_nop 0
	v_pk_mul_f32 v[16:17], v[32:33], v[16:17] op_sel:[1,0]
	s_nop 0
	v_pk_fma_f32 v[16:17], v[16:17], v[22:23], v[26:27]
	s_nop 0
	v_pk_fma_f32 v[2:3], v[16:17], s[84:85], v[2:3] op_sel_hi:[1,0,1]
	global_store_dwordx4 v[34:35], v[0:3], off offset:128
	s_nop 1
	v_mov_b64_e32 v[0:1], v[108:109]
	v_mov_b64_e32 v[2:3], v[110:111]
	s_nop 0
	v_mov_b64_e32 v[16:17], v[158:159]
	v_mov_b64_e32 v[18:19], v[160:161]
	v_mov_b64_e32 v[20:21], v[206:207]
	v_mov_b64_e32 v[22:23], v[208:209]
	v_pk_add_f32 v[0:1], v[0:1], v[32:33] op_sel_hi:[1,0] neg_lo:[0,1] neg_hi:[0,1]
	v_pk_add_f32 v[2:3], v[2:3], v[32:33] op_sel_hi:[1,0] neg_lo:[0,1] neg_hi:[0,1]
	v_pk_mul_f32 v[0:1], v[32:33], v[0:1] op_sel:[1,0]
	v_pk_mul_f32 v[2:3], v[32:33], v[2:3] op_sel:[1,0]
	v_pk_fma_f32 v[0:1], v[0:1], v[16:17], v[20:21]
	v_pk_fma_f32 v[2:3], v[2:3], v[18:19], v[22:23]
	v_pk_fma_f32 v[0:1], v[0:1], s[84:85], v[4:5] op_sel_hi:[1,0,1]
	v_pk_fma_f32 v[2:3], v[2:3], s[84:85], v[6:7] op_sel_hi:[1,0,1]
	global_store_dwordx4 v[34:35], v[0:3], off offset:160
	s_nop 1
	v_mov_b64_e32 v[0:1], v[112:113]
	v_mov_b64_e32 v[2:3], v[114:115]
	s_nop 0
	v_mov_b64_e32 v[4:5], v[162:163]
	v_mov_b64_e32 v[6:7], v[164:165]
	v_mov_b64_e32 v[16:17], v[210:211]
	v_mov_b64_e32 v[18:19], v[212:213]
	v_pk_add_f32 v[0:1], v[0:1], v[32:33] op_sel_hi:[1,0] neg_lo:[0,1] neg_hi:[0,1]
	v_pk_add_f32 v[2:3], v[2:3], v[32:33] op_sel_hi:[1,0] neg_lo:[0,1] neg_hi:[0,1]
	v_pk_mul_f32 v[0:1], v[32:33], v[0:1] op_sel:[1,0]
	v_pk_mul_f32 v[2:3], v[32:33], v[2:3] op_sel:[1,0]
	v_pk_fma_f32 v[0:1], v[0:1], v[4:5], v[16:17]
	v_pk_fma_f32 v[2:3], v[2:3], v[6:7], v[18:19]
	v_pk_fma_f32 v[0:1], v[0:1], s[84:85], v[8:9] op_sel_hi:[1,0,1]
	v_pk_fma_f32 v[2:3], v[2:3], s[84:85], v[10:11] op_sel_hi:[1,0,1]
	global_store_dwordx4 v[34:35], v[0:3], off offset:192
	s_nop 1
	v_mov_b64_e32 v[0:1], v[116:117]
	v_mov_b64_e32 v[2:3], v[118:119]
	s_nop 0
	v_mov_b64_e32 v[4:5], v[166:167]
	v_mov_b64_e32 v[6:7], v[168:169]
	v_mov_b64_e32 v[8:9], v[236:237]
	v_mov_b64_e32 v[10:11], v[238:239]
	v_pk_add_f32 v[0:1], v[0:1], v[32:33] op_sel_hi:[1,0] neg_lo:[0,1] neg_hi:[0,1]
	v_pk_add_f32 v[2:3], v[2:3], v[32:33] op_sel_hi:[1,0] neg_lo:[0,1] neg_hi:[0,1]
	v_pk_mul_f32 v[0:1], v[32:33], v[0:1] op_sel:[1,0]
	v_pk_mul_f32 v[2:3], v[32:33], v[2:3] op_sel:[1,0]
	v_pk_fma_f32 v[0:1], v[0:1], v[4:5], v[8:9]
	v_pk_fma_f32 v[2:3], v[2:3], v[6:7], v[10:11]
	v_pk_fma_f32 v[0:1], v[0:1], s[84:85], v[12:13] op_sel_hi:[1,0,1]
	v_pk_fma_f32 v[2:3], v[2:3], s[84:85], v[14:15] op_sel_hi:[1,0,1]
	global_store_dwordx4 v[34:35], v[0:3], off offset:224

	.amdhsa_kernel _Z4mega6Params
		.amdhsa_group_segment_fixed_size 80000
		.amdhsa_private_segment_fixed_size 0
		.amdhsa_kernarg_size 544
		.amdhsa_user_sgpr_count 2
		.amdhsa_user_sgpr_dispatch_ptr 0
		.amdhsa_user_sgpr_queue_ptr 0
		.amdhsa_user_sgpr_kernarg_segment_ptr 1
		.amdhsa_user_sgpr_dispatch_id 0
		.amdhsa_user_sgpr_kernarg_preload_length 0
		.amdhsa_user_sgpr_kernarg_preload_offset 0
		.amdhsa_user_sgpr_private_segment_size 0
		.amdhsa_uses_dynamic_stack 0
		.amdhsa_enable_private_segment 0
		.amdhsa_system_sgpr_workgroup_id_x 1
		.amdhsa_system_sgpr_workgroup_id_y 0
		.amdhsa_system_sgpr_workgroup_id_z 0
		.amdhsa_system_sgpr_workgroup_info 0
		.amdhsa_system_vgpr_workitem_id 2
		.amdhsa_next_free_vgpr 256
		.amdhsa_next_free_sgpr 98
		.amdhsa_accum_offset 256
		.amdhsa_reserve_vcc 1
		.amdhsa_float_round_mode_32 0
		.amdhsa_float_round_mode_16_64 0
		.amdhsa_float_denorm_mode_32 3
		.amdhsa_float_denorm_mode_16_64 3
		.amdhsa_dx10_clamp 1
		.amdhsa_ieee_mode 1
		.amdhsa_fp16_overflow 0
		.amdhsa_tg_split 0
		.amdhsa_exception_fp_ieee_invalid_op 0
		.amdhsa_exception_fp_denorm_src 0
		.amdhsa_exception_fp_ieee_div_zero 0
		.amdhsa_exception_fp_ieee_overflow 0
		.amdhsa_exception_fp_ieee_underflow 0
		.amdhsa_exception_fp_ieee_inexact 0
		.amdhsa_exception_int_div_zero 0
	.end_amdhsa_kernel

amdhsa.kernels:
  - .agpr_count:     0
    .args:
      - .offset:         0
        .size:           288
        .value_kind:     by_value
      - .offset:         288
        .size:           4
        .value_kind:     hidden_block_count_x
      - .offset:         292
        .size:           4
        .value_kind:     hidden_block_count_y
      - .offset:         296
        .size:           4
        .value_kind:     hidden_block_count_z
      - .offset:         300
        .size:           2
        .value_kind:     hidden_group_size_x
      - .offset:         302
        .size:           2
        .value_kind:     hidden_group_size_y
      - .offset:         304
        .size:           2
        .value_kind:     hidden_group_size_z
      - .offset:         306
        .size:           2
        .value_kind:     hidden_remainder_x
      - .offset:         308
        .size:           2
        .value_kind:     hidden_remainder_y
      - .offset:         310
        .size:           2
        .value_kind:     hidden_remainder_z
      - .offset:         328
        .size:           8
        .value_kind:     hidden_global_offset_x
      - .offset:         336
        .size:           8
        .value_kind:     hidden_global_offset_y
      - .offset:         344
        .size:           8
        .value_kind:     hidden_global_offset_z
      - .offset:         352
        .size:           2
        .value_kind:     hidden_grid_dims
      - .offset:         376
        .size:           8
        .value_kind:     hidden_multigrid_sync_arg
    .group_segment_fixed_size: 80000
    .kernarg_segment_align: 8
    .kernarg_segment_size: 544
    .language:       OpenCL C
    .language_version:
      - 2
      - 0
    .max_flat_workgroup_size: 256
    .name:           _Z4mega6Params
    .private_segment_fixed_size: 0
    .sgpr_count:     104
    .sgpr_spill_count: 124
    .symbol:         _Z4mega6Params.kd
    .uniform_work_group_size: 1
    .uses_dynamic_stack: false
    .vgpr_count:     256
    .vgpr_spill_count: 0
    .wavefront_size: 64
